# 2-DMA load segments: DMAs issued before the 16 ds_reads (reads land later in the partner's MFMA block), s_sleep 1 there; rest as v52
# speedup vs baseline: 1.0034x; 1.0024x over previous
.LBB0_146:
	s_ashr_i32 s25, s24, 31
	s_lshl_b64 s[26:27], s[24:25], 20
	s_add_u32 s26, s47, s26
	s_addc_u32 s27, s48, s27
	s_and_b64 s[28:29], s[38:39], exec
	s_cselect_b32 s2, s27, s41
	s_cselect_b32 s5, s26, s40
	s_ashr_i32 s23, s22, 31
	s_lshl_b64 s[28:29], s[22:23], 20
	s_add_u32 s28, s49, s28
	s_addc_u32 s29, s50, s29
	s_and_b64 s[44:45], s[38:39], exec
	s_cselect_b32 s23, s29, s43
	s_cselect_b32 s25, s28, s42
	s_add_u32 s40, s40, 0x80080
	s_addc_u32 s41, s41, 0
	s_add_u32 s31, s42, 0x100
	s_addc_u32 s62, s43, 0
	s_mov_b32 s63, -2
	s_sleep 1
	s_add_u32 s42, s40, 0xfff80080
	s_addc_u32 s43, s41, -1
	s_add_i32 s71, 0, 0x10000
	s_cmp_eq_u32 s63, 28
	s_cselect_b32 s45, s2, s43
	s_cselect_b32 s44, s5, s42
	s_cselect_b32 s43, s23, s62
	s_cselect_b32 s42, s25, s31
	s_add_i32 s73, 0, 0x14000
	s_waitcnt lgkmcnt(0)
	v_lshl_add_u64 v[202:203], s[40:41], 0, v[148:149]
	s_add_i32 m0, s53, 0xc000
	s_nop 0
	global_load_lds_dwordx4 v[202:203], off
	v_lshl_add_u64 v[202:203], s[40:41], 0, v[150:151]
	s_add_i32 m0, s53, 0xe000
	s_nop 0
	global_load_lds_dwordx4 v[202:203], off
	v_add_u32_e32 v156, s71, v169
	v_add_u32_e32 v178, s73, v169
	ds_read_b128 v[132:135], v156
	ds_read_b128 v[136:139], v156 offset:1024
	ds_read_b128 v[152:155], v156 offset:2048
	ds_read_b128 v[156:159], v156 offset:3072
	ds_read_b128 v[160:163], v178
	ds_read_b128 v[164:167], v178 offset:1024
	ds_read_b128 v[174:177], v178 offset:2048
	ds_read_b128 v[178:181], v178 offset:3072
	ds_read_b128 v[182:185], v171
	ds_read_b128 v[186:189], v171 offset:1024
	ds_read_b128 v[190:193], v171 offset:2048
	ds_read_b128 v[194:197], v171 offset:3072
	ds_read_b128 v[198:201], v171 offset:4096
	ds_read_b128 v[208:211], v171 offset:5120
	ds_read_b128 v[212:215], v171 offset:6144
	ds_read_b128 v[216:219], v171 offset:7168
	s_waitcnt vmcnt(8)
	s_waitcnt lgkmcnt(0)
	s_barrier
	s_setprio 1
	s_waitcnt lgkmcnt(0)
	v_mfma_f32_16x16x32_bf16 v[128:131], v[132:135], v[182:185], 0
	v_mfma_f32_16x16x32_bf16 v[128:131], v[136:139], v[186:189], v[128:131]
	v_mfma_f32_16x16x32_bf16 v[116:119], v[160:163], v[182:185], 0
	v_mfma_f32_16x16x32_bf16 v[116:119], v[164:167], v[186:189], v[116:119]
	v_mfma_f32_16x16x32_bf16 v[124:127], v[152:155], v[182:185], 0
	v_mfma_f32_16x16x32_bf16 v[124:127], v[156:159], v[186:189], v[124:127]
	v_mfma_f32_16x16x32_bf16 v[108:111], v[174:177], v[182:185], 0
	v_mfma_f32_16x16x32_bf16 v[108:111], v[178:181], v[186:189], v[108:111]
	v_mfma_f32_16x16x32_bf16 v[120:123], v[132:135], v[190:193], 0
	v_mfma_f32_16x16x32_bf16 v[120:123], v[136:139], v[194:197], v[120:123]
	v_mfma_f32_16x16x32_bf16 v[100:103], v[160:163], v[190:193], 0
	v_mfma_f32_16x16x32_bf16 v[100:103], v[164:167], v[194:197], v[100:103]
	v_mfma_f32_16x16x32_bf16 v[112:115], v[152:155], v[190:193], 0
	v_mfma_f32_16x16x32_bf16 v[112:115], v[156:159], v[194:197], v[112:115]
	v_mfma_f32_16x16x32_bf16 v[92:95], v[174:177], v[190:193], 0
	v_mfma_f32_16x16x32_bf16 v[92:95], v[178:181], v[194:197], v[92:95]
	v_mfma_f32_16x16x32_bf16 v[104:107], v[132:135], v[198:201], 0
	v_mfma_f32_16x16x32_bf16 v[104:107], v[136:139], v[208:211], v[104:107]
	v_mfma_f32_16x16x32_bf16 v[84:87], v[160:163], v[198:201], 0
	v_mfma_f32_16x16x32_bf16 v[84:87], v[164:167], v[208:211], v[84:87]
	v_mfma_f32_16x16x32_bf16 v[96:99], v[152:155], v[198:201], 0
	v_mfma_f32_16x16x32_bf16 v[96:99], v[156:159], v[208:211], v[96:99]
	v_mfma_f32_16x16x32_bf16 v[76:79], v[174:177], v[198:201], 0
	v_mfma_f32_16x16x32_bf16 v[76:79], v[178:181], v[208:211], v[76:79]
	v_mfma_f32_16x16x32_bf16 v[88:91], v[132:135], v[212:215], 0
	v_mfma_f32_16x16x32_bf16 v[88:91], v[136:139], v[216:219], v[88:91]
	v_mfma_f32_16x16x32_bf16 v[72:75], v[160:163], v[212:215], 0
	v_mfma_f32_16x16x32_bf16 v[72:75], v[164:167], v[216:219], v[72:75]
	v_mfma_f32_16x16x32_bf16 v[80:83], v[152:155], v[212:215], 0
	v_mfma_f32_16x16x32_bf16 v[80:83], v[156:159], v[216:219], v[80:83]
	v_mfma_f32_16x16x32_bf16 v[68:71], v[174:177], v[212:215], 0
	v_mfma_f32_16x16x32_bf16 v[68:71], v[178:181], v[216:219], v[68:71]
	s_setprio 0
	s_barrier
	s_sleep 2
	s_add_i32 s71, s71, s51
	v_lshl_add_u64 v[202:203], s[42:43], 0, v[2:3]
	s_mov_b32 m0, s71
	ds_read_b128 v[182:185], v171 offset:16384
	ds_read_b128 v[186:189], v171 offset:17408
	ds_read_b128 v[190:193], v171 offset:18432
	ds_read_b128 v[194:197], v171 offset:19456
	ds_read_b128 v[198:201], v171 offset:20480
	ds_read_b128 v[208:211], v171 offset:21504
	ds_read_b128 v[212:215], v171 offset:22528
	ds_read_b128 v[216:219], v171 offset:23552
	global_load_lds_dwordx4 v[202:203], off
	s_add_i32 m0, s71, 0x2000
	s_add_u32 s74, s42, 0x80000
	v_lshl_add_u64 v[204:205], s[42:43], 0, v[142:143]
	s_addc_u32 s75, s43, 0
	s_add_i32 s71, s73, s51
	global_load_lds_dwordx4 v[204:205], off
	v_lshl_add_u64 v[206:207], s[74:75], 0, v[2:3]
	s_mov_b32 m0, s71
	v_lshl_add_u64 v[220:221], s[44:45], 0, v[140:141]
	global_load_lds_dwordx4 v[206:207], off
	v_lshl_add_u64 v[206:207], s[74:75], 0, v[142:143]
	s_add_i32 m0, s71, 0x2000
	s_nop 0
	global_load_lds_dwordx4 v[206:207], off
	v_lshl_add_u64 v[206:207], s[44:45], 0, v[0:1]
	s_mov_b32 m0, s53
	s_nop 0
	global_load_lds_dwordx4 v[206:207], off
	s_mov_b32 m0, s54
	s_nop 0
	global_load_lds_dwordx4 v[220:221], off
	s_waitcnt vmcnt(8)
	s_waitcnt lgkmcnt(0)
	s_barrier
	s_setprio 1
	s_waitcnt lgkmcnt(0)
	v_mfma_f32_16x16x32_bf16 v[64:67], v[132:135], v[182:185], 0
	v_mfma_f32_16x16x32_bf16 v[64:67], v[136:139], v[186:189], v[64:67]
	v_mfma_f32_16x16x32_bf16 v[52:55], v[160:163], v[182:185], 0
	v_mfma_f32_16x16x32_bf16 v[52:55], v[164:167], v[186:189], v[52:55]
	v_mfma_f32_16x16x32_bf16 v[60:63], v[152:155], v[182:185], 0
	v_mfma_f32_16x16x32_bf16 v[60:63], v[156:159], v[186:189], v[60:63]
	v_mfma_f32_16x16x32_bf16 v[44:47], v[174:177], v[182:185], 0
	v_mfma_f32_16x16x32_bf16 v[44:47], v[178:181], v[186:189], v[44:47]
	v_mfma_f32_16x16x32_bf16 v[56:59], v[132:135], v[190:193], 0
	v_mfma_f32_16x16x32_bf16 v[56:59], v[136:139], v[194:197], v[56:59]
	v_mfma_f32_16x16x32_bf16 v[36:39], v[160:163], v[190:193], 0
	v_mfma_f32_16x16x32_bf16 v[36:39], v[164:167], v[194:197], v[36:39]
	v_mfma_f32_16x16x32_bf16 v[48:51], v[152:155], v[190:193], 0
	v_mfma_f32_16x16x32_bf16 v[48:51], v[156:159], v[194:197], v[48:51]
	v_mfma_f32_16x16x32_bf16 v[28:31], v[174:177], v[190:193], 0
	v_mfma_f32_16x16x32_bf16 v[28:31], v[178:181], v[194:197], v[28:31]
	v_mfma_f32_16x16x32_bf16 v[40:43], v[132:135], v[198:201], 0
	v_mfma_f32_16x16x32_bf16 v[40:43], v[136:139], v[208:211], v[40:43]
	v_mfma_f32_16x16x32_bf16 v[20:23], v[160:163], v[198:201], 0
	v_mfma_f32_16x16x32_bf16 v[20:23], v[164:167], v[208:211], v[20:23]
	v_mfma_f32_16x16x32_bf16 v[32:35], v[152:155], v[198:201], 0
	v_mfma_f32_16x16x32_bf16 v[32:35], v[156:159], v[208:211], v[32:35]
	v_mfma_f32_16x16x32_bf16 v[12:15], v[174:177], v[198:201], 0
	v_mfma_f32_16x16x32_bf16 v[12:15], v[178:181], v[208:211], v[12:15]
	v_mfma_f32_16x16x32_bf16 v[24:27], v[132:135], v[212:215], 0
	v_mfma_f32_16x16x32_bf16 v[24:27], v[136:139], v[216:219], v[24:27]
	v_mfma_f32_16x16x32_bf16 v[8:11], v[160:163], v[212:215], 0
	v_mfma_f32_16x16x32_bf16 v[8:11], v[164:167], v[216:219], v[8:11]
	v_mfma_f32_16x16x32_bf16 v[16:19], v[152:155], v[212:215], 0
	v_mfma_f32_16x16x32_bf16 v[16:19], v[156:159], v[216:219], v[16:19]
	v_mfma_f32_16x16x32_bf16 v[4:7], v[174:177], v[212:215], 0
	v_mfma_f32_16x16x32_bf16 v[4:7], v[178:181], v[216:219], v[4:7]
	s_setprio 0
	s_barrier
	s_sleep 1
	s_add_i32 s71, 0, 0x18000
	s_add_i32 s73, 0, 0x1c000
	s_add_u32 s44, s44, 0x80000
	s_addc_u32 s45, s45, 0
	s_mov_b32 m0, s55
	v_lshl_add_u64 v[222:223], s[44:45], 0, v[0:1]
	global_load_lds_dwordx4 v[222:223], off
	v_lshl_add_u64 v[222:223], s[44:45], 0, v[140:141]
	s_mov_b32 m0, s56
	s_nop 0
	global_load_lds_dwordx4 v[222:223], off
	v_add_u32_e32 v156, s71, v169
	v_add_u32_e32 v178, s73, v169
	ds_read_b128 v[132:135], v156
	ds_read_b128 v[136:139], v156 offset:1024
	ds_read_b128 v[152:155], v156 offset:2048
	ds_read_b128 v[156:159], v156 offset:3072
	ds_read_b128 v[160:163], v178
	ds_read_b128 v[164:167], v178 offset:1024
	ds_read_b128 v[174:177], v178 offset:2048
	ds_read_b128 v[178:181], v178 offset:3072
	ds_read_b128 v[182:185], v171 offset:32768
	ds_read_b128 v[186:189], v171 offset:33792
	ds_read_b128 v[190:193], v171 offset:34816
	ds_read_b128 v[194:197], v171 offset:35840
	ds_read_b128 v[198:201], v171 offset:36864
	ds_read_b128 v[208:211], v171 offset:37888
	ds_read_b128 v[212:215], v171 offset:38912
	ds_read_b128 v[216:219], v171 offset:39936
	s_waitcnt vmcnt(8)
	s_waitcnt lgkmcnt(0)
	s_barrier
	s_setprio 1
	s_waitcnt lgkmcnt(0)
	v_mfma_f32_16x16x32_bf16 v[128:131], v[132:135], v[182:185], v[128:131]
	v_mfma_f32_16x16x32_bf16 v[128:131], v[136:139], v[186:189], v[128:131]
	v_mfma_f32_16x16x32_bf16 v[116:119], v[160:163], v[182:185], v[116:119]
	v_mfma_f32_16x16x32_bf16 v[116:119], v[164:167], v[186:189], v[116:119]
	v_mfma_f32_16x16x32_bf16 v[124:127], v[152:155], v[182:185], v[124:127]
	v_mfma_f32_16x16x32_bf16 v[124:127], v[156:159], v[186:189], v[124:127]
	v_mfma_f32_16x16x32_bf16 v[108:111], v[174:177], v[182:185], v[108:111]
	v_mfma_f32_16x16x32_bf16 v[108:111], v[178:181], v[186:189], v[108:111]
	v_mfma_f32_16x16x32_bf16 v[120:123], v[132:135], v[190:193], v[120:123]
	v_mfma_f32_16x16x32_bf16 v[120:123], v[136:139], v[194:197], v[120:123]
	v_mfma_f32_16x16x32_bf16 v[100:103], v[160:163], v[190:193], v[100:103]
	v_mfma_f32_16x16x32_bf16 v[100:103], v[164:167], v[194:197], v[100:103]
	v_mfma_f32_16x16x32_bf16 v[112:115], v[152:155], v[190:193], v[112:115]
	v_mfma_f32_16x16x32_bf16 v[112:115], v[156:159], v[194:197], v[112:115]
	v_mfma_f32_16x16x32_bf16 v[92:95], v[174:177], v[190:193], v[92:95]
	v_mfma_f32_16x16x32_bf16 v[92:95], v[178:181], v[194:197], v[92:95]
	v_mfma_f32_16x16x32_bf16 v[104:107], v[132:135], v[198:201], v[104:107]
	v_mfma_f32_16x16x32_bf16 v[104:107], v[136:139], v[208:211], v[104:107]
	v_mfma_f32_16x16x32_bf16 v[84:87], v[160:163], v[198:201], v[84:87]
	v_mfma_f32_16x16x32_bf16 v[84:87], v[164:167], v[208:211], v[84:87]
	v_mfma_f32_16x16x32_bf16 v[96:99], v[152:155], v[198:201], v[96:99]
	v_mfma_f32_16x16x32_bf16 v[96:99], v[156:159], v[208:211], v[96:99]
	v_mfma_f32_16x16x32_bf16 v[76:79], v[174:177], v[198:201], v[76:79]
	v_mfma_f32_16x16x32_bf16 v[76:79], v[178:181], v[208:211], v[76:79]
	v_mfma_f32_16x16x32_bf16 v[88:91], v[132:135], v[212:215], v[88:91]
	v_mfma_f32_16x16x32_bf16 v[88:91], v[136:139], v[216:219], v[88:91]
	v_mfma_f32_16x16x32_bf16 v[72:75], v[160:163], v[212:215], v[72:75]
	v_mfma_f32_16x16x32_bf16 v[72:75], v[164:167], v[216:219], v[72:75]
	v_mfma_f32_16x16x32_bf16 v[80:83], v[152:155], v[212:215], v[80:83]
	v_mfma_f32_16x16x32_bf16 v[80:83], v[156:159], v[216:219], v[80:83]
	v_mfma_f32_16x16x32_bf16 v[68:71], v[174:177], v[212:215], v[68:71]
	v_mfma_f32_16x16x32_bf16 v[68:71], v[178:181], v[216:219], v[68:71]
	s_setprio 0
	s_barrier
	s_sleep 2
	s_add_i32 s44, s71, s51
	v_lshl_add_u64 v[202:203], v[202:203], 0, s[66:67]
	s_mov_b32 m0, s44
	ds_read_b128 v[182:185], v171 offset:49152
	ds_read_b128 v[186:189], v171 offset:50176
	ds_read_b128 v[190:193], v171 offset:51200
	ds_read_b128 v[194:197], v171 offset:52224
	ds_read_b128 v[198:201], v171 offset:53248
	ds_read_b128 v[208:211], v171 offset:54272
	ds_read_b128 v[212:215], v171 offset:55296
	ds_read_b128 v[216:219], v171 offset:56320
	global_load_lds_dwordx4 v[202:203], off
	s_add_i32 m0, s44, 0x2000
	s_add_u32 s42, s42, 0x80080
	v_lshl_add_u64 v[202:203], v[204:205], 0, s[66:67]
	s_addc_u32 s43, s43, 0
	s_add_i32 s44, s73, s51
	global_load_lds_dwordx4 v[202:203], off
	v_lshl_add_u64 v[202:203], s[42:43], 0, v[2:3]
	s_mov_b32 m0, s44
	s_nop 0
	global_load_lds_dwordx4 v[202:203], off
	v_lshl_add_u64 v[202:203], s[42:43], 0, v[142:143]
	s_add_i32 m0, s44, 0x2000
	s_nop 0
	global_load_lds_dwordx4 v[202:203], off
	v_lshl_add_u64 v[202:203], v[206:207], 0, s[66:67]
	s_mov_b32 m0, s65
	s_nop 0
	global_load_lds_dwordx4 v[202:203], off
	v_lshl_add_u64 v[202:203], v[220:221], 0, s[66:67]
	s_mov_b32 m0, s68
	s_nop 0
	global_load_lds_dwordx4 v[202:203], off
	s_waitcnt vmcnt(8)
	s_waitcnt lgkmcnt(0)
	s_barrier
	s_setprio 1
	s_waitcnt lgkmcnt(0)
	v_mfma_f32_16x16x32_bf16 v[64:67], v[132:135], v[182:185], v[64:67]
	v_mfma_f32_16x16x32_bf16 v[64:67], v[136:139], v[186:189], v[64:67]
	v_mfma_f32_16x16x32_bf16 v[52:55], v[160:163], v[182:185], v[52:55]
	v_mfma_f32_16x16x32_bf16 v[52:55], v[164:167], v[186:189], v[52:55]
	v_mfma_f32_16x16x32_bf16 v[60:63], v[152:155], v[182:185], v[60:63]
	v_mfma_f32_16x16x32_bf16 v[60:63], v[156:159], v[186:189], v[60:63]
	v_mfma_f32_16x16x32_bf16 v[44:47], v[174:177], v[182:185], v[44:47]
	v_mfma_f32_16x16x32_bf16 v[44:47], v[178:181], v[186:189], v[44:47]
	v_mfma_f32_16x16x32_bf16 v[56:59], v[132:135], v[190:193], v[56:59]
	v_mfma_f32_16x16x32_bf16 v[56:59], v[136:139], v[194:197], v[56:59]
	v_mfma_f32_16x16x32_bf16 v[36:39], v[160:163], v[190:193], v[36:39]
	v_mfma_f32_16x16x32_bf16 v[36:39], v[164:167], v[194:197], v[36:39]
	v_mfma_f32_16x16x32_bf16 v[48:51], v[152:155], v[190:193], v[48:51]
	v_mfma_f32_16x16x32_bf16 v[48:51], v[156:159], v[194:197], v[48:51]
	v_mfma_f32_16x16x32_bf16 v[28:31], v[174:177], v[190:193], v[28:31]
	v_mfma_f32_16x16x32_bf16 v[28:31], v[178:181], v[194:197], v[28:31]
	v_mfma_f32_16x16x32_bf16 v[40:43], v[132:135], v[198:201], v[40:43]
	v_mfma_f32_16x16x32_bf16 v[40:43], v[136:139], v[208:211], v[40:43]
	v_mfma_f32_16x16x32_bf16 v[20:23], v[160:163], v[198:201], v[20:23]
	v_mfma_f32_16x16x32_bf16 v[20:23], v[164:167], v[208:211], v[20:23]
	v_mfma_f32_16x16x32_bf16 v[32:35], v[152:155], v[198:201], v[32:35]
	v_mfma_f32_16x16x32_bf16 v[32:35], v[156:159], v[208:211], v[32:35]
	v_mfma_f32_16x16x32_bf16 v[12:15], v[174:177], v[198:201], v[12:15]
	v_mfma_f32_16x16x32_bf16 v[12:15], v[178:181], v[208:211], v[12:15]
	v_mfma_f32_16x16x32_bf16 v[24:27], v[132:135], v[212:215], v[24:27]
	v_mfma_f32_16x16x32_bf16 v[24:27], v[136:139], v[216:219], v[24:27]
	v_mfma_f32_16x16x32_bf16 v[8:11], v[160:163], v[212:215], v[8:11]
	v_mfma_f32_16x16x32_bf16 v[8:11], v[164:167], v[216:219], v[8:11]
	v_mfma_f32_16x16x32_bf16 v[16:19], v[152:155], v[212:215], v[16:19]
	v_mfma_f32_16x16x32_bf16 v[16:19], v[156:159], v[216:219], v[16:19]
	v_mfma_f32_16x16x32_bf16 v[4:7], v[174:177], v[212:215], v[4:7]
	v_mfma_f32_16x16x32_bf16 v[4:7], v[178:181], v[216:219], v[4:7]
	s_setprio 0
	s_barrier
	s_add_i32 s63, s63, 2
	s_add_u32 s40, s40, 0x100
	s_addc_u32 s41, s41, 0
	s_add_u32 s31, s31, 0x100
	s_addc_u32 s62, s62, 0
	s_cmp_gt_u32 s63, 29
.LBB0_147:
	s_sleep 1
	s_add_u32 s42, s40, 0xfff80080
	s_addc_u32 s43, s41, -1
	s_add_i32 s71, 0, 0x10000
	s_cmp_eq_u32 s63, 28
	s_cselect_b32 s45, s2, s43
	s_cselect_b32 s44, s5, s42
	s_cselect_b32 s43, s23, s62
	s_cselect_b32 s42, s25, s31
	s_add_i32 s73, 0, 0x14000
	s_waitcnt lgkmcnt(0)
	v_lshl_add_u64 v[202:203], s[40:41], 0, v[148:149]
	s_add_i32 m0, s53, 0xc000
	s_nop 0
	global_load_lds_dwordx4 v[202:203], off
	v_lshl_add_u64 v[202:203], s[40:41], 0, v[150:151]
	s_add_i32 m0, s53, 0xe000
	s_nop 0
	global_load_lds_dwordx4 v[202:203], off
	v_add_u32_e32 v156, s71, v169
	v_add_u32_e32 v178, s73, v169
	ds_read_b128 v[132:135], v156
	ds_read_b128 v[136:139], v156 offset:1024
	ds_read_b128 v[152:155], v156 offset:2048
	ds_read_b128 v[156:159], v156 offset:3072
	ds_read_b128 v[160:163], v178
	ds_read_b128 v[164:167], v178 offset:1024
	ds_read_b128 v[174:177], v178 offset:2048
	ds_read_b128 v[178:181], v178 offset:3072
	ds_read_b128 v[182:185], v171
	ds_read_b128 v[186:189], v171 offset:1024
	ds_read_b128 v[190:193], v171 offset:2048
	ds_read_b128 v[194:197], v171 offset:3072
	ds_read_b128 v[198:201], v171 offset:4096
	ds_read_b128 v[208:211], v171 offset:5120
	ds_read_b128 v[212:215], v171 offset:6144
	ds_read_b128 v[216:219], v171 offset:7168
	s_waitcnt vmcnt(8)
	s_waitcnt lgkmcnt(0)
	s_barrier
	s_setprio 1
	s_waitcnt lgkmcnt(0)
	v_mfma_f32_16x16x32_bf16 v[128:131], v[132:135], v[182:185], v[128:131]
	v_mfma_f32_16x16x32_bf16 v[128:131], v[136:139], v[186:189], v[128:131]
	v_mfma_f32_16x16x32_bf16 v[116:119], v[160:163], v[182:185], v[116:119]
	v_mfma_f32_16x16x32_bf16 v[116:119], v[164:167], v[186:189], v[116:119]
	v_mfma_f32_16x16x32_bf16 v[124:127], v[152:155], v[182:185], v[124:127]
	v_mfma_f32_16x16x32_bf16 v[124:127], v[156:159], v[186:189], v[124:127]
	v_mfma_f32_16x16x32_bf16 v[108:111], v[174:177], v[182:185], v[108:111]
	v_mfma_f32_16x16x32_bf16 v[108:111], v[178:181], v[186:189], v[108:111]
	v_mfma_f32_16x16x32_bf16 v[120:123], v[132:135], v[190:193], v[120:123]
	v_mfma_f32_16x16x32_bf16 v[120:123], v[136:139], v[194:197], v[120:123]
	v_mfma_f32_16x16x32_bf16 v[100:103], v[160:163], v[190:193], v[100:103]
	v_mfma_f32_16x16x32_bf16 v[100:103], v[164:167], v[194:197], v[100:103]
	v_mfma_f32_16x16x32_bf16 v[112:115], v[152:155], v[190:193], v[112:115]
	v_mfma_f32_16x16x32_bf16 v[112:115], v[156:159], v[194:197], v[112:115]
	v_mfma_f32_16x16x32_bf16 v[92:95], v[174:177], v[190:193], v[92:95]
	v_mfma_f32_16x16x32_bf16 v[92:95], v[178:181], v[194:197], v[92:95]
	v_mfma_f32_16x16x32_bf16 v[104:107], v[132:135], v[198:201], v[104:107]
	v_mfma_f32_16x16x32_bf16 v[104:107], v[136:139], v[208:211], v[104:107]
	v_mfma_f32_16x16x32_bf16 v[84:87], v[160:163], v[198:201], v[84:87]
	v_mfma_f32_16x16x32_bf16 v[84:87], v[164:167], v[208:211], v[84:87]
	v_mfma_f32_16x16x32_bf16 v[96:99], v[152:155], v[198:201], v[96:99]
	v_mfma_f32_16x16x32_bf16 v[96:99], v[156:159], v[208:211], v[96:99]
	v_mfma_f32_16x16x32_bf16 v[76:79], v[174:177], v[198:201], v[76:79]
	v_mfma_f32_16x16x32_bf16 v[76:79], v[178:181], v[208:211], v[76:79]
	v_mfma_f32_16x16x32_bf16 v[88:91], v[132:135], v[212:215], v[88:91]
	v_mfma_f32_16x16x32_bf16 v[88:91], v[136:139], v[216:219], v[88:91]
	v_mfma_f32_16x16x32_bf16 v[72:75], v[160:163], v[212:215], v[72:75]
	v_mfma_f32_16x16x32_bf16 v[72:75], v[164:167], v[216:219], v[72:75]
	v_mfma_f32_16x16x32_bf16 v[80:83], v[152:155], v[212:215], v[80:83]
	v_mfma_f32_16x16x32_bf16 v[80:83], v[156:159], v[216:219], v[80:83]
	v_mfma_f32_16x16x32_bf16 v[68:71], v[174:177], v[212:215], v[68:71]
	v_mfma_f32_16x16x32_bf16 v[68:71], v[178:181], v[216:219], v[68:71]
	s_setprio 0
	s_barrier
	s_sleep 2
	s_add_i32 s71, s71, s51
	v_lshl_add_u64 v[202:203], s[42:43], 0, v[2:3]
	s_mov_b32 m0, s71
	ds_read_b128 v[182:185], v171 offset:16384
	ds_read_b128 v[186:189], v171 offset:17408
	ds_read_b128 v[190:193], v171 offset:18432
	ds_read_b128 v[194:197], v171 offset:19456
	ds_read_b128 v[198:201], v171 offset:20480
	ds_read_b128 v[208:211], v171 offset:21504
	ds_read_b128 v[212:215], v171 offset:22528
	ds_read_b128 v[216:219], v171 offset:23552
	global_load_lds_dwordx4 v[202:203], off
	s_add_i32 m0, s71, 0x2000
	s_add_u32 s74, s42, 0x80000
	v_lshl_add_u64 v[204:205], s[42:43], 0, v[142:143]
	s_addc_u32 s75, s43, 0
	s_add_i32 s71, s73, s51
	global_load_lds_dwordx4 v[204:205], off
	v_lshl_add_u64 v[206:207], s[74:75], 0, v[2:3]
	s_mov_b32 m0, s71
	v_lshl_add_u64 v[220:221], s[44:45], 0, v[140:141]
	global_load_lds_dwordx4 v[206:207], off
	v_lshl_add_u64 v[206:207], s[74:75], 0, v[142:143]
	s_add_i32 m0, s71, 0x2000
	s_nop 0
	global_load_lds_dwordx4 v[206:207], off
	v_lshl_add_u64 v[206:207], s[44:45], 0, v[0:1]
	s_mov_b32 m0, s53
	s_nop 0
	global_load_lds_dwordx4 v[206:207], off
	s_mov_b32 m0, s54
	s_nop 0
	global_load_lds_dwordx4 v[220:221], off
	s_waitcnt vmcnt(8)
	s_waitcnt lgkmcnt(0)
	s_barrier
	s_setprio 1
	s_waitcnt lgkmcnt(0)
	v_mfma_f32_16x16x32_bf16 v[64:67], v[132:135], v[182:185], v[64:67]
	v_mfma_f32_16x16x32_bf16 v[64:67], v[136:139], v[186:189], v[64:67]
	v_mfma_f32_16x16x32_bf16 v[52:55], v[160:163], v[182:185], v[52:55]
	v_mfma_f32_16x16x32_bf16 v[52:55], v[164:167], v[186:189], v[52:55]
	v_mfma_f32_16x16x32_bf16 v[60:63], v[152:155], v[182:185], v[60:63]
	v_mfma_f32_16x16x32_bf16 v[60:63], v[156:159], v[186:189], v[60:63]
	v_mfma_f32_16x16x32_bf16 v[44:47], v[174:177], v[182:185], v[44:47]
	v_mfma_f32_16x16x32_bf16 v[44:47], v[178:181], v[186:189], v[44:47]
	v_mfma_f32_16x16x32_bf16 v[56:59], v[132:135], v[190:193], v[56:59]
	v_mfma_f32_16x16x32_bf16 v[56:59], v[136:139], v[194:197], v[56:59]
	v_mfma_f32_16x16x32_bf16 v[36:39], v[160:163], v[190:193], v[36:39]
	v_mfma_f32_16x16x32_bf16 v[36:39], v[164:167], v[194:197], v[36:39]
	v_mfma_f32_16x16x32_bf16 v[48:51], v[152:155], v[190:193], v[48:51]
	v_mfma_f32_16x16x32_bf16 v[48:51], v[156:159], v[194:197], v[48:51]
	v_mfma_f32_16x16x32_bf16 v[28:31], v[174:177], v[190:193], v[28:31]
	v_mfma_f32_16x16x32_bf16 v[28:31], v[178:181], v[194:197], v[28:31]
	v_mfma_f32_16x16x32_bf16 v[40:43], v[132:135], v[198:201], v[40:43]
	v_mfma_f32_16x16x32_bf16 v[40:43], v[136:139], v[208:211], v[40:43]
	v_mfma_f32_16x16x32_bf16 v[20:23], v[160:163], v[198:201], v[20:23]
	v_mfma_f32_16x16x32_bf16 v[20:23], v[164:167], v[208:211], v[20:23]
	v_mfma_f32_16x16x32_bf16 v[32:35], v[152:155], v[198:201], v[32:35]
	v_mfma_f32_16x16x32_bf16 v[32:35], v[156:159], v[208:211], v[32:35]
	v_mfma_f32_16x16x32_bf16 v[12:15], v[174:177], v[198:201], v[12:15]
	v_mfma_f32_16x16x32_bf16 v[12:15], v[178:181], v[208:211], v[12:15]
	v_mfma_f32_16x16x32_bf16 v[24:27], v[132:135], v[212:215], v[24:27]
	v_mfma_f32_16x16x32_bf16 v[24:27], v[136:139], v[216:219], v[24:27]
	v_mfma_f32_16x16x32_bf16 v[8:11], v[160:163], v[212:215], v[8:11]
	v_mfma_f32_16x16x32_bf16 v[8:11], v[164:167], v[216:219], v[8:11]
	v_mfma_f32_16x16x32_bf16 v[16:19], v[152:155], v[212:215], v[16:19]
	v_mfma_f32_16x16x32_bf16 v[16:19], v[156:159], v[216:219], v[16:19]
	v_mfma_f32_16x16x32_bf16 v[4:7], v[174:177], v[212:215], v[4:7]
	v_mfma_f32_16x16x32_bf16 v[4:7], v[178:181], v[216:219], v[4:7]
	s_setprio 0
	s_barrier
	s_sleep 1
	s_add_i32 s71, 0, 0x18000
	s_add_i32 s73, 0, 0x1c000
	s_add_u32 s44, s44, 0x80000
	s_addc_u32 s45, s45, 0
	s_mov_b32 m0, s55
	v_lshl_add_u64 v[222:223], s[44:45], 0, v[0:1]
	global_load_lds_dwordx4 v[222:223], off
	v_lshl_add_u64 v[222:223], s[44:45], 0, v[140:141]
	s_mov_b32 m0, s56
	s_nop 0
	global_load_lds_dwordx4 v[222:223], off
	v_add_u32_e32 v156, s71, v169
	v_add_u32_e32 v178, s73, v169
	ds_read_b128 v[132:135], v156
	ds_read_b128 v[136:139], v156 offset:1024
	ds_read_b128 v[152:155], v156 offset:2048
	ds_read_b128 v[156:159], v156 offset:3072
	ds_read_b128 v[160:163], v178
	ds_read_b128 v[164:167], v178 offset:1024
	ds_read_b128 v[174:177], v178 offset:2048
	ds_read_b128 v[178:181], v178 offset:3072
	ds_read_b128 v[182:185], v171 offset:32768
	ds_read_b128 v[186:189], v171 offset:33792
	ds_read_b128 v[190:193], v171 offset:34816
	ds_read_b128 v[194:197], v171 offset:35840
	ds_read_b128 v[198:201], v171 offset:36864
	ds_read_b128 v[208:211], v171 offset:37888
	ds_read_b128 v[212:215], v171 offset:38912
	ds_read_b128 v[216:219], v171 offset:39936
	s_waitcnt vmcnt(8)
	s_waitcnt lgkmcnt(0)
	s_barrier
	s_setprio 1
	s_waitcnt lgkmcnt(0)
	v_mfma_f32_16x16x32_bf16 v[128:131], v[132:135], v[182:185], v[128:131]
	v_mfma_f32_16x16x32_bf16 v[128:131], v[136:139], v[186:189], v[128:131]
	v_mfma_f32_16x16x32_bf16 v[116:119], v[160:163], v[182:185], v[116:119]
	v_mfma_f32_16x16x32_bf16 v[116:119], v[164:167], v[186:189], v[116:119]
	v_mfma_f32_16x16x32_bf16 v[124:127], v[152:155], v[182:185], v[124:127]
	v_mfma_f32_16x16x32_bf16 v[124:127], v[156:159], v[186:189], v[124:127]
	v_mfma_f32_16x16x32_bf16 v[108:111], v[174:177], v[182:185], v[108:111]
	v_mfma_f32_16x16x32_bf16 v[108:111], v[178:181], v[186:189], v[108:111]
	v_mfma_f32_16x16x32_bf16 v[120:123], v[132:135], v[190:193], v[120:123]
	v_mfma_f32_16x16x32_bf16 v[120:123], v[136:139], v[194:197], v[120:123]
	v_mfma_f32_16x16x32_bf16 v[100:103], v[160:163], v[190:193], v[100:103]
	v_mfma_f32_16x16x32_bf16 v[100:103], v[164:167], v[194:197], v[100:103]
	v_mfma_f32_16x16x32_bf16 v[112:115], v[152:155], v[190:193], v[112:115]
	v_mfma_f32_16x16x32_bf16 v[112:115], v[156:159], v[194:197], v[112:115]
	v_mfma_f32_16x16x32_bf16 v[92:95], v[174:177], v[190:193], v[92:95]
	v_mfma_f32_16x16x32_bf16 v[92:95], v[178:181], v[194:197], v[92:95]
	v_mfma_f32_16x16x32_bf16 v[104:107], v[132:135], v[198:201], v[104:107]
	v_mfma_f32_16x16x32_bf16 v[104:107], v[136:139], v[208:211], v[104:107]
	v_mfma_f32_16x16x32_bf16 v[84:87], v[160:163], v[198:201], v[84:87]
	v_mfma_f32_16x16x32_bf16 v[84:87], v[164:167], v[208:211], v[84:87]
	v_mfma_f32_16x16x32_bf16 v[96:99], v[152:155], v[198:201], v[96:99]
	v_mfma_f32_16x16x32_bf16 v[96:99], v[156:159], v[208:211], v[96:99]
	v_mfma_f32_16x16x32_bf16 v[76:79], v[174:177], v[198:201], v[76:79]
	v_mfma_f32_16x16x32_bf16 v[76:79], v[178:181], v[208:211], v[76:79]
	v_mfma_f32_16x16x32_bf16 v[88:91], v[132:135], v[212:215], v[88:91]
	v_mfma_f32_16x16x32_bf16 v[88:91], v[136:139], v[216:219], v[88:91]
	v_mfma_f32_16x16x32_bf16 v[72:75], v[160:163], v[212:215], v[72:75]
	v_mfma_f32_16x16x32_bf16 v[72:75], v[164:167], v[216:219], v[72:75]
	v_mfma_f32_16x16x32_bf16 v[80:83], v[152:155], v[212:215], v[80:83]
	v_mfma_f32_16x16x32_bf16 v[80:83], v[156:159], v[216:219], v[80:83]
	v_mfma_f32_16x16x32_bf16 v[68:71], v[174:177], v[212:215], v[68:71]
	v_mfma_f32_16x16x32_bf16 v[68:71], v[178:181], v[216:219], v[68:71]
	s_setprio 0
	s_barrier
	s_sleep 2
	s_add_i32 s44, s71, s51
	v_lshl_add_u64 v[202:203], v[202:203], 0, s[66:67]
	s_mov_b32 m0, s44
	ds_read_b128 v[182:185], v171 offset:49152
	ds_read_b128 v[186:189], v171 offset:50176
	ds_read_b128 v[190:193], v171 offset:51200
	ds_read_b128 v[194:197], v171 offset:52224
	ds_read_b128 v[198:201], v171 offset:53248
	ds_read_b128 v[208:211], v171 offset:54272
	ds_read_b128 v[212:215], v171 offset:55296
	ds_read_b128 v[216:219], v171 offset:56320
	global_load_lds_dwordx4 v[202:203], off
	s_add_i32 m0, s44, 0x2000
	s_add_u32 s42, s42, 0x80080
	v_lshl_add_u64 v[202:203], v[204:205], 0, s[66:67]
	s_addc_u32 s43, s43, 0
	s_add_i32 s44, s73, s51
	global_load_lds_dwordx4 v[202:203], off
	v_lshl_add_u64 v[202:203], s[42:43], 0, v[2:3]
	s_mov_b32 m0, s44
	s_nop 0
	global_load_lds_dwordx4 v[202:203], off
	v_lshl_add_u64 v[202:203], s[42:43], 0, v[142:143]
	s_add_i32 m0, s44, 0x2000
	s_nop 0
	global_load_lds_dwordx4 v[202:203], off
	v_lshl_add_u64 v[202:203], v[206:207], 0, s[66:67]
	s_mov_b32 m0, s65
	s_nop 0
	global_load_lds_dwordx4 v[202:203], off
	v_lshl_add_u64 v[202:203], v[220:221], 0, s[66:67]
	s_mov_b32 m0, s68
	s_nop 0
	global_load_lds_dwordx4 v[202:203], off
	s_waitcnt vmcnt(8)
	s_waitcnt lgkmcnt(0)
	s_barrier
	s_setprio 1
	s_waitcnt lgkmcnt(0)
	v_mfma_f32_16x16x32_bf16 v[64:67], v[132:135], v[182:185], v[64:67]
	v_mfma_f32_16x16x32_bf16 v[64:67], v[136:139], v[186:189], v[64:67]
	v_mfma_f32_16x16x32_bf16 v[52:55], v[160:163], v[182:185], v[52:55]
	v_mfma_f32_16x16x32_bf16 v[52:55], v[164:167], v[186:189], v[52:55]
	v_mfma_f32_16x16x32_bf16 v[60:63], v[152:155], v[182:185], v[60:63]
	v_mfma_f32_16x16x32_bf16 v[60:63], v[156:159], v[186:189], v[60:63]
	v_mfma_f32_16x16x32_bf16 v[44:47], v[174:177], v[182:185], v[44:47]
	v_mfma_f32_16x16x32_bf16 v[44:47], v[178:181], v[186:189], v[44:47]
	v_mfma_f32_16x16x32_bf16 v[56:59], v[132:135], v[190:193], v[56:59]
	v_mfma_f32_16x16x32_bf16 v[56:59], v[136:139], v[194:197], v[56:59]
	v_mfma_f32_16x16x32_bf16 v[36:39], v[160:163], v[190:193], v[36:39]
	v_mfma_f32_16x16x32_bf16 v[36:39], v[164:167], v[194:197], v[36:39]
	v_mfma_f32_16x16x32_bf16 v[48:51], v[152:155], v[190:193], v[48:51]
	v_mfma_f32_16x16x32_bf16 v[48:51], v[156:159], v[194:197], v[48:51]
	v_mfma_f32_16x16x32_bf16 v[28:31], v[174:177], v[190:193], v[28:31]
	v_mfma_f32_16x16x32_bf16 v[28:31], v[178:181], v[194:197], v[28:31]
	v_mfma_f32_16x16x32_bf16 v[40:43], v[132:135], v[198:201], v[40:43]
	v_mfma_f32_16x16x32_bf16 v[40:43], v[136:139], v[208:211], v[40:43]
	v_mfma_f32_16x16x32_bf16 v[20:23], v[160:163], v[198:201], v[20:23]
	v_mfma_f32_16x16x32_bf16 v[20:23], v[164:167], v[208:211], v[20:23]
	v_mfma_f32_16x16x32_bf16 v[32:35], v[152:155], v[198:201], v[32:35]
	v_mfma_f32_16x16x32_bf16 v[32:35], v[156:159], v[208:211], v[32:35]
	v_mfma_f32_16x16x32_bf16 v[12:15], v[174:177], v[198:201], v[12:15]
	v_mfma_f32_16x16x32_bf16 v[12:15], v[178:181], v[208:211], v[12:15]
	v_mfma_f32_16x16x32_bf16 v[24:27], v[132:135], v[212:215], v[24:27]
	v_mfma_f32_16x16x32_bf16 v[24:27], v[136:139], v[216:219], v[24:27]
	v_mfma_f32_16x16x32_bf16 v[8:11], v[160:163], v[212:215], v[8:11]
	v_mfma_f32_16x16x32_bf16 v[8:11], v[164:167], v[216:219], v[8:11]
	v_mfma_f32_16x16x32_bf16 v[16:19], v[152:155], v[212:215], v[16:19]
	v_mfma_f32_16x16x32_bf16 v[16:19], v[156:159], v[216:219], v[16:19]
	v_mfma_f32_16x16x32_bf16 v[4:7], v[174:177], v[212:215], v[4:7]
	v_mfma_f32_16x16x32_bf16 v[4:7], v[178:181], v[216:219], v[4:7]
	s_setprio 0
	s_barrier
	s_add_i32 s63, s63, 2
	s_add_u32 s40, s40, 0x100
	s_addc_u32 s41, s41, 0
	s_add_u32 s31, s31, 0x100
	s_addc_u32 s62, s62, 0
	s_cmp_gt_u32 s63, 29
	s_cbranch_scc0 .LBB0_147
	s_and_b64 vcc, exec, s[18:19]
	s_cbranch_vccz .LBB0_150
	s_barrier

.LBB0_210:
	s_ashr_i32 s21, s20, 31
	s_lshl_b64 s[22:23], s[20:21], 20
	s_add_u32 s22, s4, s22
	s_addc_u32 s23, s5, s23
	s_and_b64 s[24:25], s[34:35], exec
	s_cselect_b32 s21, s23, s29
	s_cselect_b32 s53, s22, s28
	s_ashr_i32 s19, s18, 31
	s_lshl_b64 s[24:25], s[18:19], 20
	s_add_u32 s24, s2, s24
	s_addc_u32 s25, s40, s25
	s_and_b64 s[38:39], s[34:35], exec
	s_cselect_b32 s19, s25, s31
	s_cselect_b32 s54, s24, s30
	s_add_u32 s28, s28, 0x80080
	s_addc_u32 s29, s29, 0
	s_add_u32 s55, s30, 0x100
	s_addc_u32 s56, s31, 0
	s_mov_b32 s57, -2
	s_sleep 1
	s_add_u32 s30, s28, 0xfff80080
	s_addc_u32 s31, s29, -1
	s_add_i32 s58, 0, 0x10000
	s_cmp_eq_u32 s57, 28
	s_cselect_b32 s39, s21, s31
	s_cselect_b32 s38, s53, s30
	s_cselect_b32 s31, s19, s56
	s_cselect_b32 s30, s54, s55
	s_add_i32 s60, 0, 0x14000
	s_add_i32 m0, s43, 0xc000
	s_nop 0
	global_load_lds_dwordx4 v136, s[28:29]
	s_add_i32 m0, s43, 0xe000
	s_nop 0
	global_load_lds_dwordx4 v138, s[28:29]
	v_add_u32_e32 v148, s58, v151
	ds_read_b128 v[140:143], v148
	ds_read_b128 v[144:147], v148 offset:1024
	ds_read_b128 v[156:159], v148 offset:2048
	ds_read_b128 v[160:163], v148 offset:3072
	v_add_u32_e32 v148, s60, v151
	ds_read_b128 v[164:167], v148
	ds_read_b128 v[168:171], v148 offset:1024
	ds_read_b128 v[172:175], v148 offset:2048
	ds_read_b128 v[176:179], v148 offset:3072
	ds_read_b128 v[180:183], v154
	ds_read_b128 v[184:187], v154 offset:1024
	ds_read_b128 v[188:191], v154 offset:2048
	ds_read_b128 v[192:195], v154 offset:3072
	ds_read_b128 v[196:199], v154 offset:4096
	ds_read_b128 v[200:203], v154 offset:5120
	ds_read_b128 v[208:211], v154 offset:6144
	ds_read_b128 v[212:215], v154 offset:7168
	s_waitcnt vmcnt(8)
	s_waitcnt lgkmcnt(0)
	s_barrier
	s_setprio 1
	s_waitcnt lgkmcnt(0)
	v_mfma_f32_16x16x32_bf16 v[128:131], v[140:143], v[180:183], 0
	v_mfma_f32_16x16x32_bf16 v[128:131], v[144:147], v[184:187], v[128:131]
	v_mfma_f32_16x16x32_bf16 v[120:123], v[164:167], v[180:183], 0
	v_mfma_f32_16x16x32_bf16 v[120:123], v[168:171], v[184:187], v[120:123]
	v_mfma_f32_16x16x32_bf16 v[124:127], v[156:159], v[180:183], 0
	v_mfma_f32_16x16x32_bf16 v[124:127], v[160:163], v[184:187], v[124:127]
	v_mfma_f32_16x16x32_bf16 v[116:119], v[172:175], v[180:183], 0
	v_mfma_f32_16x16x32_bf16 v[116:119], v[176:179], v[184:187], v[116:119]
	v_mfma_f32_16x16x32_bf16 v[112:115], v[140:143], v[188:191], 0
	v_mfma_f32_16x16x32_bf16 v[112:115], v[144:147], v[192:195], v[112:115]
	v_mfma_f32_16x16x32_bf16 v[104:107], v[164:167], v[188:191], 0
	v_mfma_f32_16x16x32_bf16 v[104:107], v[168:171], v[192:195], v[104:107]
	v_mfma_f32_16x16x32_bf16 v[108:111], v[156:159], v[188:191], 0
	v_mfma_f32_16x16x32_bf16 v[108:111], v[160:163], v[192:195], v[108:111]
	v_mfma_f32_16x16x32_bf16 v[100:103], v[172:175], v[188:191], 0
	v_mfma_f32_16x16x32_bf16 v[100:103], v[176:179], v[192:195], v[100:103]
	v_mfma_f32_16x16x32_bf16 v[96:99], v[140:143], v[196:199], 0
	v_mfma_f32_16x16x32_bf16 v[96:99], v[144:147], v[200:203], v[96:99]
	v_mfma_f32_16x16x32_bf16 v[88:91], v[164:167], v[196:199], 0
	v_mfma_f32_16x16x32_bf16 v[88:91], v[168:171], v[200:203], v[88:91]
	v_mfma_f32_16x16x32_bf16 v[92:95], v[156:159], v[196:199], 0
	v_mfma_f32_16x16x32_bf16 v[92:95], v[160:163], v[200:203], v[92:95]
	v_mfma_f32_16x16x32_bf16 v[84:87], v[172:175], v[196:199], 0
	v_mfma_f32_16x16x32_bf16 v[84:87], v[176:179], v[200:203], v[84:87]
	v_mfma_f32_16x16x32_bf16 v[80:83], v[140:143], v[208:211], 0
	v_mfma_f32_16x16x32_bf16 v[80:83], v[144:147], v[212:215], v[80:83]
	v_mfma_f32_16x16x32_bf16 v[72:75], v[164:167], v[208:211], 0
	v_mfma_f32_16x16x32_bf16 v[72:75], v[168:171], v[212:215], v[72:75]
	v_mfma_f32_16x16x32_bf16 v[76:79], v[156:159], v[208:211], 0
	v_mfma_f32_16x16x32_bf16 v[76:79], v[160:163], v[212:215], v[76:79]
	v_mfma_f32_16x16x32_bf16 v[68:71], v[172:175], v[208:211], 0
	v_mfma_f32_16x16x32_bf16 v[68:71], v[176:179], v[212:215], v[68:71]
	s_setprio 0
	s_barrier
	s_sleep 2
	s_add_i32 s58, s58, s41
	s_mov_b32 m0, s58
	ds_read_b128 v[180:183], v154 offset:16384
	ds_read_b128 v[184:187], v154 offset:17408
	ds_read_b128 v[188:191], v154 offset:18432
	ds_read_b128 v[192:195], v154 offset:19456
	ds_read_b128 v[196:199], v154 offset:20480
	ds_read_b128 v[200:203], v154 offset:21504
	ds_read_b128 v[208:211], v154 offset:22528
	ds_read_b128 v[212:215], v154 offset:23552
	global_load_lds_dwordx4 v2, s[30:31]
	s_add_i32 m0, s58, 0x2000
	s_add_u32 s62, s30, 0x80000
	s_addc_u32 s63, s31, 0
	s_add_i32 s58, s60, s41
	global_load_lds_dwordx4 v0, s[30:31]
	s_mov_b32 m0, s58
	s_nop 0
	global_load_lds_dwordx4 v2, s[62:63]
	s_add_i32 m0, s58, 0x2000
	s_nop 0
	global_load_lds_dwordx4 v0, s[62:63]
	s_mov_b32 m0, s43
	s_nop 0
	global_load_lds_dwordx4 v134, s[38:39]
	s_mov_b32 m0, s44
	s_nop 0
	global_load_lds_dwordx4 v132, s[38:39]
	s_waitcnt vmcnt(8)
	s_waitcnt lgkmcnt(0)
	s_barrier
	s_setprio 1
	s_waitcnt lgkmcnt(0)
	v_mfma_f32_16x16x32_bf16 v[64:67], v[140:143], v[180:183], 0
	v_mfma_f32_16x16x32_bf16 v[64:67], v[144:147], v[184:187], v[64:67]
	v_mfma_f32_16x16x32_bf16 v[56:59], v[164:167], v[180:183], 0
	v_mfma_f32_16x16x32_bf16 v[56:59], v[168:171], v[184:187], v[56:59]
	v_mfma_f32_16x16x32_bf16 v[60:63], v[156:159], v[180:183], 0
	v_mfma_f32_16x16x32_bf16 v[60:63], v[160:163], v[184:187], v[60:63]
	v_mfma_f32_16x16x32_bf16 v[52:55], v[172:175], v[180:183], 0
	v_mfma_f32_16x16x32_bf16 v[52:55], v[176:179], v[184:187], v[52:55]
	v_mfma_f32_16x16x32_bf16 v[48:51], v[140:143], v[188:191], 0
	v_mfma_f32_16x16x32_bf16 v[48:51], v[144:147], v[192:195], v[48:51]
	v_mfma_f32_16x16x32_bf16 v[40:43], v[164:167], v[188:191], 0
	v_mfma_f32_16x16x32_bf16 v[40:43], v[168:171], v[192:195], v[40:43]
	v_mfma_f32_16x16x32_bf16 v[44:47], v[156:159], v[188:191], 0
	v_mfma_f32_16x16x32_bf16 v[44:47], v[160:163], v[192:195], v[44:47]
	v_mfma_f32_16x16x32_bf16 v[36:39], v[172:175], v[188:191], 0
	v_mfma_f32_16x16x32_bf16 v[36:39], v[176:179], v[192:195], v[36:39]
	v_mfma_f32_16x16x32_bf16 v[32:35], v[140:143], v[196:199], 0
	v_mfma_f32_16x16x32_bf16 v[32:35], v[144:147], v[200:203], v[32:35]
	v_mfma_f32_16x16x32_bf16 v[24:27], v[164:167], v[196:199], 0
	v_mfma_f32_16x16x32_bf16 v[24:27], v[168:171], v[200:203], v[24:27]
	v_mfma_f32_16x16x32_bf16 v[28:31], v[156:159], v[196:199], 0
	v_mfma_f32_16x16x32_bf16 v[28:31], v[160:163], v[200:203], v[28:31]
	v_mfma_f32_16x16x32_bf16 v[20:23], v[172:175], v[196:199], 0
	v_mfma_f32_16x16x32_bf16 v[20:23], v[176:179], v[200:203], v[20:23]
	v_mfma_f32_16x16x32_bf16 v[16:19], v[140:143], v[208:211], 0
	v_mfma_f32_16x16x32_bf16 v[16:19], v[144:147], v[212:215], v[16:19]
	v_mfma_f32_16x16x32_bf16 v[8:11], v[164:167], v[208:211], 0
	v_mfma_f32_16x16x32_bf16 v[8:11], v[168:171], v[212:215], v[8:11]
	v_mfma_f32_16x16x32_bf16 v[12:15], v[156:159], v[208:211], 0
	v_mfma_f32_16x16x32_bf16 v[12:15], v[160:163], v[212:215], v[12:15]
	v_mfma_f32_16x16x32_bf16 v[4:7], v[172:175], v[208:211], 0
	v_mfma_f32_16x16x32_bf16 v[4:7], v[176:179], v[212:215], v[4:7]
	s_setprio 0
	s_barrier
	s_sleep 1
	s_add_i32 s58, 0, 0x18000
	s_add_i32 s60, 0, 0x1c000
	s_add_u32 s38, s38, 0x80000
	s_addc_u32 s39, s39, 0
	s_mov_b32 m0, s45
	s_nop 0
	global_load_lds_dwordx4 v134, s[38:39]
	s_mov_b32 m0, s47
	s_nop 0
	global_load_lds_dwordx4 v132, s[38:39]
	v_add_u32_e32 v155, s58, v151
	ds_read_b128 v[140:143], v155
	ds_read_b128 v[144:147], v155 offset:1024
	ds_read_b128 v[156:159], v155 offset:2048
	ds_read_b128 v[160:163], v155 offset:3072
	v_add_u32_e32 v155, s60, v151
	ds_read_b128 v[164:167], v155
	ds_read_b128 v[168:171], v155 offset:1024
	ds_read_b128 v[172:175], v155 offset:2048
	ds_read_b128 v[176:179], v155 offset:3072
	ds_read_b128 v[180:183], v154 offset:32768
	ds_read_b128 v[184:187], v154 offset:33792
	ds_read_b128 v[188:191], v154 offset:34816
	ds_read_b128 v[192:195], v154 offset:35840
	ds_read_b128 v[196:199], v154 offset:36864
	ds_read_b128 v[200:203], v154 offset:37888
	ds_read_b128 v[208:211], v154 offset:38912
	ds_read_b128 v[212:215], v154 offset:39936
	s_waitcnt vmcnt(8)
	s_waitcnt lgkmcnt(0)
	s_barrier
	s_setprio 1
	s_waitcnt lgkmcnt(0)
	v_mfma_f32_16x16x32_bf16 v[128:131], v[140:143], v[180:183], v[128:131]
	v_mfma_f32_16x16x32_bf16 v[128:131], v[144:147], v[184:187], v[128:131]
	v_mfma_f32_16x16x32_bf16 v[120:123], v[164:167], v[180:183], v[120:123]
	v_mfma_f32_16x16x32_bf16 v[120:123], v[168:171], v[184:187], v[120:123]
	v_mfma_f32_16x16x32_bf16 v[124:127], v[156:159], v[180:183], v[124:127]
	v_mfma_f32_16x16x32_bf16 v[124:127], v[160:163], v[184:187], v[124:127]
	v_mfma_f32_16x16x32_bf16 v[116:119], v[172:175], v[180:183], v[116:119]
	v_mfma_f32_16x16x32_bf16 v[116:119], v[176:179], v[184:187], v[116:119]
	v_mfma_f32_16x16x32_bf16 v[112:115], v[140:143], v[188:191], v[112:115]
	v_mfma_f32_16x16x32_bf16 v[112:115], v[144:147], v[192:195], v[112:115]
	v_mfma_f32_16x16x32_bf16 v[104:107], v[164:167], v[188:191], v[104:107]
	v_mfma_f32_16x16x32_bf16 v[104:107], v[168:171], v[192:195], v[104:107]
	v_mfma_f32_16x16x32_bf16 v[108:111], v[156:159], v[188:191], v[108:111]
	v_mfma_f32_16x16x32_bf16 v[108:111], v[160:163], v[192:195], v[108:111]
	v_mfma_f32_16x16x32_bf16 v[100:103], v[172:175], v[188:191], v[100:103]
	v_mfma_f32_16x16x32_bf16 v[100:103], v[176:179], v[192:195], v[100:103]
	v_mfma_f32_16x16x32_bf16 v[96:99], v[140:143], v[196:199], v[96:99]
	v_mfma_f32_16x16x32_bf16 v[96:99], v[144:147], v[200:203], v[96:99]
	v_mfma_f32_16x16x32_bf16 v[88:91], v[164:167], v[196:199], v[88:91]
	v_mfma_f32_16x16x32_bf16 v[88:91], v[168:171], v[200:203], v[88:91]
	v_mfma_f32_16x16x32_bf16 v[92:95], v[156:159], v[196:199], v[92:95]
	v_mfma_f32_16x16x32_bf16 v[92:95], v[160:163], v[200:203], v[92:95]
	v_mfma_f32_16x16x32_bf16 v[84:87], v[172:175], v[196:199], v[84:87]
	v_mfma_f32_16x16x32_bf16 v[84:87], v[176:179], v[200:203], v[84:87]
	v_mfma_f32_16x16x32_bf16 v[80:83], v[140:143], v[208:211], v[80:83]
	v_mfma_f32_16x16x32_bf16 v[80:83], v[144:147], v[212:215], v[80:83]
	v_mfma_f32_16x16x32_bf16 v[72:75], v[164:167], v[208:211], v[72:75]
	v_mfma_f32_16x16x32_bf16 v[72:75], v[168:171], v[212:215], v[72:75]
	v_mfma_f32_16x16x32_bf16 v[76:79], v[156:159], v[208:211], v[76:79]
	v_mfma_f32_16x16x32_bf16 v[76:79], v[160:163], v[212:215], v[76:79]
	v_mfma_f32_16x16x32_bf16 v[68:71], v[172:175], v[208:211], v[68:71]
	v_mfma_f32_16x16x32_bf16 v[68:71], v[176:179], v[212:215], v[68:71]
	s_setprio 0
	s_barrier
	s_sleep 2
	s_add_i32 s62, s58, s41
	s_add_u32 s30, s30, 0x80
	s_addc_u32 s31, s31, 0
	s_mov_b32 m0, s62
	ds_read_b128 v[180:183], v154 offset:49152
	ds_read_b128 v[184:187], v154 offset:50176
	ds_read_b128 v[188:191], v154 offset:51200
	ds_read_b128 v[192:195], v154 offset:52224
	ds_read_b128 v[196:199], v154 offset:53248
	ds_read_b128 v[200:203], v154 offset:54272
	ds_read_b128 v[208:211], v154 offset:55296
	ds_read_b128 v[212:215], v154 offset:56320
	global_load_lds_dwordx4 v2, s[30:31]
	s_add_i32 m0, s62, 0x2000
	s_nop 0
	s_add_i32 s62, s60, s41
	global_load_lds_dwordx4 v0, s[30:31]
	s_add_u32 s30, s30, 0x80000
	s_addc_u32 s31, s31, 0
	s_mov_b32 m0, s62
	s_nop 0
	global_load_lds_dwordx4 v2, s[30:31]
	s_add_i32 m0, s62, 0x2000
	s_nop 0
	global_load_lds_dwordx4 v0, s[30:31]
	s_sub_u32 s38, s38, 0x7ff80
	s_subb_u32 s39, s39, 0
	s_mov_b32 m0, s48
	s_nop 0
	global_load_lds_dwordx4 v134, s[38:39]
	s_mov_b32 m0, s49
	s_nop 0
	global_load_lds_dwordx4 v132, s[38:39]
	s_waitcnt vmcnt(8)
	s_waitcnt lgkmcnt(0)
	s_barrier
	s_setprio 1
	s_waitcnt lgkmcnt(0)
	v_mfma_f32_16x16x32_bf16 v[64:67], v[140:143], v[180:183], v[64:67]
	v_mfma_f32_16x16x32_bf16 v[64:67], v[144:147], v[184:187], v[64:67]
	v_mfma_f32_16x16x32_bf16 v[56:59], v[164:167], v[180:183], v[56:59]
	v_mfma_f32_16x16x32_bf16 v[56:59], v[168:171], v[184:187], v[56:59]
	v_mfma_f32_16x16x32_bf16 v[60:63], v[156:159], v[180:183], v[60:63]
	v_mfma_f32_16x16x32_bf16 v[60:63], v[160:163], v[184:187], v[60:63]
	v_mfma_f32_16x16x32_bf16 v[52:55], v[172:175], v[180:183], v[52:55]
	v_mfma_f32_16x16x32_bf16 v[52:55], v[176:179], v[184:187], v[52:55]
	v_mfma_f32_16x16x32_bf16 v[48:51], v[140:143], v[188:191], v[48:51]
	v_mfma_f32_16x16x32_bf16 v[48:51], v[144:147], v[192:195], v[48:51]
	v_mfma_f32_16x16x32_bf16 v[40:43], v[164:167], v[188:191], v[40:43]
	v_mfma_f32_16x16x32_bf16 v[40:43], v[168:171], v[192:195], v[40:43]
	v_mfma_f32_16x16x32_bf16 v[44:47], v[156:159], v[188:191], v[44:47]
	v_mfma_f32_16x16x32_bf16 v[44:47], v[160:163], v[192:195], v[44:47]
	v_mfma_f32_16x16x32_bf16 v[36:39], v[172:175], v[188:191], v[36:39]
	v_mfma_f32_16x16x32_bf16 v[36:39], v[176:179], v[192:195], v[36:39]
	v_mfma_f32_16x16x32_bf16 v[32:35], v[140:143], v[196:199], v[32:35]
	v_mfma_f32_16x16x32_bf16 v[32:35], v[144:147], v[200:203], v[32:35]
	v_mfma_f32_16x16x32_bf16 v[24:27], v[164:167], v[196:199], v[24:27]
	v_mfma_f32_16x16x32_bf16 v[24:27], v[168:171], v[200:203], v[24:27]
	v_mfma_f32_16x16x32_bf16 v[28:31], v[156:159], v[196:199], v[28:31]
	v_mfma_f32_16x16x32_bf16 v[28:31], v[160:163], v[200:203], v[28:31]
	v_mfma_f32_16x16x32_bf16 v[20:23], v[172:175], v[196:199], v[20:23]
	v_mfma_f32_16x16x32_bf16 v[20:23], v[176:179], v[200:203], v[20:23]
	v_mfma_f32_16x16x32_bf16 v[16:19], v[140:143], v[208:211], v[16:19]
	v_mfma_f32_16x16x32_bf16 v[16:19], v[144:147], v[212:215], v[16:19]
	v_mfma_f32_16x16x32_bf16 v[8:11], v[164:167], v[208:211], v[8:11]
	v_mfma_f32_16x16x32_bf16 v[8:11], v[168:171], v[212:215], v[8:11]
	v_mfma_f32_16x16x32_bf16 v[12:15], v[156:159], v[208:211], v[12:15]
	v_mfma_f32_16x16x32_bf16 v[12:15], v[160:163], v[212:215], v[12:15]
	v_mfma_f32_16x16x32_bf16 v[4:7], v[172:175], v[208:211], v[4:7]
	v_mfma_f32_16x16x32_bf16 v[4:7], v[176:179], v[212:215], v[4:7]
	s_setprio 0
	s_barrier
	s_add_i32 s57, s57, 2
	s_add_u32 s28, s28, 0x100
	s_addc_u32 s29, s29, 0
	s_add_u32 s55, s55, 0x100
	s_addc_u32 s56, s56, 0
	s_cmp_gt_u32 s57, 29
.LBB0_211:
	s_sleep 1
	s_add_u32 s30, s28, 0xfff80080
	s_addc_u32 s31, s29, -1
	s_add_i32 s58, 0, 0x10000
	s_cmp_eq_u32 s57, 28
	s_cselect_b32 s39, s21, s31
	s_cselect_b32 s38, s53, s30
	s_cselect_b32 s31, s19, s56
	s_cselect_b32 s30, s54, s55
	s_add_i32 s60, 0, 0x14000
	s_add_i32 m0, s43, 0xc000
	s_nop 0
	global_load_lds_dwordx4 v136, s[28:29]
	s_add_i32 m0, s43, 0xe000
	s_nop 0
	global_load_lds_dwordx4 v138, s[28:29]
	v_add_u32_e32 v148, s58, v151
	ds_read_b128 v[140:143], v148
	ds_read_b128 v[144:147], v148 offset:1024
	ds_read_b128 v[156:159], v148 offset:2048
	ds_read_b128 v[160:163], v148 offset:3072
	v_add_u32_e32 v148, s60, v151
	ds_read_b128 v[164:167], v148
	ds_read_b128 v[168:171], v148 offset:1024
	ds_read_b128 v[172:175], v148 offset:2048
	ds_read_b128 v[176:179], v148 offset:3072
	ds_read_b128 v[180:183], v154
	ds_read_b128 v[184:187], v154 offset:1024
	ds_read_b128 v[188:191], v154 offset:2048
	ds_read_b128 v[192:195], v154 offset:3072
	ds_read_b128 v[196:199], v154 offset:4096
	ds_read_b128 v[200:203], v154 offset:5120
	ds_read_b128 v[208:211], v154 offset:6144
	ds_read_b128 v[212:215], v154 offset:7168
	s_waitcnt vmcnt(8)
	s_waitcnt lgkmcnt(0)
	s_barrier
	s_setprio 1
	s_waitcnt lgkmcnt(0)
	v_mfma_f32_16x16x32_bf16 v[128:131], v[140:143], v[180:183], v[128:131]
	v_mfma_f32_16x16x32_bf16 v[128:131], v[144:147], v[184:187], v[128:131]
	v_mfma_f32_16x16x32_bf16 v[120:123], v[164:167], v[180:183], v[120:123]
	v_mfma_f32_16x16x32_bf16 v[120:123], v[168:171], v[184:187], v[120:123]
	v_mfma_f32_16x16x32_bf16 v[124:127], v[156:159], v[180:183], v[124:127]
	v_mfma_f32_16x16x32_bf16 v[124:127], v[160:163], v[184:187], v[124:127]
	v_mfma_f32_16x16x32_bf16 v[116:119], v[172:175], v[180:183], v[116:119]
	v_mfma_f32_16x16x32_bf16 v[116:119], v[176:179], v[184:187], v[116:119]
	v_mfma_f32_16x16x32_bf16 v[112:115], v[140:143], v[188:191], v[112:115]
	v_mfma_f32_16x16x32_bf16 v[112:115], v[144:147], v[192:195], v[112:115]
	v_mfma_f32_16x16x32_bf16 v[104:107], v[164:167], v[188:191], v[104:107]
	v_mfma_f32_16x16x32_bf16 v[104:107], v[168:171], v[192:195], v[104:107]
	v_mfma_f32_16x16x32_bf16 v[108:111], v[156:159], v[188:191], v[108:111]
	v_mfma_f32_16x16x32_bf16 v[108:111], v[160:163], v[192:195], v[108:111]
	v_mfma_f32_16x16x32_bf16 v[100:103], v[172:175], v[188:191], v[100:103]
	v_mfma_f32_16x16x32_bf16 v[100:103], v[176:179], v[192:195], v[100:103]
	v_mfma_f32_16x16x32_bf16 v[96:99], v[140:143], v[196:199], v[96:99]
	v_mfma_f32_16x16x32_bf16 v[96:99], v[144:147], v[200:203], v[96:99]
	v_mfma_f32_16x16x32_bf16 v[88:91], v[164:167], v[196:199], v[88:91]
	v_mfma_f32_16x16x32_bf16 v[88:91], v[168:171], v[200:203], v[88:91]
	v_mfma_f32_16x16x32_bf16 v[92:95], v[156:159], v[196:199], v[92:95]
	v_mfma_f32_16x16x32_bf16 v[92:95], v[160:163], v[200:203], v[92:95]
	v_mfma_f32_16x16x32_bf16 v[84:87], v[172:175], v[196:199], v[84:87]
	v_mfma_f32_16x16x32_bf16 v[84:87], v[176:179], v[200:203], v[84:87]
	v_mfma_f32_16x16x32_bf16 v[80:83], v[140:143], v[208:211], v[80:83]
	v_mfma_f32_16x16x32_bf16 v[80:83], v[144:147], v[212:215], v[80:83]
	v_mfma_f32_16x16x32_bf16 v[72:75], v[164:167], v[208:211], v[72:75]
	v_mfma_f32_16x16x32_bf16 v[72:75], v[168:171], v[212:215], v[72:75]
	v_mfma_f32_16x16x32_bf16 v[76:79], v[156:159], v[208:211], v[76:79]
	v_mfma_f32_16x16x32_bf16 v[76:79], v[160:163], v[212:215], v[76:79]
	v_mfma_f32_16x16x32_bf16 v[68:71], v[172:175], v[208:211], v[68:71]
	v_mfma_f32_16x16x32_bf16 v[68:71], v[176:179], v[212:215], v[68:71]
	s_setprio 0
	s_barrier
	s_sleep 2
	s_add_i32 s58, s58, s41
	s_mov_b32 m0, s58
	ds_read_b128 v[180:183], v154 offset:16384
	ds_read_b128 v[184:187], v154 offset:17408
	ds_read_b128 v[188:191], v154 offset:18432
	ds_read_b128 v[192:195], v154 offset:19456
	ds_read_b128 v[196:199], v154 offset:20480
	ds_read_b128 v[200:203], v154 offset:21504
	ds_read_b128 v[208:211], v154 offset:22528
	ds_read_b128 v[212:215], v154 offset:23552
	global_load_lds_dwordx4 v2, s[30:31]
	s_add_i32 m0, s58, 0x2000
	s_add_u32 s62, s30, 0x80000
	s_addc_u32 s63, s31, 0
	s_add_i32 s58, s60, s41
	global_load_lds_dwordx4 v0, s[30:31]
	s_mov_b32 m0, s58
	s_nop 0
	global_load_lds_dwordx4 v2, s[62:63]
	s_add_i32 m0, s58, 0x2000
	s_nop 0
	global_load_lds_dwordx4 v0, s[62:63]
	s_mov_b32 m0, s43
	s_nop 0
	global_load_lds_dwordx4 v134, s[38:39]
	s_mov_b32 m0, s44
	s_nop 0
	global_load_lds_dwordx4 v132, s[38:39]
	s_waitcnt vmcnt(8)
	s_waitcnt lgkmcnt(0)
	s_barrier
	s_setprio 1
	s_waitcnt lgkmcnt(0)
	v_mfma_f32_16x16x32_bf16 v[64:67], v[140:143], v[180:183], v[64:67]
	v_mfma_f32_16x16x32_bf16 v[64:67], v[144:147], v[184:187], v[64:67]
	v_mfma_f32_16x16x32_bf16 v[56:59], v[164:167], v[180:183], v[56:59]
	v_mfma_f32_16x16x32_bf16 v[56:59], v[168:171], v[184:187], v[56:59]
	v_mfma_f32_16x16x32_bf16 v[60:63], v[156:159], v[180:183], v[60:63]
	v_mfma_f32_16x16x32_bf16 v[60:63], v[160:163], v[184:187], v[60:63]
	v_mfma_f32_16x16x32_bf16 v[52:55], v[172:175], v[180:183], v[52:55]
	v_mfma_f32_16x16x32_bf16 v[52:55], v[176:179], v[184:187], v[52:55]
	v_mfma_f32_16x16x32_bf16 v[48:51], v[140:143], v[188:191], v[48:51]
	v_mfma_f32_16x16x32_bf16 v[48:51], v[144:147], v[192:195], v[48:51]
	v_mfma_f32_16x16x32_bf16 v[40:43], v[164:167], v[188:191], v[40:43]
	v_mfma_f32_16x16x32_bf16 v[40:43], v[168:171], v[192:195], v[40:43]
	v_mfma_f32_16x16x32_bf16 v[44:47], v[156:159], v[188:191], v[44:47]
	v_mfma_f32_16x16x32_bf16 v[44:47], v[160:163], v[192:195], v[44:47]
	v_mfma_f32_16x16x32_bf16 v[36:39], v[172:175], v[188:191], v[36:39]
	v_mfma_f32_16x16x32_bf16 v[36:39], v[176:179], v[192:195], v[36:39]
	v_mfma_f32_16x16x32_bf16 v[32:35], v[140:143], v[196:199], v[32:35]
	v_mfma_f32_16x16x32_bf16 v[32:35], v[144:147], v[200:203], v[32:35]
	v_mfma_f32_16x16x32_bf16 v[24:27], v[164:167], v[196:199], v[24:27]
	v_mfma_f32_16x16x32_bf16 v[24:27], v[168:171], v[200:203], v[24:27]
	v_mfma_f32_16x16x32_bf16 v[28:31], v[156:159], v[196:199], v[28:31]
	v_mfma_f32_16x16x32_bf16 v[28:31], v[160:163], v[200:203], v[28:31]
	v_mfma_f32_16x16x32_bf16 v[20:23], v[172:175], v[196:199], v[20:23]
	v_mfma_f32_16x16x32_bf16 v[20:23], v[176:179], v[200:203], v[20:23]
	v_mfma_f32_16x16x32_bf16 v[16:19], v[140:143], v[208:211], v[16:19]
	v_mfma_f32_16x16x32_bf16 v[16:19], v[144:147], v[212:215], v[16:19]
	v_mfma_f32_16x16x32_bf16 v[8:11], v[164:167], v[208:211], v[8:11]
	v_mfma_f32_16x16x32_bf16 v[8:11], v[168:171], v[212:215], v[8:11]
	v_mfma_f32_16x16x32_bf16 v[12:15], v[156:159], v[208:211], v[12:15]
	v_mfma_f32_16x16x32_bf16 v[12:15], v[160:163], v[212:215], v[12:15]
	v_mfma_f32_16x16x32_bf16 v[4:7], v[172:175], v[208:211], v[4:7]
	v_mfma_f32_16x16x32_bf16 v[4:7], v[176:179], v[212:215], v[4:7]
	s_setprio 0
	s_barrier
	s_sleep 1
	s_add_i32 s58, 0, 0x18000
	s_add_i32 s60, 0, 0x1c000
	s_add_u32 s38, s38, 0x80000
	s_addc_u32 s39, s39, 0
	s_mov_b32 m0, s45
	s_nop 0
	global_load_lds_dwordx4 v134, s[38:39]
	s_mov_b32 m0, s47
	s_nop 0
	global_load_lds_dwordx4 v132, s[38:39]
	v_add_u32_e32 v155, s58, v151
	ds_read_b128 v[140:143], v155
	ds_read_b128 v[144:147], v155 offset:1024
	ds_read_b128 v[156:159], v155 offset:2048
	ds_read_b128 v[160:163], v155 offset:3072
	v_add_u32_e32 v155, s60, v151
	ds_read_b128 v[164:167], v155
	ds_read_b128 v[168:171], v155 offset:1024
	ds_read_b128 v[172:175], v155 offset:2048
	ds_read_b128 v[176:179], v155 offset:3072
	ds_read_b128 v[180:183], v154 offset:32768
	ds_read_b128 v[184:187], v154 offset:33792
	ds_read_b128 v[188:191], v154 offset:34816
	ds_read_b128 v[192:195], v154 offset:35840
	ds_read_b128 v[196:199], v154 offset:36864
	ds_read_b128 v[200:203], v154 offset:37888
	ds_read_b128 v[208:211], v154 offset:38912
	ds_read_b128 v[212:215], v154 offset:39936
	s_waitcnt vmcnt(8)
	s_waitcnt lgkmcnt(0)
	s_barrier
	s_setprio 1
	s_waitcnt lgkmcnt(0)
	v_mfma_f32_16x16x32_bf16 v[128:131], v[140:143], v[180:183], v[128:131]
	v_mfma_f32_16x16x32_bf16 v[128:131], v[144:147], v[184:187], v[128:131]
	v_mfma_f32_16x16x32_bf16 v[120:123], v[164:167], v[180:183], v[120:123]
	v_mfma_f32_16x16x32_bf16 v[120:123], v[168:171], v[184:187], v[120:123]
	v_mfma_f32_16x16x32_bf16 v[124:127], v[156:159], v[180:183], v[124:127]
	v_mfma_f32_16x16x32_bf16 v[124:127], v[160:163], v[184:187], v[124:127]
	v_mfma_f32_16x16x32_bf16 v[116:119], v[172:175], v[180:183], v[116:119]
	v_mfma_f32_16x16x32_bf16 v[116:119], v[176:179], v[184:187], v[116:119]
	v_mfma_f32_16x16x32_bf16 v[112:115], v[140:143], v[188:191], v[112:115]
	v_mfma_f32_16x16x32_bf16 v[112:115], v[144:147], v[192:195], v[112:115]
	v_mfma_f32_16x16x32_bf16 v[104:107], v[164:167], v[188:191], v[104:107]
	v_mfma_f32_16x16x32_bf16 v[104:107], v[168:171], v[192:195], v[104:107]
	v_mfma_f32_16x16x32_bf16 v[108:111], v[156:159], v[188:191], v[108:111]
	v_mfma_f32_16x16x32_bf16 v[108:111], v[160:163], v[192:195], v[108:111]
	v_mfma_f32_16x16x32_bf16 v[100:103], v[172:175], v[188:191], v[100:103]
	v_mfma_f32_16x16x32_bf16 v[100:103], v[176:179], v[192:195], v[100:103]
	v_mfma_f32_16x16x32_bf16 v[96:99], v[140:143], v[196:199], v[96:99]
	v_mfma_f32_16x16x32_bf16 v[96:99], v[144:147], v[200:203], v[96:99]
	v_mfma_f32_16x16x32_bf16 v[88:91], v[164:167], v[196:199], v[88:91]
	v_mfma_f32_16x16x32_bf16 v[88:91], v[168:171], v[200:203], v[88:91]
	v_mfma_f32_16x16x32_bf16 v[92:95], v[156:159], v[196:199], v[92:95]
	v_mfma_f32_16x16x32_bf16 v[92:95], v[160:163], v[200:203], v[92:95]
	v_mfma_f32_16x16x32_bf16 v[84:87], v[172:175], v[196:199], v[84:87]
	v_mfma_f32_16x16x32_bf16 v[84:87], v[176:179], v[200:203], v[84:87]
	v_mfma_f32_16x16x32_bf16 v[80:83], v[140:143], v[208:211], v[80:83]
	v_mfma_f32_16x16x32_bf16 v[80:83], v[144:147], v[212:215], v[80:83]
	v_mfma_f32_16x16x32_bf16 v[72:75], v[164:167], v[208:211], v[72:75]
	v_mfma_f32_16x16x32_bf16 v[72:75], v[168:171], v[212:215], v[72:75]
	v_mfma_f32_16x16x32_bf16 v[76:79], v[156:159], v[208:211], v[76:79]
	v_mfma_f32_16x16x32_bf16 v[76:79], v[160:163], v[212:215], v[76:79]
	v_mfma_f32_16x16x32_bf16 v[68:71], v[172:175], v[208:211], v[68:71]
	v_mfma_f32_16x16x32_bf16 v[68:71], v[176:179], v[212:215], v[68:71]
	s_setprio 0
	s_barrier
	s_sleep 2
	s_add_i32 s62, s58, s41
	s_add_u32 s30, s30, 0x80
	s_addc_u32 s31, s31, 0
	s_mov_b32 m0, s62
	ds_read_b128 v[180:183], v154 offset:49152
	ds_read_b128 v[184:187], v154 offset:50176
	ds_read_b128 v[188:191], v154 offset:51200
	ds_read_b128 v[192:195], v154 offset:52224
	ds_read_b128 v[196:199], v154 offset:53248
	ds_read_b128 v[200:203], v154 offset:54272
	ds_read_b128 v[208:211], v154 offset:55296
	ds_read_b128 v[212:215], v154 offset:56320
	global_load_lds_dwordx4 v2, s[30:31]
	s_add_i32 m0, s62, 0x2000
	s_nop 0
	s_add_i32 s62, s60, s41
	global_load_lds_dwordx4 v0, s[30:31]
	s_add_u32 s30, s30, 0x80000
	s_addc_u32 s31, s31, 0
	s_mov_b32 m0, s62
	s_nop 0
	global_load_lds_dwordx4 v2, s[30:31]
	s_add_i32 m0, s62, 0x2000
	s_nop 0
	global_load_lds_dwordx4 v0, s[30:31]
	s_sub_u32 s38, s38, 0x7ff80
	s_subb_u32 s39, s39, 0
	s_mov_b32 m0, s48
	s_nop 0
	global_load_lds_dwordx4 v134, s[38:39]
	s_mov_b32 m0, s49
	s_nop 0
	global_load_lds_dwordx4 v132, s[38:39]
	s_waitcnt vmcnt(8)
	s_waitcnt lgkmcnt(0)
	s_barrier
	s_setprio 1
	s_waitcnt lgkmcnt(0)
	v_mfma_f32_16x16x32_bf16 v[64:67], v[140:143], v[180:183], v[64:67]
	v_mfma_f32_16x16x32_bf16 v[64:67], v[144:147], v[184:187], v[64:67]
	v_mfma_f32_16x16x32_bf16 v[56:59], v[164:167], v[180:183], v[56:59]
	v_mfma_f32_16x16x32_bf16 v[56:59], v[168:171], v[184:187], v[56:59]
	v_mfma_f32_16x16x32_bf16 v[60:63], v[156:159], v[180:183], v[60:63]
	v_mfma_f32_16x16x32_bf16 v[60:63], v[160:163], v[184:187], v[60:63]
	v_mfma_f32_16x16x32_bf16 v[52:55], v[172:175], v[180:183], v[52:55]
	v_mfma_f32_16x16x32_bf16 v[52:55], v[176:179], v[184:187], v[52:55]
	v_mfma_f32_16x16x32_bf16 v[48:51], v[140:143], v[188:191], v[48:51]
	v_mfma_f32_16x16x32_bf16 v[48:51], v[144:147], v[192:195], v[48:51]
	v_mfma_f32_16x16x32_bf16 v[40:43], v[164:167], v[188:191], v[40:43]
	v_mfma_f32_16x16x32_bf16 v[40:43], v[168:171], v[192:195], v[40:43]
	v_mfma_f32_16x16x32_bf16 v[44:47], v[156:159], v[188:191], v[44:47]
	v_mfma_f32_16x16x32_bf16 v[44:47], v[160:163], v[192:195], v[44:47]
	v_mfma_f32_16x16x32_bf16 v[36:39], v[172:175], v[188:191], v[36:39]
	v_mfma_f32_16x16x32_bf16 v[36:39], v[176:179], v[192:195], v[36:39]
	v_mfma_f32_16x16x32_bf16 v[32:35], v[140:143], v[196:199], v[32:35]
	v_mfma_f32_16x16x32_bf16 v[32:35], v[144:147], v[200:203], v[32:35]
	v_mfma_f32_16x16x32_bf16 v[24:27], v[164:167], v[196:199], v[24:27]
	v_mfma_f32_16x16x32_bf16 v[24:27], v[168:171], v[200:203], v[24:27]
	v_mfma_f32_16x16x32_bf16 v[28:31], v[156:159], v[196:199], v[28:31]
	v_mfma_f32_16x16x32_bf16 v[28:31], v[160:163], v[200:203], v[28:31]
	v_mfma_f32_16x16x32_bf16 v[20:23], v[172:175], v[196:199], v[20:23]
	v_mfma_f32_16x16x32_bf16 v[20:23], v[176:179], v[200:203], v[20:23]
	v_mfma_f32_16x16x32_bf16 v[16:19], v[140:143], v[208:211], v[16:19]
	v_mfma_f32_16x16x32_bf16 v[16:19], v[144:147], v[212:215], v[16:19]
	v_mfma_f32_16x16x32_bf16 v[8:11], v[164:167], v[208:211], v[8:11]
	v_mfma_f32_16x16x32_bf16 v[8:11], v[168:171], v[212:215], v[8:11]
	v_mfma_f32_16x16x32_bf16 v[12:15], v[156:159], v[208:211], v[12:15]
	v_mfma_f32_16x16x32_bf16 v[12:15], v[160:163], v[212:215], v[12:15]
	v_mfma_f32_16x16x32_bf16 v[4:7], v[172:175], v[208:211], v[4:7]
	v_mfma_f32_16x16x32_bf16 v[4:7], v[176:179], v[212:215], v[4:7]
	s_setprio 0
	s_barrier
	s_add_i32 s57, s57, 2
	s_add_u32 s28, s28, 0x100
	s_addc_u32 s29, s29, 0
	s_add_u32 s55, s55, 0x100
	s_addc_u32 s56, s56, 0
	s_cmp_gt_u32 s57, 29
	s_cbranch_scc0 .LBB0_211
	s_and_b64 vcc, exec, s[16:17]
	s_cbranch_vccz .LBB0_214
	s_barrier

.LBB0_300:
	s_add_u32 s40, s18, 0x100
	s_addc_u32 s41, s19, 0
	s_mov_b32 s48, -2
	s_sleep 1
	s_add_u32 s18, s16, 0x100
	s_addc_u32 s19, s17, 0
	s_add_i32 s49, 0, 0x10000
	s_cmpk_eq_i32 s48, 0x54
	s_cselect_b32 s23, s13, s19
	s_cselect_b32 s22, s12, s18
	s_cselect_b32 s21, s15, s41
	s_cselect_b32 s20, s14, s40
	s_add_i32 s50, 0, 0x14000
	v_lshl_add_u64 v[204:205], s[16:17], 0, v[192:193]
	s_add_i32 m0, s28, 0xc000
	s_nop 0
	global_load_lds_dwordx4 v[204:205], off
	v_lshl_add_u64 v[204:205], s[16:17], 0, v[194:195]
	s_add_i32 m0, s28, 0xe000
	s_nop 0
	global_load_lds_dwordx4 v[204:205], off
	v_add_u32_e32 v144, s49, v219
	v_add_u32_e32 v160, s50, v219
	ds_read_b128 v[124:127], v144
	ds_read_b128 v[128:131], v144 offset:1024
	ds_read_b128 v[140:143], v144 offset:2048
	ds_read_b128 v[144:147], v144 offset:3072
	ds_read_b128 v[148:151], v160
	ds_read_b128 v[152:155], v160 offset:1024
	ds_read_b128 v[156:159], v160 offset:2048
	ds_read_b128 v[160:163], v160 offset:3072
	ds_read_b128 v[164:167], v221
	ds_read_b128 v[168:171], v221 offset:1024
	ds_read_b128 v[172:175], v221 offset:2048
	ds_read_b128 v[176:179], v221 offset:3072
	ds_read_b128 v[180:183], v221 offset:4096
	ds_read_b128 v[184:187], v221 offset:5120
	ds_read_b128 v[196:199], v221 offset:6144
	ds_read_b128 v[200:203], v221 offset:7168
	s_waitcnt vmcnt(8)
	s_waitcnt lgkmcnt(0)
	s_barrier
	s_setprio 1
	s_waitcnt lgkmcnt(0)
	v_mfma_f32_16x16x32_bf16 v[136:139], v[124:127], v[164:167], 0
	v_mfma_f32_16x16x32_bf16 v[136:139], v[128:131], v[168:171], v[136:139]
	v_mfma_f32_16x16x32_bf16 v[120:123], v[148:151], v[164:167], 0
	v_mfma_f32_16x16x32_bf16 v[120:123], v[152:155], v[168:171], v[120:123]
	v_mfma_f32_16x16x32_bf16 v[132:135], v[140:143], v[164:167], 0
	v_mfma_f32_16x16x32_bf16 v[132:135], v[144:147], v[168:171], v[132:135]
	v_mfma_f32_16x16x32_bf16 v[116:119], v[156:159], v[164:167], 0
	v_mfma_f32_16x16x32_bf16 v[116:119], v[160:163], v[168:171], v[116:119]
	v_mfma_f32_16x16x32_bf16 v[112:115], v[124:127], v[172:175], 0
	v_mfma_f32_16x16x32_bf16 v[112:115], v[128:131], v[176:179], v[112:115]
	v_mfma_f32_16x16x32_bf16 v[104:107], v[148:151], v[172:175], 0
	v_mfma_f32_16x16x32_bf16 v[104:107], v[152:155], v[176:179], v[104:107]
	v_mfma_f32_16x16x32_bf16 v[108:111], v[140:143], v[172:175], 0
	v_mfma_f32_16x16x32_bf16 v[108:111], v[144:147], v[176:179], v[108:111]
	v_mfma_f32_16x16x32_bf16 v[100:103], v[156:159], v[172:175], 0
	v_mfma_f32_16x16x32_bf16 v[100:103], v[160:163], v[176:179], v[100:103]
	v_mfma_f32_16x16x32_bf16 v[96:99], v[124:127], v[180:183], 0
	v_mfma_f32_16x16x32_bf16 v[96:99], v[128:131], v[184:187], v[96:99]
	v_mfma_f32_16x16x32_bf16 v[88:91], v[148:151], v[180:183], 0
	v_mfma_f32_16x16x32_bf16 v[88:91], v[152:155], v[184:187], v[88:91]
	v_mfma_f32_16x16x32_bf16 v[92:95], v[140:143], v[180:183], 0
	v_mfma_f32_16x16x32_bf16 v[92:95], v[144:147], v[184:187], v[92:95]
	v_mfma_f32_16x16x32_bf16 v[84:87], v[156:159], v[180:183], 0
	v_mfma_f32_16x16x32_bf16 v[84:87], v[160:163], v[184:187], v[84:87]
	v_mfma_f32_16x16x32_bf16 v[80:83], v[124:127], v[196:199], 0
	v_mfma_f32_16x16x32_bf16 v[80:83], v[128:131], v[200:203], v[80:83]
	v_mfma_f32_16x16x32_bf16 v[72:75], v[148:151], v[196:199], 0
	v_mfma_f32_16x16x32_bf16 v[72:75], v[152:155], v[200:203], v[72:75]
	v_mfma_f32_16x16x32_bf16 v[76:79], v[140:143], v[196:199], 0
	v_mfma_f32_16x16x32_bf16 v[76:79], v[144:147], v[200:203], v[76:79]
	v_mfma_f32_16x16x32_bf16 v[68:71], v[156:159], v[196:199], 0
	v_mfma_f32_16x16x32_bf16 v[68:71], v[160:163], v[200:203], v[68:71]
	s_setprio 0
	s_barrier
	s_sleep 2
	s_add_i32 s16, s49, s2
	v_lshl_add_u64 v[204:205], s[20:21], 0, v[2:3]
	s_mov_b32 m0, s16
	ds_read_b128 v[164:167], v221 offset:16384
	ds_read_b128 v[168:171], v221 offset:17408
	ds_read_b128 v[172:175], v221 offset:18432
	ds_read_b128 v[176:179], v221 offset:19456
	ds_read_b128 v[180:183], v221 offset:20480
	ds_read_b128 v[184:187], v221 offset:21504
	ds_read_b128 v[196:199], v221 offset:22528
	ds_read_b128 v[200:203], v221 offset:23552
	global_load_lds_dwordx4 v[204:205], off
	s_add_i32 m0, s16, 0x2000
	s_add_u32 s16, s20, 0x160000
	v_lshl_add_u64 v[206:207], s[20:21], 0, v[190:191]
	s_addc_u32 s17, s21, 0
	s_add_i32 s49, s50, s2
	global_load_lds_dwordx4 v[206:207], off
	v_lshl_add_u64 v[208:209], s[16:17], 0, v[2:3]
	s_mov_b32 m0, s49
	v_lshl_add_u64 v[210:211], s[22:23], 0, v[188:189]
	global_load_lds_dwordx4 v[208:209], off
	v_lshl_add_u64 v[208:209], s[16:17], 0, v[190:191]
	s_add_i32 m0, s49, 0x2000
	s_nop 0
	global_load_lds_dwordx4 v[208:209], off
	v_lshl_add_u64 v[208:209], s[22:23], 0, v[0:1]
	s_mov_b32 m0, s28
	s_nop 0
	global_load_lds_dwordx4 v[208:209], off
	s_mov_b32 m0, s29
	s_nop 0
	global_load_lds_dwordx4 v[210:211], off
	s_waitcnt vmcnt(8)
	s_waitcnt lgkmcnt(0)
	s_barrier
	s_setprio 1
	s_waitcnt lgkmcnt(0)
	v_mfma_f32_16x16x32_bf16 v[64:67], v[124:127], v[164:167], 0
	v_mfma_f32_16x16x32_bf16 v[64:67], v[128:131], v[168:171], v[64:67]
	v_mfma_f32_16x16x32_bf16 v[56:59], v[148:151], v[164:167], 0
	v_mfma_f32_16x16x32_bf16 v[56:59], v[152:155], v[168:171], v[56:59]
	v_mfma_f32_16x16x32_bf16 v[60:63], v[140:143], v[164:167], 0
	v_mfma_f32_16x16x32_bf16 v[60:63], v[144:147], v[168:171], v[60:63]
	v_mfma_f32_16x16x32_bf16 v[52:55], v[156:159], v[164:167], 0
	v_mfma_f32_16x16x32_bf16 v[52:55], v[160:163], v[168:171], v[52:55]
	v_mfma_f32_16x16x32_bf16 v[48:51], v[124:127], v[172:175], 0
	v_mfma_f32_16x16x32_bf16 v[48:51], v[128:131], v[176:179], v[48:51]
	v_mfma_f32_16x16x32_bf16 v[40:43], v[148:151], v[172:175], 0
	v_mfma_f32_16x16x32_bf16 v[40:43], v[152:155], v[176:179], v[40:43]
	v_mfma_f32_16x16x32_bf16 v[44:47], v[140:143], v[172:175], 0
	v_mfma_f32_16x16x32_bf16 v[44:47], v[144:147], v[176:179], v[44:47]
	v_mfma_f32_16x16x32_bf16 v[36:39], v[156:159], v[172:175], 0
	v_mfma_f32_16x16x32_bf16 v[36:39], v[160:163], v[176:179], v[36:39]
	v_mfma_f32_16x16x32_bf16 v[32:35], v[124:127], v[180:183], 0
	v_mfma_f32_16x16x32_bf16 v[32:35], v[128:131], v[184:187], v[32:35]
	v_mfma_f32_16x16x32_bf16 v[24:27], v[148:151], v[180:183], 0
	v_mfma_f32_16x16x32_bf16 v[24:27], v[152:155], v[184:187], v[24:27]
	v_mfma_f32_16x16x32_bf16 v[28:31], v[140:143], v[180:183], 0
	v_mfma_f32_16x16x32_bf16 v[28:31], v[144:147], v[184:187], v[28:31]
	v_mfma_f32_16x16x32_bf16 v[20:23], v[156:159], v[180:183], 0
	v_mfma_f32_16x16x32_bf16 v[20:23], v[160:163], v[184:187], v[20:23]
	v_mfma_f32_16x16x32_bf16 v[16:19], v[124:127], v[196:199], 0
	v_mfma_f32_16x16x32_bf16 v[16:19], v[128:131], v[200:203], v[16:19]
	v_mfma_f32_16x16x32_bf16 v[8:11], v[148:151], v[196:199], 0
	v_mfma_f32_16x16x32_bf16 v[8:11], v[152:155], v[200:203], v[8:11]
	v_mfma_f32_16x16x32_bf16 v[12:15], v[140:143], v[196:199], 0
	v_mfma_f32_16x16x32_bf16 v[12:15], v[144:147], v[200:203], v[12:15]
	v_mfma_f32_16x16x32_bf16 v[4:7], v[156:159], v[196:199], 0
	v_mfma_f32_16x16x32_bf16 v[4:7], v[160:163], v[200:203], v[4:7]
	s_setprio 0
	s_barrier
	s_sleep 1
	s_add_i32 s49, 0, 0x18000
	s_add_i32 s50, 0, 0x1c000
	s_add_u32 s16, s22, 0x160000
	s_addc_u32 s17, s23, 0
	s_mov_b32 m0, s30
	v_lshl_add_u64 v[212:213], s[16:17], 0, v[0:1]
	global_load_lds_dwordx4 v[212:213], off
	v_lshl_add_u64 v[212:213], s[16:17], 0, v[188:189]
	s_mov_b32 m0, s31
	s_nop 0
	global_load_lds_dwordx4 v[212:213], off
	v_add_u32_e32 v144, s49, v219
	v_add_u32_e32 v160, s50, v219
	ds_read_b128 v[124:127], v144
	ds_read_b128 v[128:131], v144 offset:1024
	ds_read_b128 v[140:143], v144 offset:2048
	ds_read_b128 v[144:147], v144 offset:3072
	ds_read_b128 v[148:151], v160
	ds_read_b128 v[152:155], v160 offset:1024
	ds_read_b128 v[156:159], v160 offset:2048
	ds_read_b128 v[160:163], v160 offset:3072
	ds_read_b128 v[164:167], v221 offset:32768
	ds_read_b128 v[168:171], v221 offset:33792
	ds_read_b128 v[172:175], v221 offset:34816
	ds_read_b128 v[176:179], v221 offset:35840
	ds_read_b128 v[180:183], v221 offset:36864
	ds_read_b128 v[184:187], v221 offset:37888
	ds_read_b128 v[196:199], v221 offset:38912
	ds_read_b128 v[200:203], v221 offset:39936
	s_waitcnt vmcnt(8)
	s_waitcnt lgkmcnt(0)
	s_barrier
	s_setprio 1
	s_waitcnt lgkmcnt(0)
	v_mfma_f32_16x16x32_bf16 v[136:139], v[124:127], v[164:167], v[136:139]
	v_mfma_f32_16x16x32_bf16 v[136:139], v[128:131], v[168:171], v[136:139]
	v_mfma_f32_16x16x32_bf16 v[120:123], v[148:151], v[164:167], v[120:123]
	v_mfma_f32_16x16x32_bf16 v[120:123], v[152:155], v[168:171], v[120:123]
	v_mfma_f32_16x16x32_bf16 v[132:135], v[140:143], v[164:167], v[132:135]
	v_mfma_f32_16x16x32_bf16 v[132:135], v[144:147], v[168:171], v[132:135]
	v_mfma_f32_16x16x32_bf16 v[116:119], v[156:159], v[164:167], v[116:119]
	v_mfma_f32_16x16x32_bf16 v[116:119], v[160:163], v[168:171], v[116:119]
	v_mfma_f32_16x16x32_bf16 v[112:115], v[124:127], v[172:175], v[112:115]
	v_mfma_f32_16x16x32_bf16 v[112:115], v[128:131], v[176:179], v[112:115]
	v_mfma_f32_16x16x32_bf16 v[104:107], v[148:151], v[172:175], v[104:107]
	v_mfma_f32_16x16x32_bf16 v[104:107], v[152:155], v[176:179], v[104:107]
	v_mfma_f32_16x16x32_bf16 v[108:111], v[140:143], v[172:175], v[108:111]
	v_mfma_f32_16x16x32_bf16 v[108:111], v[144:147], v[176:179], v[108:111]
	v_mfma_f32_16x16x32_bf16 v[100:103], v[156:159], v[172:175], v[100:103]
	v_mfma_f32_16x16x32_bf16 v[100:103], v[160:163], v[176:179], v[100:103]
	v_mfma_f32_16x16x32_bf16 v[96:99], v[124:127], v[180:183], v[96:99]
	v_mfma_f32_16x16x32_bf16 v[96:99], v[128:131], v[184:187], v[96:99]
	v_mfma_f32_16x16x32_bf16 v[88:91], v[148:151], v[180:183], v[88:91]
	v_mfma_f32_16x16x32_bf16 v[88:91], v[152:155], v[184:187], v[88:91]
	v_mfma_f32_16x16x32_bf16 v[92:95], v[140:143], v[180:183], v[92:95]
	v_mfma_f32_16x16x32_bf16 v[92:95], v[144:147], v[184:187], v[92:95]
	v_mfma_f32_16x16x32_bf16 v[84:87], v[156:159], v[180:183], v[84:87]
	v_mfma_f32_16x16x32_bf16 v[84:87], v[160:163], v[184:187], v[84:87]
	v_mfma_f32_16x16x32_bf16 v[80:83], v[124:127], v[196:199], v[80:83]
	v_mfma_f32_16x16x32_bf16 v[80:83], v[128:131], v[200:203], v[80:83]
	v_mfma_f32_16x16x32_bf16 v[72:75], v[148:151], v[196:199], v[72:75]
	v_mfma_f32_16x16x32_bf16 v[72:75], v[152:155], v[200:203], v[72:75]
	v_mfma_f32_16x16x32_bf16 v[76:79], v[140:143], v[196:199], v[76:79]
	v_mfma_f32_16x16x32_bf16 v[76:79], v[144:147], v[200:203], v[76:79]
	v_mfma_f32_16x16x32_bf16 v[68:71], v[156:159], v[196:199], v[68:71]
	v_mfma_f32_16x16x32_bf16 v[68:71], v[160:163], v[200:203], v[68:71]
	s_setprio 0
	s_barrier
	s_sleep 2
	s_add_i32 s16, s49, s2
	v_lshl_add_u64 v[204:205], v[204:205], 0, s[66:67]
	s_mov_b32 m0, s16
	ds_read_b128 v[164:167], v221 offset:49152
	ds_read_b128 v[168:171], v221 offset:50176
	ds_read_b128 v[172:175], v221 offset:51200
	ds_read_b128 v[176:179], v221 offset:52224
	ds_read_b128 v[180:183], v221 offset:53248
	ds_read_b128 v[184:187], v221 offset:54272
	ds_read_b128 v[196:199], v221 offset:55296
	ds_read_b128 v[200:203], v221 offset:56320
	global_load_lds_dwordx4 v[204:205], off
	s_add_i32 m0, s16, 0x2000
	s_add_u32 s16, s20, 0x160080
	v_lshl_add_u64 v[204:205], v[206:207], 0, s[66:67]
	s_addc_u32 s17, s21, 0
	s_add_i32 s20, s50, s2
	global_load_lds_dwordx4 v[204:205], off
	v_lshl_add_u64 v[204:205], s[16:17], 0, v[2:3]
	s_mov_b32 m0, s20
	s_nop 0
	global_load_lds_dwordx4 v[204:205], off
	v_lshl_add_u64 v[204:205], s[16:17], 0, v[190:191]
	s_add_i32 m0, s20, 0x2000
	s_nop 0
	global_load_lds_dwordx4 v[204:205], off
	v_lshl_add_u64 v[204:205], v[208:209], 0, s[66:67]
	s_mov_b32 m0, s34
	s_nop 0
	global_load_lds_dwordx4 v[204:205], off
	v_lshl_add_u64 v[204:205], v[210:211], 0, s[66:67]
	s_mov_b32 m0, s35
	s_nop 0
	global_load_lds_dwordx4 v[204:205], off
	s_waitcnt vmcnt(8)
	s_waitcnt lgkmcnt(0)
	s_barrier
	s_setprio 1
	s_waitcnt lgkmcnt(0)
	v_mfma_f32_16x16x32_bf16 v[64:67], v[124:127], v[164:167], v[64:67]
	v_mfma_f32_16x16x32_bf16 v[64:67], v[128:131], v[168:171], v[64:67]
	v_mfma_f32_16x16x32_bf16 v[56:59], v[148:151], v[164:167], v[56:59]
	v_mfma_f32_16x16x32_bf16 v[56:59], v[152:155], v[168:171], v[56:59]
	v_mfma_f32_16x16x32_bf16 v[60:63], v[140:143], v[164:167], v[60:63]
	v_mfma_f32_16x16x32_bf16 v[60:63], v[144:147], v[168:171], v[60:63]
	v_mfma_f32_16x16x32_bf16 v[52:55], v[156:159], v[164:167], v[52:55]
	v_mfma_f32_16x16x32_bf16 v[52:55], v[160:163], v[168:171], v[52:55]
	v_mfma_f32_16x16x32_bf16 v[48:51], v[124:127], v[172:175], v[48:51]
	v_mfma_f32_16x16x32_bf16 v[48:51], v[128:131], v[176:179], v[48:51]
	v_mfma_f32_16x16x32_bf16 v[40:43], v[148:151], v[172:175], v[40:43]
	v_mfma_f32_16x16x32_bf16 v[40:43], v[152:155], v[176:179], v[40:43]
	v_mfma_f32_16x16x32_bf16 v[44:47], v[140:143], v[172:175], v[44:47]
	v_mfma_f32_16x16x32_bf16 v[44:47], v[144:147], v[176:179], v[44:47]
	v_mfma_f32_16x16x32_bf16 v[36:39], v[156:159], v[172:175], v[36:39]
	v_mfma_f32_16x16x32_bf16 v[36:39], v[160:163], v[176:179], v[36:39]
	v_mfma_f32_16x16x32_bf16 v[32:35], v[124:127], v[180:183], v[32:35]
	v_mfma_f32_16x16x32_bf16 v[32:35], v[128:131], v[184:187], v[32:35]
	v_mfma_f32_16x16x32_bf16 v[24:27], v[148:151], v[180:183], v[24:27]
	v_mfma_f32_16x16x32_bf16 v[24:27], v[152:155], v[184:187], v[24:27]
	v_mfma_f32_16x16x32_bf16 v[28:31], v[140:143], v[180:183], v[28:31]
	v_mfma_f32_16x16x32_bf16 v[28:31], v[144:147], v[184:187], v[28:31]
	v_mfma_f32_16x16x32_bf16 v[20:23], v[156:159], v[180:183], v[20:23]
	v_mfma_f32_16x16x32_bf16 v[20:23], v[160:163], v[184:187], v[20:23]
	v_mfma_f32_16x16x32_bf16 v[16:19], v[124:127], v[196:199], v[16:19]
	v_mfma_f32_16x16x32_bf16 v[16:19], v[128:131], v[200:203], v[16:19]
	v_mfma_f32_16x16x32_bf16 v[8:11], v[148:151], v[196:199], v[8:11]
	v_mfma_f32_16x16x32_bf16 v[8:11], v[152:155], v[200:203], v[8:11]
	v_mfma_f32_16x16x32_bf16 v[12:15], v[140:143], v[196:199], v[12:15]
	v_mfma_f32_16x16x32_bf16 v[12:15], v[144:147], v[200:203], v[12:15]
	v_mfma_f32_16x16x32_bf16 v[4:7], v[156:159], v[196:199], v[4:7]
	v_mfma_f32_16x16x32_bf16 v[4:7], v[160:163], v[200:203], v[4:7]
	s_setprio 0
	s_barrier
	s_add_i32 s48, s48, 2
	s_add_u32 s40, s40, 0x100
	s_addc_u32 s41, s41, 0
	s_cmpk_gt_u32 s48, 0x55
	s_mov_b64 s[16:17], s[18:19]
.LBB0_301:
	s_sleep 1
	s_add_u32 s18, s16, 0x100
	s_addc_u32 s19, s17, 0
	s_add_i32 s49, 0, 0x10000
	s_cmpk_eq_i32 s48, 0x54
	s_cselect_b32 s23, s13, s19
	s_cselect_b32 s22, s12, s18
	s_cselect_b32 s21, s15, s41
	s_cselect_b32 s20, s14, s40
	s_add_i32 s50, 0, 0x14000
	v_lshl_add_u64 v[204:205], s[16:17], 0, v[192:193]
	s_add_i32 m0, s28, 0xc000
	s_nop 0
	global_load_lds_dwordx4 v[204:205], off
	v_lshl_add_u64 v[204:205], s[16:17], 0, v[194:195]
	s_add_i32 m0, s28, 0xe000
	s_nop 0
	global_load_lds_dwordx4 v[204:205], off
	v_add_u32_e32 v144, s49, v219
	v_add_u32_e32 v160, s50, v219
	ds_read_b128 v[124:127], v144
	ds_read_b128 v[128:131], v144 offset:1024
	ds_read_b128 v[140:143], v144 offset:2048
	ds_read_b128 v[144:147], v144 offset:3072
	ds_read_b128 v[148:151], v160
	ds_read_b128 v[152:155], v160 offset:1024
	ds_read_b128 v[156:159], v160 offset:2048
	ds_read_b128 v[160:163], v160 offset:3072
	ds_read_b128 v[164:167], v221
	ds_read_b128 v[168:171], v221 offset:1024
	ds_read_b128 v[172:175], v221 offset:2048
	ds_read_b128 v[176:179], v221 offset:3072
	ds_read_b128 v[180:183], v221 offset:4096
	ds_read_b128 v[184:187], v221 offset:5120
	ds_read_b128 v[196:199], v221 offset:6144
	ds_read_b128 v[200:203], v221 offset:7168
	s_waitcnt vmcnt(8)
	s_waitcnt lgkmcnt(0)
	s_barrier
	s_setprio 1
	s_waitcnt lgkmcnt(0)
	v_mfma_f32_16x16x32_bf16 v[136:139], v[124:127], v[164:167], v[136:139]
	v_mfma_f32_16x16x32_bf16 v[136:139], v[128:131], v[168:171], v[136:139]
	v_mfma_f32_16x16x32_bf16 v[120:123], v[148:151], v[164:167], v[120:123]
	v_mfma_f32_16x16x32_bf16 v[120:123], v[152:155], v[168:171], v[120:123]
	v_mfma_f32_16x16x32_bf16 v[132:135], v[140:143], v[164:167], v[132:135]
	v_mfma_f32_16x16x32_bf16 v[132:135], v[144:147], v[168:171], v[132:135]
	v_mfma_f32_16x16x32_bf16 v[116:119], v[156:159], v[164:167], v[116:119]
	v_mfma_f32_16x16x32_bf16 v[116:119], v[160:163], v[168:171], v[116:119]
	v_mfma_f32_16x16x32_bf16 v[112:115], v[124:127], v[172:175], v[112:115]
	v_mfma_f32_16x16x32_bf16 v[112:115], v[128:131], v[176:179], v[112:115]
	v_mfma_f32_16x16x32_bf16 v[104:107], v[148:151], v[172:175], v[104:107]
	v_mfma_f32_16x16x32_bf16 v[104:107], v[152:155], v[176:179], v[104:107]
	v_mfma_f32_16x16x32_bf16 v[108:111], v[140:143], v[172:175], v[108:111]
	v_mfma_f32_16x16x32_bf16 v[108:111], v[144:147], v[176:179], v[108:111]
	v_mfma_f32_16x16x32_bf16 v[100:103], v[156:159], v[172:175], v[100:103]
	v_mfma_f32_16x16x32_bf16 v[100:103], v[160:163], v[176:179], v[100:103]
	v_mfma_f32_16x16x32_bf16 v[96:99], v[124:127], v[180:183], v[96:99]
	v_mfma_f32_16x16x32_bf16 v[96:99], v[128:131], v[184:187], v[96:99]
	v_mfma_f32_16x16x32_bf16 v[88:91], v[148:151], v[180:183], v[88:91]
	v_mfma_f32_16x16x32_bf16 v[88:91], v[152:155], v[184:187], v[88:91]
	v_mfma_f32_16x16x32_bf16 v[92:95], v[140:143], v[180:183], v[92:95]
	v_mfma_f32_16x16x32_bf16 v[92:95], v[144:147], v[184:187], v[92:95]
	v_mfma_f32_16x16x32_bf16 v[84:87], v[156:159], v[180:183], v[84:87]
	v_mfma_f32_16x16x32_bf16 v[84:87], v[160:163], v[184:187], v[84:87]
	v_mfma_f32_16x16x32_bf16 v[80:83], v[124:127], v[196:199], v[80:83]
	v_mfma_f32_16x16x32_bf16 v[80:83], v[128:131], v[200:203], v[80:83]
	v_mfma_f32_16x16x32_bf16 v[72:75], v[148:151], v[196:199], v[72:75]
	v_mfma_f32_16x16x32_bf16 v[72:75], v[152:155], v[200:203], v[72:75]
	v_mfma_f32_16x16x32_bf16 v[76:79], v[140:143], v[196:199], v[76:79]
	v_mfma_f32_16x16x32_bf16 v[76:79], v[144:147], v[200:203], v[76:79]
	v_mfma_f32_16x16x32_bf16 v[68:71], v[156:159], v[196:199], v[68:71]
	v_mfma_f32_16x16x32_bf16 v[68:71], v[160:163], v[200:203], v[68:71]
	s_setprio 0
	s_barrier
	s_sleep 2
	s_add_i32 s16, s49, s2
	v_lshl_add_u64 v[204:205], s[20:21], 0, v[2:3]
	s_mov_b32 m0, s16
	ds_read_b128 v[164:167], v221 offset:16384
	ds_read_b128 v[168:171], v221 offset:17408
	ds_read_b128 v[172:175], v221 offset:18432
	ds_read_b128 v[176:179], v221 offset:19456
	ds_read_b128 v[180:183], v221 offset:20480
	ds_read_b128 v[184:187], v221 offset:21504
	ds_read_b128 v[196:199], v221 offset:22528
	ds_read_b128 v[200:203], v221 offset:23552
	global_load_lds_dwordx4 v[204:205], off
	s_add_i32 m0, s16, 0x2000
	s_add_u32 s16, s20, 0x160000
	v_lshl_add_u64 v[206:207], s[20:21], 0, v[190:191]
	s_addc_u32 s17, s21, 0
	s_add_i32 s49, s50, s2
	global_load_lds_dwordx4 v[206:207], off
	v_lshl_add_u64 v[208:209], s[16:17], 0, v[2:3]
	s_mov_b32 m0, s49
	v_lshl_add_u64 v[210:211], s[22:23], 0, v[188:189]
	global_load_lds_dwordx4 v[208:209], off
	v_lshl_add_u64 v[208:209], s[16:17], 0, v[190:191]
	s_add_i32 m0, s49, 0x2000
	s_nop 0
	global_load_lds_dwordx4 v[208:209], off
	v_lshl_add_u64 v[208:209], s[22:23], 0, v[0:1]
	s_mov_b32 m0, s28
	s_nop 0
	global_load_lds_dwordx4 v[208:209], off
	s_mov_b32 m0, s29
	s_nop 0
	global_load_lds_dwordx4 v[210:211], off
	s_waitcnt vmcnt(8)
	s_waitcnt lgkmcnt(0)
	s_barrier
	s_setprio 1
	s_waitcnt lgkmcnt(0)
	v_mfma_f32_16x16x32_bf16 v[64:67], v[124:127], v[164:167], v[64:67]
	v_mfma_f32_16x16x32_bf16 v[64:67], v[128:131], v[168:171], v[64:67]
	v_mfma_f32_16x16x32_bf16 v[56:59], v[148:151], v[164:167], v[56:59]
	v_mfma_f32_16x16x32_bf16 v[56:59], v[152:155], v[168:171], v[56:59]
	v_mfma_f32_16x16x32_bf16 v[60:63], v[140:143], v[164:167], v[60:63]
	v_mfma_f32_16x16x32_bf16 v[60:63], v[144:147], v[168:171], v[60:63]
	v_mfma_f32_16x16x32_bf16 v[52:55], v[156:159], v[164:167], v[52:55]
	v_mfma_f32_16x16x32_bf16 v[52:55], v[160:163], v[168:171], v[52:55]
	v_mfma_f32_16x16x32_bf16 v[48:51], v[124:127], v[172:175], v[48:51]
	v_mfma_f32_16x16x32_bf16 v[48:51], v[128:131], v[176:179], v[48:51]
	v_mfma_f32_16x16x32_bf16 v[40:43], v[148:151], v[172:175], v[40:43]
	v_mfma_f32_16x16x32_bf16 v[40:43], v[152:155], v[176:179], v[40:43]
	v_mfma_f32_16x16x32_bf16 v[44:47], v[140:143], v[172:175], v[44:47]
	v_mfma_f32_16x16x32_bf16 v[44:47], v[144:147], v[176:179], v[44:47]
	v_mfma_f32_16x16x32_bf16 v[36:39], v[156:159], v[172:175], v[36:39]
	v_mfma_f32_16x16x32_bf16 v[36:39], v[160:163], v[176:179], v[36:39]
	v_mfma_f32_16x16x32_bf16 v[32:35], v[124:127], v[180:183], v[32:35]
	v_mfma_f32_16x16x32_bf16 v[32:35], v[128:131], v[184:187], v[32:35]
	v_mfma_f32_16x16x32_bf16 v[24:27], v[148:151], v[180:183], v[24:27]
	v_mfma_f32_16x16x32_bf16 v[24:27], v[152:155], v[184:187], v[24:27]
	v_mfma_f32_16x16x32_bf16 v[28:31], v[140:143], v[180:183], v[28:31]
	v_mfma_f32_16x16x32_bf16 v[28:31], v[144:147], v[184:187], v[28:31]
	v_mfma_f32_16x16x32_bf16 v[20:23], v[156:159], v[180:183], v[20:23]
	v_mfma_f32_16x16x32_bf16 v[20:23], v[160:163], v[184:187], v[20:23]
	v_mfma_f32_16x16x32_bf16 v[16:19], v[124:127], v[196:199], v[16:19]
	v_mfma_f32_16x16x32_bf16 v[16:19], v[128:131], v[200:203], v[16:19]
	v_mfma_f32_16x16x32_bf16 v[8:11], v[148:151], v[196:199], v[8:11]
	v_mfma_f32_16x16x32_bf16 v[8:11], v[152:155], v[200:203], v[8:11]
	v_mfma_f32_16x16x32_bf16 v[12:15], v[140:143], v[196:199], v[12:15]
	v_mfma_f32_16x16x32_bf16 v[12:15], v[144:147], v[200:203], v[12:15]
	v_mfma_f32_16x16x32_bf16 v[4:7], v[156:159], v[196:199], v[4:7]
	v_mfma_f32_16x16x32_bf16 v[4:7], v[160:163], v[200:203], v[4:7]
	s_setprio 0
	s_barrier
	s_sleep 1
	s_add_i32 s49, 0, 0x18000
	s_add_i32 s50, 0, 0x1c000
	s_add_u32 s16, s22, 0x160000
	s_addc_u32 s17, s23, 0
	s_mov_b32 m0, s30
	v_lshl_add_u64 v[212:213], s[16:17], 0, v[0:1]
	global_load_lds_dwordx4 v[212:213], off
	v_lshl_add_u64 v[212:213], s[16:17], 0, v[188:189]
	s_mov_b32 m0, s31
	s_nop 0
	global_load_lds_dwordx4 v[212:213], off
	v_add_u32_e32 v144, s49, v219
	v_add_u32_e32 v160, s50, v219
	ds_read_b128 v[124:127], v144
	ds_read_b128 v[128:131], v144 offset:1024
	ds_read_b128 v[140:143], v144 offset:2048
	ds_read_b128 v[144:147], v144 offset:3072
	ds_read_b128 v[148:151], v160
	ds_read_b128 v[152:155], v160 offset:1024
	ds_read_b128 v[156:159], v160 offset:2048
	ds_read_b128 v[160:163], v160 offset:3072
	ds_read_b128 v[164:167], v221 offset:32768
	ds_read_b128 v[168:171], v221 offset:33792
	ds_read_b128 v[172:175], v221 offset:34816
	ds_read_b128 v[176:179], v221 offset:35840
	ds_read_b128 v[180:183], v221 offset:36864
	ds_read_b128 v[184:187], v221 offset:37888
	ds_read_b128 v[196:199], v221 offset:38912
	ds_read_b128 v[200:203], v221 offset:39936
	s_waitcnt vmcnt(8)
	s_waitcnt lgkmcnt(0)
	s_barrier
	s_setprio 1
	s_waitcnt lgkmcnt(0)
	v_mfma_f32_16x16x32_bf16 v[136:139], v[124:127], v[164:167], v[136:139]
	v_mfma_f32_16x16x32_bf16 v[136:139], v[128:131], v[168:171], v[136:139]
	v_mfma_f32_16x16x32_bf16 v[120:123], v[148:151], v[164:167], v[120:123]
	v_mfma_f32_16x16x32_bf16 v[120:123], v[152:155], v[168:171], v[120:123]
	v_mfma_f32_16x16x32_bf16 v[132:135], v[140:143], v[164:167], v[132:135]
	v_mfma_f32_16x16x32_bf16 v[132:135], v[144:147], v[168:171], v[132:135]
	v_mfma_f32_16x16x32_bf16 v[116:119], v[156:159], v[164:167], v[116:119]
	v_mfma_f32_16x16x32_bf16 v[116:119], v[160:163], v[168:171], v[116:119]
	v_mfma_f32_16x16x32_bf16 v[112:115], v[124:127], v[172:175], v[112:115]
	v_mfma_f32_16x16x32_bf16 v[112:115], v[128:131], v[176:179], v[112:115]
	v_mfma_f32_16x16x32_bf16 v[104:107], v[148:151], v[172:175], v[104:107]
	v_mfma_f32_16x16x32_bf16 v[104:107], v[152:155], v[176:179], v[104:107]
	v_mfma_f32_16x16x32_bf16 v[108:111], v[140:143], v[172:175], v[108:111]
	v_mfma_f32_16x16x32_bf16 v[108:111], v[144:147], v[176:179], v[108:111]
	v_mfma_f32_16x16x32_bf16 v[100:103], v[156:159], v[172:175], v[100:103]
	v_mfma_f32_16x16x32_bf16 v[100:103], v[160:163], v[176:179], v[100:103]
	v_mfma_f32_16x16x32_bf16 v[96:99], v[124:127], v[180:183], v[96:99]
	v_mfma_f32_16x16x32_bf16 v[96:99], v[128:131], v[184:187], v[96:99]
	v_mfma_f32_16x16x32_bf16 v[88:91], v[148:151], v[180:183], v[88:91]
	v_mfma_f32_16x16x32_bf16 v[88:91], v[152:155], v[184:187], v[88:91]
	v_mfma_f32_16x16x32_bf16 v[92:95], v[140:143], v[180:183], v[92:95]
	v_mfma_f32_16x16x32_bf16 v[92:95], v[144:147], v[184:187], v[92:95]
	v_mfma_f32_16x16x32_bf16 v[84:87], v[156:159], v[180:183], v[84:87]
	v_mfma_f32_16x16x32_bf16 v[84:87], v[160:163], v[184:187], v[84:87]
	v_mfma_f32_16x16x32_bf16 v[80:83], v[124:127], v[196:199], v[80:83]
	v_mfma_f32_16x16x32_bf16 v[80:83], v[128:131], v[200:203], v[80:83]
	v_mfma_f32_16x16x32_bf16 v[72:75], v[148:151], v[196:199], v[72:75]
	v_mfma_f32_16x16x32_bf16 v[72:75], v[152:155], v[200:203], v[72:75]
	v_mfma_f32_16x16x32_bf16 v[76:79], v[140:143], v[196:199], v[76:79]
	v_mfma_f32_16x16x32_bf16 v[76:79], v[144:147], v[200:203], v[76:79]
	v_mfma_f32_16x16x32_bf16 v[68:71], v[156:159], v[196:199], v[68:71]
	v_mfma_f32_16x16x32_bf16 v[68:71], v[160:163], v[200:203], v[68:71]
	s_setprio 0
	s_barrier
	s_sleep 2
	s_add_i32 s16, s49, s2
	v_lshl_add_u64 v[204:205], v[204:205], 0, s[66:67]
	s_mov_b32 m0, s16
	ds_read_b128 v[164:167], v221 offset:49152
	ds_read_b128 v[168:171], v221 offset:50176
	ds_read_b128 v[172:175], v221 offset:51200
	ds_read_b128 v[176:179], v221 offset:52224
	ds_read_b128 v[180:183], v221 offset:53248
	ds_read_b128 v[184:187], v221 offset:54272
	ds_read_b128 v[196:199], v221 offset:55296
	ds_read_b128 v[200:203], v221 offset:56320
	global_load_lds_dwordx4 v[204:205], off
	s_add_i32 m0, s16, 0x2000
	s_add_u32 s16, s20, 0x160080
	v_lshl_add_u64 v[204:205], v[206:207], 0, s[66:67]
	s_addc_u32 s17, s21, 0
	s_add_i32 s20, s50, s2
	global_load_lds_dwordx4 v[204:205], off
	v_lshl_add_u64 v[204:205], s[16:17], 0, v[2:3]
	s_mov_b32 m0, s20
	s_nop 0
	global_load_lds_dwordx4 v[204:205], off
	v_lshl_add_u64 v[204:205], s[16:17], 0, v[190:191]
	s_add_i32 m0, s20, 0x2000
	s_nop 0
	global_load_lds_dwordx4 v[204:205], off
	v_lshl_add_u64 v[204:205], v[208:209], 0, s[66:67]
	s_mov_b32 m0, s34
	s_nop 0
	global_load_lds_dwordx4 v[204:205], off
	v_lshl_add_u64 v[204:205], v[210:211], 0, s[66:67]
	s_mov_b32 m0, s35
	s_nop 0
	global_load_lds_dwordx4 v[204:205], off
	s_waitcnt vmcnt(8)
	s_waitcnt lgkmcnt(0)
	s_barrier
	s_setprio 1
	s_waitcnt lgkmcnt(0)
	v_mfma_f32_16x16x32_bf16 v[64:67], v[124:127], v[164:167], v[64:67]
	v_mfma_f32_16x16x32_bf16 v[64:67], v[128:131], v[168:171], v[64:67]
	v_mfma_f32_16x16x32_bf16 v[56:59], v[148:151], v[164:167], v[56:59]
	v_mfma_f32_16x16x32_bf16 v[56:59], v[152:155], v[168:171], v[56:59]
	v_mfma_f32_16x16x32_bf16 v[60:63], v[140:143], v[164:167], v[60:63]
	v_mfma_f32_16x16x32_bf16 v[60:63], v[144:147], v[168:171], v[60:63]
	v_mfma_f32_16x16x32_bf16 v[52:55], v[156:159], v[164:167], v[52:55]
	v_mfma_f32_16x16x32_bf16 v[52:55], v[160:163], v[168:171], v[52:55]
	v_mfma_f32_16x16x32_bf16 v[48:51], v[124:127], v[172:175], v[48:51]
	v_mfma_f32_16x16x32_bf16 v[48:51], v[128:131], v[176:179], v[48:51]
	v_mfma_f32_16x16x32_bf16 v[40:43], v[148:151], v[172:175], v[40:43]
	v_mfma_f32_16x16x32_bf16 v[40:43], v[152:155], v[176:179], v[40:43]
	v_mfma_f32_16x16x32_bf16 v[44:47], v[140:143], v[172:175], v[44:47]
	v_mfma_f32_16x16x32_bf16 v[44:47], v[144:147], v[176:179], v[44:47]
	v_mfma_f32_16x16x32_bf16 v[36:39], v[156:159], v[172:175], v[36:39]
	v_mfma_f32_16x16x32_bf16 v[36:39], v[160:163], v[176:179], v[36:39]
	v_mfma_f32_16x16x32_bf16 v[32:35], v[124:127], v[180:183], v[32:35]
	v_mfma_f32_16x16x32_bf16 v[32:35], v[128:131], v[184:187], v[32:35]
	v_mfma_f32_16x16x32_bf16 v[24:27], v[148:151], v[180:183], v[24:27]
	v_mfma_f32_16x16x32_bf16 v[24:27], v[152:155], v[184:187], v[24:27]
	v_mfma_f32_16x16x32_bf16 v[28:31], v[140:143], v[180:183], v[28:31]
	v_mfma_f32_16x16x32_bf16 v[28:31], v[144:147], v[184:187], v[28:31]
	v_mfma_f32_16x16x32_bf16 v[20:23], v[156:159], v[180:183], v[20:23]
	v_mfma_f32_16x16x32_bf16 v[20:23], v[160:163], v[184:187], v[20:23]
	v_mfma_f32_16x16x32_bf16 v[16:19], v[124:127], v[196:199], v[16:19]
	v_mfma_f32_16x16x32_bf16 v[16:19], v[128:131], v[200:203], v[16:19]
	v_mfma_f32_16x16x32_bf16 v[8:11], v[148:151], v[196:199], v[8:11]
	v_mfma_f32_16x16x32_bf16 v[8:11], v[152:155], v[200:203], v[8:11]
	v_mfma_f32_16x16x32_bf16 v[12:15], v[140:143], v[196:199], v[12:15]
	v_mfma_f32_16x16x32_bf16 v[12:15], v[144:147], v[200:203], v[12:15]
	v_mfma_f32_16x16x32_bf16 v[4:7], v[156:159], v[196:199], v[4:7]
	v_mfma_f32_16x16x32_bf16 v[4:7], v[160:163], v[200:203], v[4:7]
	s_setprio 0
	s_barrier
	s_add_i32 s48, s48, 2
	s_add_u32 s40, s40, 0x100
	s_addc_u32 s41, s41, 0
	s_cmpk_gt_u32 s48, 0x55
	s_mov_b64 s[16:17], s[18:19]
	s_cbranch_scc0 .LBB0_301
	s_and_b64 vcc, exec, s[10:11]
	s_cbranch_vccz .LBB0_304
	s_barrier

.LBB0_346:
	s_add_u32 s38, s16, 0x100
	s_addc_u32 s39, s17, 0
	s_mov_b32 s43, -2
	s_sleep 1
	s_add_u32 s16, s14, 0x100
	s_addc_u32 s17, s15, 0
	s_add_i32 s44, 0, 0x10000
	s_cmpk_eq_i32 s43, 0x54
	s_cselect_b32 s21, s11, s17
	s_cselect_b32 s20, s10, s16
	s_cselect_b32 s19, s13, s39
	s_cselect_b32 s18, s12, s38
	s_add_i32 s45, 0, 0x14000
	v_lshl_add_u64 v[204:205], s[14:15], 0, v[200:201]
	s_add_i32 m0, s23, 0xc000
	s_nop 0
	global_load_lds_dwordx4 v[204:205], off
	v_lshl_add_u64 v[204:205], s[14:15], 0, v[202:203]
	s_add_i32 m0, s23, 0xe000
	s_nop 0
	global_load_lds_dwordx4 v[204:205], off
	v_add_u32_e32 v144, s44, v236
	v_add_u32_e32 v160, s45, v236
	ds_read_b128 v[132:135], v144
	ds_read_b128 v[136:139], v144 offset:1024
	ds_read_b128 v[140:143], v144 offset:2048
	ds_read_b128 v[144:147], v144 offset:3072
	ds_read_b128 v[148:151], v160
	ds_read_b128 v[152:155], v160 offset:1024
	ds_read_b128 v[156:159], v160 offset:2048
	ds_read_b128 v[160:163], v160 offset:3072
	ds_read_b128 v[164:167], v238
	ds_read_b128 v[168:171], v238 offset:1024
	ds_read_b128 v[172:175], v238 offset:2048
	ds_read_b128 v[176:179], v238 offset:3072
	ds_read_b128 v[180:183], v238 offset:4096
	ds_read_b128 v[184:187], v238 offset:5120
	ds_read_b128 v[188:191], v238 offset:6144
	ds_read_b128 v[192:195], v238 offset:7168
	s_waitcnt vmcnt(8)
	s_waitcnt lgkmcnt(0)
	s_barrier
	s_setprio 1
	s_waitcnt lgkmcnt(0)
	v_mfma_f32_16x16x32_bf16 v[128:131], v[132:135], v[164:167], 0
	v_mfma_f32_16x16x32_bf16 v[128:131], v[136:139], v[168:171], v[128:131]
	v_mfma_f32_16x16x32_bf16 v[120:123], v[148:151], v[164:167], 0
	v_mfma_f32_16x16x32_bf16 v[120:123], v[152:155], v[168:171], v[120:123]
	v_mfma_f32_16x16x32_bf16 v[124:127], v[140:143], v[164:167], 0
	v_mfma_f32_16x16x32_bf16 v[124:127], v[144:147], v[168:171], v[124:127]
	v_mfma_f32_16x16x32_bf16 v[112:115], v[156:159], v[164:167], 0
	v_mfma_f32_16x16x32_bf16 v[112:115], v[160:163], v[168:171], v[112:115]
	v_mfma_f32_16x16x32_bf16 v[116:119], v[132:135], v[172:175], 0
	v_mfma_f32_16x16x32_bf16 v[116:119], v[136:139], v[176:179], v[116:119]
	v_mfma_f32_16x16x32_bf16 v[104:107], v[148:151], v[172:175], 0
	v_mfma_f32_16x16x32_bf16 v[104:107], v[152:155], v[176:179], v[104:107]
	v_mfma_f32_16x16x32_bf16 v[108:111], v[140:143], v[172:175], 0
	v_mfma_f32_16x16x32_bf16 v[108:111], v[144:147], v[176:179], v[108:111]
	v_mfma_f32_16x16x32_bf16 v[96:99], v[156:159], v[172:175], 0
	v_mfma_f32_16x16x32_bf16 v[96:99], v[160:163], v[176:179], v[96:99]
	v_mfma_f32_16x16x32_bf16 v[100:103], v[132:135], v[180:183], 0
	v_mfma_f32_16x16x32_bf16 v[100:103], v[136:139], v[184:187], v[100:103]
	v_mfma_f32_16x16x32_bf16 v[88:91], v[148:151], v[180:183], 0
	v_mfma_f32_16x16x32_bf16 v[88:91], v[152:155], v[184:187], v[88:91]
	v_mfma_f32_16x16x32_bf16 v[92:95], v[140:143], v[180:183], 0
	v_mfma_f32_16x16x32_bf16 v[92:95], v[144:147], v[184:187], v[92:95]
	v_mfma_f32_16x16x32_bf16 v[80:83], v[156:159], v[180:183], 0
	v_mfma_f32_16x16x32_bf16 v[80:83], v[160:163], v[184:187], v[80:83]
	v_mfma_f32_16x16x32_bf16 v[84:87], v[132:135], v[188:191], 0
	v_mfma_f32_16x16x32_bf16 v[84:87], v[136:139], v[192:195], v[84:87]
	v_mfma_f32_16x16x32_bf16 v[72:75], v[148:151], v[188:191], 0
	v_mfma_f32_16x16x32_bf16 v[72:75], v[152:155], v[192:195], v[72:75]
	v_mfma_f32_16x16x32_bf16 v[76:79], v[140:143], v[188:191], 0
	v_mfma_f32_16x16x32_bf16 v[76:79], v[144:147], v[192:195], v[76:79]
	v_mfma_f32_16x16x32_bf16 v[68:71], v[156:159], v[188:191], 0
	v_mfma_f32_16x16x32_bf16 v[68:71], v[160:163], v[192:195], v[68:71]
	s_setprio 0
	s_barrier
	s_sleep 2
	s_add_i32 s14, s44, s22
	v_lshl_add_u64 v[204:205], s[18:19], 0, v[2:3]
	s_mov_b32 m0, s14
	ds_read_b128 v[164:167], v238 offset:16384
	ds_read_b128 v[168:171], v238 offset:17408
	ds_read_b128 v[172:175], v238 offset:18432
	ds_read_b128 v[176:179], v238 offset:19456
	ds_read_b128 v[180:183], v238 offset:20480
	ds_read_b128 v[184:187], v238 offset:21504
	ds_read_b128 v[188:191], v238 offset:22528
	ds_read_b128 v[192:195], v238 offset:23552
	global_load_lds_dwordx4 v[204:205], off
	s_add_i32 m0, s14, 0x2000
	s_add_u32 s14, s18, 0x160000
	v_lshl_add_u64 v[206:207], s[18:19], 0, v[198:199]
	s_addc_u32 s15, s19, 0
	s_add_i32 s44, s45, s22
	global_load_lds_dwordx4 v[206:207], off
	v_lshl_add_u64 v[208:209], s[14:15], 0, v[2:3]
	s_mov_b32 m0, s44
	v_lshl_add_u64 v[210:211], s[20:21], 0, v[196:197]
	global_load_lds_dwordx4 v[208:209], off
	v_lshl_add_u64 v[208:209], s[14:15], 0, v[198:199]
	s_add_i32 m0, s44, 0x2000
	s_nop 0
	global_load_lds_dwordx4 v[208:209], off
	v_lshl_add_u64 v[208:209], s[20:21], 0, v[0:1]
	s_mov_b32 m0, s23
	s_nop 0
	global_load_lds_dwordx4 v[208:209], off
	s_mov_b32 m0, s28
	s_nop 0
	global_load_lds_dwordx4 v[210:211], off
	s_waitcnt vmcnt(8)
	s_waitcnt lgkmcnt(0)
	s_barrier
	s_setprio 1
	s_waitcnt lgkmcnt(0)
	v_mfma_f32_16x16x32_bf16 v[64:67], v[132:135], v[164:167], 0
	v_mfma_f32_16x16x32_bf16 v[64:67], v[136:139], v[168:171], v[64:67]
	v_mfma_f32_16x16x32_bf16 v[56:59], v[148:151], v[164:167], 0
	v_mfma_f32_16x16x32_bf16 v[56:59], v[152:155], v[168:171], v[56:59]
	v_mfma_f32_16x16x32_bf16 v[60:63], v[140:143], v[164:167], 0
	v_mfma_f32_16x16x32_bf16 v[60:63], v[144:147], v[168:171], v[60:63]
	v_mfma_f32_16x16x32_bf16 v[48:51], v[156:159], v[164:167], 0
	v_mfma_f32_16x16x32_bf16 v[48:51], v[160:163], v[168:171], v[48:51]
	v_mfma_f32_16x16x32_bf16 v[52:55], v[132:135], v[172:175], 0
	v_mfma_f32_16x16x32_bf16 v[52:55], v[136:139], v[176:179], v[52:55]
	v_mfma_f32_16x16x32_bf16 v[40:43], v[148:151], v[172:175], 0
	v_mfma_f32_16x16x32_bf16 v[40:43], v[152:155], v[176:179], v[40:43]
	v_mfma_f32_16x16x32_bf16 v[44:47], v[140:143], v[172:175], 0
	v_mfma_f32_16x16x32_bf16 v[44:47], v[144:147], v[176:179], v[44:47]
	v_mfma_f32_16x16x32_bf16 v[32:35], v[156:159], v[172:175], 0
	v_mfma_f32_16x16x32_bf16 v[32:35], v[160:163], v[176:179], v[32:35]
	v_mfma_f32_16x16x32_bf16 v[36:39], v[132:135], v[180:183], 0
	v_mfma_f32_16x16x32_bf16 v[36:39], v[136:139], v[184:187], v[36:39]
	v_mfma_f32_16x16x32_bf16 v[24:27], v[148:151], v[180:183], 0
	v_mfma_f32_16x16x32_bf16 v[24:27], v[152:155], v[184:187], v[24:27]
	v_mfma_f32_16x16x32_bf16 v[28:31], v[140:143], v[180:183], 0
	v_mfma_f32_16x16x32_bf16 v[28:31], v[144:147], v[184:187], v[28:31]
	v_mfma_f32_16x16x32_bf16 v[16:19], v[156:159], v[180:183], 0
	v_mfma_f32_16x16x32_bf16 v[16:19], v[160:163], v[184:187], v[16:19]
	v_mfma_f32_16x16x32_bf16 v[20:23], v[132:135], v[188:191], 0
	v_mfma_f32_16x16x32_bf16 v[20:23], v[136:139], v[192:195], v[20:23]
	v_mfma_f32_16x16x32_bf16 v[8:11], v[148:151], v[188:191], 0
	v_mfma_f32_16x16x32_bf16 v[8:11], v[152:155], v[192:195], v[8:11]
	v_mfma_f32_16x16x32_bf16 v[12:15], v[140:143], v[188:191], 0
	v_mfma_f32_16x16x32_bf16 v[12:15], v[144:147], v[192:195], v[12:15]
	v_mfma_f32_16x16x32_bf16 v[4:7], v[156:159], v[188:191], 0
	v_mfma_f32_16x16x32_bf16 v[4:7], v[160:163], v[192:195], v[4:7]
	s_setprio 0
	s_barrier
	s_sleep 1
	s_add_i32 s44, 0, 0x18000
	s_add_i32 s45, 0, 0x1c000
	s_add_u32 s14, s20, 0x160000
	s_addc_u32 s15, s21, 0
	s_mov_b32 m0, s29
	v_lshl_add_u64 v[212:213], s[14:15], 0, v[0:1]
	global_load_lds_dwordx4 v[212:213], off
	v_lshl_add_u64 v[212:213], s[14:15], 0, v[196:197]
	s_mov_b32 m0, s30
	s_nop 0
	global_load_lds_dwordx4 v[212:213], off
	v_add_u32_e32 v144, s44, v236
	v_add_u32_e32 v160, s45, v236
	ds_read_b128 v[132:135], v144
	ds_read_b128 v[136:139], v144 offset:1024
	ds_read_b128 v[140:143], v144 offset:2048
	ds_read_b128 v[144:147], v144 offset:3072
	ds_read_b128 v[148:151], v160
	ds_read_b128 v[152:155], v160 offset:1024
	ds_read_b128 v[156:159], v160 offset:2048
	ds_read_b128 v[160:163], v160 offset:3072
	ds_read_b128 v[164:167], v238 offset:32768
	ds_read_b128 v[168:171], v238 offset:33792
	ds_read_b128 v[172:175], v238 offset:34816
	ds_read_b128 v[176:179], v238 offset:35840
	ds_read_b128 v[180:183], v238 offset:36864
	ds_read_b128 v[184:187], v238 offset:37888
	ds_read_b128 v[188:191], v238 offset:38912
	ds_read_b128 v[192:195], v238 offset:39936
	s_waitcnt vmcnt(8)
	s_waitcnt lgkmcnt(0)
	s_barrier
	s_setprio 1
	s_waitcnt lgkmcnt(0)
	v_mfma_f32_16x16x32_bf16 v[128:131], v[132:135], v[164:167], v[128:131]
	v_mfma_f32_16x16x32_bf16 v[128:131], v[136:139], v[168:171], v[128:131]
	v_mfma_f32_16x16x32_bf16 v[120:123], v[148:151], v[164:167], v[120:123]
	v_mfma_f32_16x16x32_bf16 v[120:123], v[152:155], v[168:171], v[120:123]
	v_mfma_f32_16x16x32_bf16 v[124:127], v[140:143], v[164:167], v[124:127]
	v_mfma_f32_16x16x32_bf16 v[124:127], v[144:147], v[168:171], v[124:127]
	v_mfma_f32_16x16x32_bf16 v[112:115], v[156:159], v[164:167], v[112:115]
	v_mfma_f32_16x16x32_bf16 v[112:115], v[160:163], v[168:171], v[112:115]
	v_mfma_f32_16x16x32_bf16 v[116:119], v[132:135], v[172:175], v[116:119]
	v_mfma_f32_16x16x32_bf16 v[116:119], v[136:139], v[176:179], v[116:119]
	v_mfma_f32_16x16x32_bf16 v[104:107], v[148:151], v[172:175], v[104:107]
	v_mfma_f32_16x16x32_bf16 v[104:107], v[152:155], v[176:179], v[104:107]
	v_mfma_f32_16x16x32_bf16 v[108:111], v[140:143], v[172:175], v[108:111]
	v_mfma_f32_16x16x32_bf16 v[108:111], v[144:147], v[176:179], v[108:111]
	v_mfma_f32_16x16x32_bf16 v[96:99], v[156:159], v[172:175], v[96:99]
	v_mfma_f32_16x16x32_bf16 v[96:99], v[160:163], v[176:179], v[96:99]
	v_mfma_f32_16x16x32_bf16 v[100:103], v[132:135], v[180:183], v[100:103]
	v_mfma_f32_16x16x32_bf16 v[100:103], v[136:139], v[184:187], v[100:103]
	v_mfma_f32_16x16x32_bf16 v[88:91], v[148:151], v[180:183], v[88:91]
	v_mfma_f32_16x16x32_bf16 v[88:91], v[152:155], v[184:187], v[88:91]
	v_mfma_f32_16x16x32_bf16 v[92:95], v[140:143], v[180:183], v[92:95]
	v_mfma_f32_16x16x32_bf16 v[92:95], v[144:147], v[184:187], v[92:95]
	v_mfma_f32_16x16x32_bf16 v[80:83], v[156:159], v[180:183], v[80:83]
	v_mfma_f32_16x16x32_bf16 v[80:83], v[160:163], v[184:187], v[80:83]
	v_mfma_f32_16x16x32_bf16 v[84:87], v[132:135], v[188:191], v[84:87]
	v_mfma_f32_16x16x32_bf16 v[84:87], v[136:139], v[192:195], v[84:87]
	v_mfma_f32_16x16x32_bf16 v[72:75], v[148:151], v[188:191], v[72:75]
	v_mfma_f32_16x16x32_bf16 v[72:75], v[152:155], v[192:195], v[72:75]
	v_mfma_f32_16x16x32_bf16 v[76:79], v[140:143], v[188:191], v[76:79]
	v_mfma_f32_16x16x32_bf16 v[76:79], v[144:147], v[192:195], v[76:79]
	v_mfma_f32_16x16x32_bf16 v[68:71], v[156:159], v[188:191], v[68:71]
	v_mfma_f32_16x16x32_bf16 v[68:71], v[160:163], v[192:195], v[68:71]
	s_setprio 0
	s_barrier
	s_sleep 2
	s_add_i32 s14, s44, s22
	v_lshl_add_u64 v[204:205], v[204:205], 0, s[66:67]
	s_mov_b32 m0, s14
	ds_read_b128 v[164:167], v238 offset:49152
	ds_read_b128 v[168:171], v238 offset:50176
	ds_read_b128 v[172:175], v238 offset:51200
	ds_read_b128 v[176:179], v238 offset:52224
	ds_read_b128 v[180:183], v238 offset:53248
	ds_read_b128 v[184:187], v238 offset:54272
	ds_read_b128 v[188:191], v238 offset:55296
	ds_read_b128 v[192:195], v238 offset:56320
	global_load_lds_dwordx4 v[204:205], off
	s_add_i32 m0, s14, 0x2000
	s_add_u32 s14, s18, 0x160080
	v_lshl_add_u64 v[204:205], v[206:207], 0, s[66:67]
	s_addc_u32 s15, s19, 0
	s_add_i32 s18, s45, s22
	global_load_lds_dwordx4 v[204:205], off
	v_lshl_add_u64 v[204:205], s[14:15], 0, v[2:3]
	s_mov_b32 m0, s18
	s_nop 0
	global_load_lds_dwordx4 v[204:205], off
	v_lshl_add_u64 v[204:205], s[14:15], 0, v[198:199]
	s_add_i32 m0, s18, 0x2000
	s_nop 0
	global_load_lds_dwordx4 v[204:205], off
	v_lshl_add_u64 v[204:205], v[208:209], 0, s[66:67]
	s_mov_b32 m0, s31
	s_nop 0
	global_load_lds_dwordx4 v[204:205], off
	v_lshl_add_u64 v[204:205], v[210:211], 0, s[66:67]
	s_mov_b32 m0, s34
	s_nop 0
	global_load_lds_dwordx4 v[204:205], off
	s_waitcnt vmcnt(8)
	s_waitcnt lgkmcnt(0)
	s_barrier
	s_setprio 1
	s_waitcnt lgkmcnt(0)
	v_mfma_f32_16x16x32_bf16 v[64:67], v[132:135], v[164:167], v[64:67]
	v_mfma_f32_16x16x32_bf16 v[64:67], v[136:139], v[168:171], v[64:67]
	v_mfma_f32_16x16x32_bf16 v[56:59], v[148:151], v[164:167], v[56:59]
	v_mfma_f32_16x16x32_bf16 v[56:59], v[152:155], v[168:171], v[56:59]
	v_mfma_f32_16x16x32_bf16 v[60:63], v[140:143], v[164:167], v[60:63]
	v_mfma_f32_16x16x32_bf16 v[60:63], v[144:147], v[168:171], v[60:63]
	v_mfma_f32_16x16x32_bf16 v[48:51], v[156:159], v[164:167], v[48:51]
	v_mfma_f32_16x16x32_bf16 v[48:51], v[160:163], v[168:171], v[48:51]
	v_mfma_f32_16x16x32_bf16 v[52:55], v[132:135], v[172:175], v[52:55]
	v_mfma_f32_16x16x32_bf16 v[52:55], v[136:139], v[176:179], v[52:55]
	v_mfma_f32_16x16x32_bf16 v[40:43], v[148:151], v[172:175], v[40:43]
	v_mfma_f32_16x16x32_bf16 v[40:43], v[152:155], v[176:179], v[40:43]
	v_mfma_f32_16x16x32_bf16 v[44:47], v[140:143], v[172:175], v[44:47]
	v_mfma_f32_16x16x32_bf16 v[44:47], v[144:147], v[176:179], v[44:47]
	v_mfma_f32_16x16x32_bf16 v[32:35], v[156:159], v[172:175], v[32:35]
	v_mfma_f32_16x16x32_bf16 v[32:35], v[160:163], v[176:179], v[32:35]
	v_mfma_f32_16x16x32_bf16 v[36:39], v[132:135], v[180:183], v[36:39]
	v_mfma_f32_16x16x32_bf16 v[36:39], v[136:139], v[184:187], v[36:39]
	v_mfma_f32_16x16x32_bf16 v[24:27], v[148:151], v[180:183], v[24:27]
	v_mfma_f32_16x16x32_bf16 v[24:27], v[152:155], v[184:187], v[24:27]
	v_mfma_f32_16x16x32_bf16 v[28:31], v[140:143], v[180:183], v[28:31]
	v_mfma_f32_16x16x32_bf16 v[28:31], v[144:147], v[184:187], v[28:31]
	v_mfma_f32_16x16x32_bf16 v[16:19], v[156:159], v[180:183], v[16:19]
	v_mfma_f32_16x16x32_bf16 v[16:19], v[160:163], v[184:187], v[16:19]
	v_mfma_f32_16x16x32_bf16 v[20:23], v[132:135], v[188:191], v[20:23]
	v_mfma_f32_16x16x32_bf16 v[20:23], v[136:139], v[192:195], v[20:23]
	v_mfma_f32_16x16x32_bf16 v[8:11], v[148:151], v[188:191], v[8:11]
	v_mfma_f32_16x16x32_bf16 v[8:11], v[152:155], v[192:195], v[8:11]
	v_mfma_f32_16x16x32_bf16 v[12:15], v[140:143], v[188:191], v[12:15]
	v_mfma_f32_16x16x32_bf16 v[12:15], v[144:147], v[192:195], v[12:15]
	v_mfma_f32_16x16x32_bf16 v[4:7], v[156:159], v[188:191], v[4:7]
	v_mfma_f32_16x16x32_bf16 v[4:7], v[160:163], v[192:195], v[4:7]
	s_setprio 0
	s_barrier
	s_add_i32 s43, s43, 2
	s_add_u32 s38, s38, 0x100
	s_addc_u32 s39, s39, 0
	s_cmpk_gt_u32 s43, 0x55
	s_mov_b64 s[14:15], s[16:17]
.LBB0_347:
	s_sleep 1
	s_add_u32 s16, s14, 0x100
	s_addc_u32 s17, s15, 0
	s_add_i32 s44, 0, 0x10000
	s_cmpk_eq_i32 s43, 0x54
	s_cselect_b32 s21, s11, s17
	s_cselect_b32 s20, s10, s16
	s_cselect_b32 s19, s13, s39
	s_cselect_b32 s18, s12, s38
	s_add_i32 s45, 0, 0x14000
	v_lshl_add_u64 v[204:205], s[14:15], 0, v[200:201]
	s_add_i32 m0, s23, 0xc000
	s_nop 0
	global_load_lds_dwordx4 v[204:205], off
	v_lshl_add_u64 v[204:205], s[14:15], 0, v[202:203]
	s_add_i32 m0, s23, 0xe000
	s_nop 0
	global_load_lds_dwordx4 v[204:205], off
	v_add_u32_e32 v144, s44, v236
	v_add_u32_e32 v160, s45, v236
	ds_read_b128 v[132:135], v144
	ds_read_b128 v[136:139], v144 offset:1024
	ds_read_b128 v[140:143], v144 offset:2048
	ds_read_b128 v[144:147], v144 offset:3072
	ds_read_b128 v[148:151], v160
	ds_read_b128 v[152:155], v160 offset:1024
	ds_read_b128 v[156:159], v160 offset:2048
	ds_read_b128 v[160:163], v160 offset:3072
	ds_read_b128 v[164:167], v238
	ds_read_b128 v[168:171], v238 offset:1024
	ds_read_b128 v[172:175], v238 offset:2048
	ds_read_b128 v[176:179], v238 offset:3072
	ds_read_b128 v[180:183], v238 offset:4096
	ds_read_b128 v[184:187], v238 offset:5120
	ds_read_b128 v[188:191], v238 offset:6144
	ds_read_b128 v[192:195], v238 offset:7168
	s_waitcnt vmcnt(8)
	s_waitcnt lgkmcnt(0)
	s_barrier
	s_setprio 1
	s_waitcnt lgkmcnt(0)
	v_mfma_f32_16x16x32_bf16 v[128:131], v[132:135], v[164:167], v[128:131]
	v_mfma_f32_16x16x32_bf16 v[128:131], v[136:139], v[168:171], v[128:131]
	v_mfma_f32_16x16x32_bf16 v[120:123], v[148:151], v[164:167], v[120:123]
	v_mfma_f32_16x16x32_bf16 v[120:123], v[152:155], v[168:171], v[120:123]
	v_mfma_f32_16x16x32_bf16 v[124:127], v[140:143], v[164:167], v[124:127]
	v_mfma_f32_16x16x32_bf16 v[124:127], v[144:147], v[168:171], v[124:127]
	v_mfma_f32_16x16x32_bf16 v[112:115], v[156:159], v[164:167], v[112:115]
	v_mfma_f32_16x16x32_bf16 v[112:115], v[160:163], v[168:171], v[112:115]
	v_mfma_f32_16x16x32_bf16 v[116:119], v[132:135], v[172:175], v[116:119]
	v_mfma_f32_16x16x32_bf16 v[116:119], v[136:139], v[176:179], v[116:119]
	v_mfma_f32_16x16x32_bf16 v[104:107], v[148:151], v[172:175], v[104:107]
	v_mfma_f32_16x16x32_bf16 v[104:107], v[152:155], v[176:179], v[104:107]
	v_mfma_f32_16x16x32_bf16 v[108:111], v[140:143], v[172:175], v[108:111]
	v_mfma_f32_16x16x32_bf16 v[108:111], v[144:147], v[176:179], v[108:111]
	v_mfma_f32_16x16x32_bf16 v[96:99], v[156:159], v[172:175], v[96:99]
	v_mfma_f32_16x16x32_bf16 v[96:99], v[160:163], v[176:179], v[96:99]
	v_mfma_f32_16x16x32_bf16 v[100:103], v[132:135], v[180:183], v[100:103]
	v_mfma_f32_16x16x32_bf16 v[100:103], v[136:139], v[184:187], v[100:103]
	v_mfma_f32_16x16x32_bf16 v[88:91], v[148:151], v[180:183], v[88:91]
	v_mfma_f32_16x16x32_bf16 v[88:91], v[152:155], v[184:187], v[88:91]
	v_mfma_f32_16x16x32_bf16 v[92:95], v[140:143], v[180:183], v[92:95]
	v_mfma_f32_16x16x32_bf16 v[92:95], v[144:147], v[184:187], v[92:95]
	v_mfma_f32_16x16x32_bf16 v[80:83], v[156:159], v[180:183], v[80:83]
	v_mfma_f32_16x16x32_bf16 v[80:83], v[160:163], v[184:187], v[80:83]
	v_mfma_f32_16x16x32_bf16 v[84:87], v[132:135], v[188:191], v[84:87]
	v_mfma_f32_16x16x32_bf16 v[84:87], v[136:139], v[192:195], v[84:87]
	v_mfma_f32_16x16x32_bf16 v[72:75], v[148:151], v[188:191], v[72:75]
	v_mfma_f32_16x16x32_bf16 v[72:75], v[152:155], v[192:195], v[72:75]
	v_mfma_f32_16x16x32_bf16 v[76:79], v[140:143], v[188:191], v[76:79]
	v_mfma_f32_16x16x32_bf16 v[76:79], v[144:147], v[192:195], v[76:79]
	v_mfma_f32_16x16x32_bf16 v[68:71], v[156:159], v[188:191], v[68:71]
	v_mfma_f32_16x16x32_bf16 v[68:71], v[160:163], v[192:195], v[68:71]
	s_setprio 0
	s_barrier
	s_sleep 2
	s_add_i32 s14, s44, s22
	v_lshl_add_u64 v[204:205], s[18:19], 0, v[2:3]
	s_mov_b32 m0, s14
	ds_read_b128 v[164:167], v238 offset:16384
	ds_read_b128 v[168:171], v238 offset:17408
	ds_read_b128 v[172:175], v238 offset:18432
	ds_read_b128 v[176:179], v238 offset:19456
	ds_read_b128 v[180:183], v238 offset:20480
	ds_read_b128 v[184:187], v238 offset:21504
	ds_read_b128 v[188:191], v238 offset:22528
	ds_read_b128 v[192:195], v238 offset:23552
	global_load_lds_dwordx4 v[204:205], off
	s_add_i32 m0, s14, 0x2000
	s_add_u32 s14, s18, 0x160000
	v_lshl_add_u64 v[206:207], s[18:19], 0, v[198:199]
	s_addc_u32 s15, s19, 0
	s_add_i32 s44, s45, s22
	global_load_lds_dwordx4 v[206:207], off
	v_lshl_add_u64 v[208:209], s[14:15], 0, v[2:3]
	s_mov_b32 m0, s44
	v_lshl_add_u64 v[210:211], s[20:21], 0, v[196:197]
	global_load_lds_dwordx4 v[208:209], off
	v_lshl_add_u64 v[208:209], s[14:15], 0, v[198:199]
	s_add_i32 m0, s44, 0x2000
	s_nop 0
	global_load_lds_dwordx4 v[208:209], off
	v_lshl_add_u64 v[208:209], s[20:21], 0, v[0:1]
	s_mov_b32 m0, s23
	s_nop 0
	global_load_lds_dwordx4 v[208:209], off
	s_mov_b32 m0, s28
	s_nop 0
	global_load_lds_dwordx4 v[210:211], off
	s_waitcnt vmcnt(8)
	s_waitcnt lgkmcnt(0)
	s_barrier
	s_setprio 1
	s_waitcnt lgkmcnt(0)
	v_mfma_f32_16x16x32_bf16 v[64:67], v[132:135], v[164:167], v[64:67]
	v_mfma_f32_16x16x32_bf16 v[64:67], v[136:139], v[168:171], v[64:67]
	v_mfma_f32_16x16x32_bf16 v[56:59], v[148:151], v[164:167], v[56:59]
	v_mfma_f32_16x16x32_bf16 v[56:59], v[152:155], v[168:171], v[56:59]
	v_mfma_f32_16x16x32_bf16 v[60:63], v[140:143], v[164:167], v[60:63]
	v_mfma_f32_16x16x32_bf16 v[60:63], v[144:147], v[168:171], v[60:63]
	v_mfma_f32_16x16x32_bf16 v[48:51], v[156:159], v[164:167], v[48:51]
	v_mfma_f32_16x16x32_bf16 v[48:51], v[160:163], v[168:171], v[48:51]
	v_mfma_f32_16x16x32_bf16 v[52:55], v[132:135], v[172:175], v[52:55]
	v_mfma_f32_16x16x32_bf16 v[52:55], v[136:139], v[176:179], v[52:55]
	v_mfma_f32_16x16x32_bf16 v[40:43], v[148:151], v[172:175], v[40:43]
	v_mfma_f32_16x16x32_bf16 v[40:43], v[152:155], v[176:179], v[40:43]
	v_mfma_f32_16x16x32_bf16 v[44:47], v[140:143], v[172:175], v[44:47]
	v_mfma_f32_16x16x32_bf16 v[44:47], v[144:147], v[176:179], v[44:47]
	v_mfma_f32_16x16x32_bf16 v[32:35], v[156:159], v[172:175], v[32:35]
	v_mfma_f32_16x16x32_bf16 v[32:35], v[160:163], v[176:179], v[32:35]
	v_mfma_f32_16x16x32_bf16 v[36:39], v[132:135], v[180:183], v[36:39]
	v_mfma_f32_16x16x32_bf16 v[36:39], v[136:139], v[184:187], v[36:39]
	v_mfma_f32_16x16x32_bf16 v[24:27], v[148:151], v[180:183], v[24:27]
	v_mfma_f32_16x16x32_bf16 v[24:27], v[152:155], v[184:187], v[24:27]
	v_mfma_f32_16x16x32_bf16 v[28:31], v[140:143], v[180:183], v[28:31]
	v_mfma_f32_16x16x32_bf16 v[28:31], v[144:147], v[184:187], v[28:31]
	v_mfma_f32_16x16x32_bf16 v[16:19], v[156:159], v[180:183], v[16:19]
	v_mfma_f32_16x16x32_bf16 v[16:19], v[160:163], v[184:187], v[16:19]
	v_mfma_f32_16x16x32_bf16 v[20:23], v[132:135], v[188:191], v[20:23]
	v_mfma_f32_16x16x32_bf16 v[20:23], v[136:139], v[192:195], v[20:23]
	v_mfma_f32_16x16x32_bf16 v[8:11], v[148:151], v[188:191], v[8:11]
	v_mfma_f32_16x16x32_bf16 v[8:11], v[152:155], v[192:195], v[8:11]
	v_mfma_f32_16x16x32_bf16 v[12:15], v[140:143], v[188:191], v[12:15]
	v_mfma_f32_16x16x32_bf16 v[12:15], v[144:147], v[192:195], v[12:15]
	v_mfma_f32_16x16x32_bf16 v[4:7], v[156:159], v[188:191], v[4:7]
	v_mfma_f32_16x16x32_bf16 v[4:7], v[160:163], v[192:195], v[4:7]
	s_setprio 0
	s_barrier
	s_sleep 1
	s_add_i32 s44, 0, 0x18000
	s_add_i32 s45, 0, 0x1c000
	s_add_u32 s14, s20, 0x160000
	s_addc_u32 s15, s21, 0
	s_mov_b32 m0, s29
	v_lshl_add_u64 v[212:213], s[14:15], 0, v[0:1]
	global_load_lds_dwordx4 v[212:213], off
	v_lshl_add_u64 v[212:213], s[14:15], 0, v[196:197]
	s_mov_b32 m0, s30
	s_nop 0
	global_load_lds_dwordx4 v[212:213], off
	v_add_u32_e32 v144, s44, v236
	v_add_u32_e32 v160, s45, v236
	ds_read_b128 v[132:135], v144
	ds_read_b128 v[136:139], v144 offset:1024
	ds_read_b128 v[140:143], v144 offset:2048
	ds_read_b128 v[144:147], v144 offset:3072
	ds_read_b128 v[148:151], v160
	ds_read_b128 v[152:155], v160 offset:1024
	ds_read_b128 v[156:159], v160 offset:2048
	ds_read_b128 v[160:163], v160 offset:3072
	ds_read_b128 v[164:167], v238 offset:32768
	ds_read_b128 v[168:171], v238 offset:33792
	ds_read_b128 v[172:175], v238 offset:34816
	ds_read_b128 v[176:179], v238 offset:35840
	ds_read_b128 v[180:183], v238 offset:36864
	ds_read_b128 v[184:187], v238 offset:37888
	ds_read_b128 v[188:191], v238 offset:38912
	ds_read_b128 v[192:195], v238 offset:39936
	s_waitcnt vmcnt(8)
	s_waitcnt lgkmcnt(0)
	s_barrier
	s_setprio 1
	s_waitcnt lgkmcnt(0)
	v_mfma_f32_16x16x32_bf16 v[128:131], v[132:135], v[164:167], v[128:131]
	v_mfma_f32_16x16x32_bf16 v[128:131], v[136:139], v[168:171], v[128:131]
	v_mfma_f32_16x16x32_bf16 v[120:123], v[148:151], v[164:167], v[120:123]
	v_mfma_f32_16x16x32_bf16 v[120:123], v[152:155], v[168:171], v[120:123]
	v_mfma_f32_16x16x32_bf16 v[124:127], v[140:143], v[164:167], v[124:127]
	v_mfma_f32_16x16x32_bf16 v[124:127], v[144:147], v[168:171], v[124:127]
	v_mfma_f32_16x16x32_bf16 v[112:115], v[156:159], v[164:167], v[112:115]
	v_mfma_f32_16x16x32_bf16 v[112:115], v[160:163], v[168:171], v[112:115]
	v_mfma_f32_16x16x32_bf16 v[116:119], v[132:135], v[172:175], v[116:119]
	v_mfma_f32_16x16x32_bf16 v[116:119], v[136:139], v[176:179], v[116:119]
	v_mfma_f32_16x16x32_bf16 v[104:107], v[148:151], v[172:175], v[104:107]
	v_mfma_f32_16x16x32_bf16 v[104:107], v[152:155], v[176:179], v[104:107]
	v_mfma_f32_16x16x32_bf16 v[108:111], v[140:143], v[172:175], v[108:111]
	v_mfma_f32_16x16x32_bf16 v[108:111], v[144:147], v[176:179], v[108:111]
	v_mfma_f32_16x16x32_bf16 v[96:99], v[156:159], v[172:175], v[96:99]
	v_mfma_f32_16x16x32_bf16 v[96:99], v[160:163], v[176:179], v[96:99]
	v_mfma_f32_16x16x32_bf16 v[100:103], v[132:135], v[180:183], v[100:103]
	v_mfma_f32_16x16x32_bf16 v[100:103], v[136:139], v[184:187], v[100:103]
	v_mfma_f32_16x16x32_bf16 v[88:91], v[148:151], v[180:183], v[88:91]
	v_mfma_f32_16x16x32_bf16 v[88:91], v[152:155], v[184:187], v[88:91]
	v_mfma_f32_16x16x32_bf16 v[92:95], v[140:143], v[180:183], v[92:95]
	v_mfma_f32_16x16x32_bf16 v[92:95], v[144:147], v[184:187], v[92:95]
	v_mfma_f32_16x16x32_bf16 v[80:83], v[156:159], v[180:183], v[80:83]
	v_mfma_f32_16x16x32_bf16 v[80:83], v[160:163], v[184:187], v[80:83]
	v_mfma_f32_16x16x32_bf16 v[84:87], v[132:135], v[188:191], v[84:87]
	v_mfma_f32_16x16x32_bf16 v[84:87], v[136:139], v[192:195], v[84:87]
	v_mfma_f32_16x16x32_bf16 v[72:75], v[148:151], v[188:191], v[72:75]
	v_mfma_f32_16x16x32_bf16 v[72:75], v[152:155], v[192:195], v[72:75]
	v_mfma_f32_16x16x32_bf16 v[76:79], v[140:143], v[188:191], v[76:79]
	v_mfma_f32_16x16x32_bf16 v[76:79], v[144:147], v[192:195], v[76:79]
	v_mfma_f32_16x16x32_bf16 v[68:71], v[156:159], v[188:191], v[68:71]
	v_mfma_f32_16x16x32_bf16 v[68:71], v[160:163], v[192:195], v[68:71]
	s_setprio 0
	s_barrier
	s_sleep 2
	s_add_i32 s14, s44, s22
	v_lshl_add_u64 v[204:205], v[204:205], 0, s[66:67]
	s_mov_b32 m0, s14
	ds_read_b128 v[164:167], v238 offset:49152
	ds_read_b128 v[168:171], v238 offset:50176
	ds_read_b128 v[172:175], v238 offset:51200
	ds_read_b128 v[176:179], v238 offset:52224
	ds_read_b128 v[180:183], v238 offset:53248
	ds_read_b128 v[184:187], v238 offset:54272
	ds_read_b128 v[188:191], v238 offset:55296
	ds_read_b128 v[192:195], v238 offset:56320
	global_load_lds_dwordx4 v[204:205], off
	s_add_i32 m0, s14, 0x2000
	s_add_u32 s14, s18, 0x160080
	v_lshl_add_u64 v[204:205], v[206:207], 0, s[66:67]
	s_addc_u32 s15, s19, 0
	s_add_i32 s18, s45, s22
	global_load_lds_dwordx4 v[204:205], off
	v_lshl_add_u64 v[204:205], s[14:15], 0, v[2:3]
	s_mov_b32 m0, s18
	s_nop 0
	global_load_lds_dwordx4 v[204:205], off
	v_lshl_add_u64 v[204:205], s[14:15], 0, v[198:199]
	s_add_i32 m0, s18, 0x2000
	s_nop 0
	global_load_lds_dwordx4 v[204:205], off
	v_lshl_add_u64 v[204:205], v[208:209], 0, s[66:67]
	s_mov_b32 m0, s31
	s_nop 0
	global_load_lds_dwordx4 v[204:205], off
	v_lshl_add_u64 v[204:205], v[210:211], 0, s[66:67]
	s_mov_b32 m0, s34
	s_nop 0
	global_load_lds_dwordx4 v[204:205], off
	s_waitcnt vmcnt(8)
	s_waitcnt lgkmcnt(0)
	s_barrier
	s_setprio 1
	s_waitcnt lgkmcnt(0)
	v_mfma_f32_16x16x32_bf16 v[64:67], v[132:135], v[164:167], v[64:67]
	v_mfma_f32_16x16x32_bf16 v[64:67], v[136:139], v[168:171], v[64:67]
	v_mfma_f32_16x16x32_bf16 v[56:59], v[148:151], v[164:167], v[56:59]
	v_mfma_f32_16x16x32_bf16 v[56:59], v[152:155], v[168:171], v[56:59]
	v_mfma_f32_16x16x32_bf16 v[60:63], v[140:143], v[164:167], v[60:63]
	v_mfma_f32_16x16x32_bf16 v[60:63], v[144:147], v[168:171], v[60:63]
	v_mfma_f32_16x16x32_bf16 v[48:51], v[156:159], v[164:167], v[48:51]
	v_mfma_f32_16x16x32_bf16 v[48:51], v[160:163], v[168:171], v[48:51]
	v_mfma_f32_16x16x32_bf16 v[52:55], v[132:135], v[172:175], v[52:55]
	v_mfma_f32_16x16x32_bf16 v[52:55], v[136:139], v[176:179], v[52:55]
	v_mfma_f32_16x16x32_bf16 v[40:43], v[148:151], v[172:175], v[40:43]
	v_mfma_f32_16x16x32_bf16 v[40:43], v[152:155], v[176:179], v[40:43]
	v_mfma_f32_16x16x32_bf16 v[44:47], v[140:143], v[172:175], v[44:47]
	v_mfma_f32_16x16x32_bf16 v[44:47], v[144:147], v[176:179], v[44:47]
	v_mfma_f32_16x16x32_bf16 v[32:35], v[156:159], v[172:175], v[32:35]
	v_mfma_f32_16x16x32_bf16 v[32:35], v[160:163], v[176:179], v[32:35]
	v_mfma_f32_16x16x32_bf16 v[36:39], v[132:135], v[180:183], v[36:39]
	v_mfma_f32_16x16x32_bf16 v[36:39], v[136:139], v[184:187], v[36:39]
	v_mfma_f32_16x16x32_bf16 v[24:27], v[148:151], v[180:183], v[24:27]
	v_mfma_f32_16x16x32_bf16 v[24:27], v[152:155], v[184:187], v[24:27]
	v_mfma_f32_16x16x32_bf16 v[28:31], v[140:143], v[180:183], v[28:31]
	v_mfma_f32_16x16x32_bf16 v[28:31], v[144:147], v[184:187], v[28:31]
	v_mfma_f32_16x16x32_bf16 v[16:19], v[156:159], v[180:183], v[16:19]
	v_mfma_f32_16x16x32_bf16 v[16:19], v[160:163], v[184:187], v[16:19]
	v_mfma_f32_16x16x32_bf16 v[20:23], v[132:135], v[188:191], v[20:23]
	v_mfma_f32_16x16x32_bf16 v[20:23], v[136:139], v[192:195], v[20:23]
	v_mfma_f32_16x16x32_bf16 v[8:11], v[148:151], v[188:191], v[8:11]
	v_mfma_f32_16x16x32_bf16 v[8:11], v[152:155], v[192:195], v[8:11]
	v_mfma_f32_16x16x32_bf16 v[12:15], v[140:143], v[188:191], v[12:15]
	v_mfma_f32_16x16x32_bf16 v[12:15], v[144:147], v[192:195], v[12:15]
	v_mfma_f32_16x16x32_bf16 v[4:7], v[156:159], v[188:191], v[4:7]
	v_mfma_f32_16x16x32_bf16 v[4:7], v[160:163], v[192:195], v[4:7]
	s_setprio 0
	s_barrier
	s_add_i32 s43, s43, 2
	s_add_u32 s38, s38, 0x100
	s_addc_u32 s39, s39, 0
	s_cmpk_gt_u32 s43, 0x55
	s_mov_b64 s[14:15], s[16:17]
	s_cbranch_scc0 .LBB0_347
	s_and_b64 vcc, exec, s[6:7]
	s_cbranch_vccz .LBB0_350
	s_barrier

.LBB0_429:
	s_ashr_i32 s23, s22, 31
	s_lshl_b64 s[24:25], s[22:23], 20
	s_add_u32 s24, s51, s24
	s_addc_u32 s25, s52, s25
	s_and_b64 s[26:27], s[40:41], exec
	s_cselect_b32 s5, s25, s29
	s_cselect_b32 s23, s24, s28
	s_ashr_i32 s21, s20, 31
	s_lshl_b64 s[26:27], s[20:21], 20
	s_add_u32 s26, s12, s26
	s_addc_u32 s27, s13, s27
	s_and_b64 s[42:43], s[40:41], exec
	s_cselect_b32 s21, s27, s31
	s_cselect_b32 s62, s26, s30
	s_add_u32 s28, s28, 0x80080
	s_addc_u32 s29, s29, 0
	s_add_u32 s63, s30, 0x100
	s_addc_u32 s68, s31, 0
	s_mov_b32 s69, -2
	s_sleep 1
	s_add_u32 s30, s28, 0xfff80080
	s_addc_u32 s31, s29, -1
	s_add_i32 s70, 0, 0x10000
	s_cmp_eq_u32 s69, 28
	s_cselect_b32 s43, s5, s31
	s_cselect_b32 s42, s23, s30
	s_cselect_b32 s31, s21, s68
	s_cselect_b32 s30, s62, s63
	s_add_i32 s73, 0, 0x14000
	s_waitcnt lgkmcnt(0)
	v_lshl_add_u64 v[160:161], s[28:29], 0, v[144:145]
	s_add_i32 m0, s15, 0xc000
	s_nop 0
	global_load_lds_dwordx4 v[160:161], off
	v_lshl_add_u64 v[160:161], s[28:29], 0, v[146:147]
	s_add_i32 m0, s15, 0xe000
	s_nop 0
	global_load_lds_dwordx4 v[160:161], off
	v_add_u32_e32 v152, s70, v163
	v_add_u32_e32 v160, s73, v163
	ds_read_b128 v[132:135], v152
	ds_read_b128 v[136:139], v152 offset:1024
	ds_read_b128 v[148:151], v152 offset:2048
	ds_read_b128 v[152:155], v152 offset:3072
	ds_read_b128 v[156:159], v160
	ds_read_b128 v[170:173], v160 offset:1024
	ds_read_b128 v[174:177], v160 offset:2048
	ds_read_b128 v[178:181], v160 offset:3072
	ds_read_b128 v[182:185], v167
	ds_read_b128 v[186:189], v167 offset:1024
	ds_read_b128 v[190:193], v167 offset:2048
	ds_read_b128 v[194:197], v167 offset:3072
	ds_read_b128 v[198:201], v167 offset:4096
	ds_read_b128 v[208:211], v167 offset:5120
	ds_read_b128 v[212:215], v167 offset:6144
	ds_read_b128 v[216:219], v167 offset:7168
	s_waitcnt vmcnt(8)
	s_waitcnt lgkmcnt(0)
	s_barrier
	s_setprio 1
	s_waitcnt lgkmcnt(0)
	v_mfma_f32_16x16x32_bf16 v[128:131], v[132:135], v[182:185], 0
	v_mfma_f32_16x16x32_bf16 v[128:131], v[136:139], v[186:189], v[128:131]
	v_mfma_f32_16x16x32_bf16 v[116:119], v[156:159], v[182:185], 0
	v_mfma_f32_16x16x32_bf16 v[116:119], v[170:173], v[186:189], v[116:119]
	v_mfma_f32_16x16x32_bf16 v[124:127], v[148:151], v[182:185], 0
	v_mfma_f32_16x16x32_bf16 v[124:127], v[152:155], v[186:189], v[124:127]
	v_mfma_f32_16x16x32_bf16 v[108:111], v[174:177], v[182:185], 0
	v_mfma_f32_16x16x32_bf16 v[108:111], v[178:181], v[186:189], v[108:111]
	v_mfma_f32_16x16x32_bf16 v[120:123], v[132:135], v[190:193], 0
	v_mfma_f32_16x16x32_bf16 v[120:123], v[136:139], v[194:197], v[120:123]
	v_mfma_f32_16x16x32_bf16 v[100:103], v[156:159], v[190:193], 0
	v_mfma_f32_16x16x32_bf16 v[100:103], v[170:173], v[194:197], v[100:103]
	v_mfma_f32_16x16x32_bf16 v[112:115], v[148:151], v[190:193], 0
	v_mfma_f32_16x16x32_bf16 v[112:115], v[152:155], v[194:197], v[112:115]
	v_mfma_f32_16x16x32_bf16 v[92:95], v[174:177], v[190:193], 0
	v_mfma_f32_16x16x32_bf16 v[92:95], v[178:181], v[194:197], v[92:95]
	v_mfma_f32_16x16x32_bf16 v[104:107], v[132:135], v[198:201], 0
	v_mfma_f32_16x16x32_bf16 v[104:107], v[136:139], v[208:211], v[104:107]
	v_mfma_f32_16x16x32_bf16 v[84:87], v[156:159], v[198:201], 0
	v_mfma_f32_16x16x32_bf16 v[84:87], v[170:173], v[208:211], v[84:87]
	v_mfma_f32_16x16x32_bf16 v[96:99], v[148:151], v[198:201], 0
	v_mfma_f32_16x16x32_bf16 v[96:99], v[152:155], v[208:211], v[96:99]
	v_mfma_f32_16x16x32_bf16 v[76:79], v[174:177], v[198:201], 0
	v_mfma_f32_16x16x32_bf16 v[76:79], v[178:181], v[208:211], v[76:79]
	v_mfma_f32_16x16x32_bf16 v[88:91], v[132:135], v[212:215], 0
	v_mfma_f32_16x16x32_bf16 v[88:91], v[136:139], v[216:219], v[88:91]
	v_mfma_f32_16x16x32_bf16 v[72:75], v[156:159], v[212:215], 0
	v_mfma_f32_16x16x32_bf16 v[72:75], v[170:173], v[216:219], v[72:75]
	v_mfma_f32_16x16x32_bf16 v[80:83], v[148:151], v[212:215], 0
	v_mfma_f32_16x16x32_bf16 v[80:83], v[152:155], v[216:219], v[80:83]
	v_mfma_f32_16x16x32_bf16 v[68:71], v[174:177], v[212:215], 0
	v_mfma_f32_16x16x32_bf16 v[68:71], v[178:181], v[216:219], v[68:71]
	s_setprio 0
	s_barrier
	s_sleep 2
	s_add_i32 s70, s70, s0
	v_lshl_add_u64 v[160:161], s[30:31], 0, v[2:3]
	s_mov_b32 m0, s70
	ds_read_b128 v[182:185], v167 offset:16384
	ds_read_b128 v[186:189], v167 offset:17408
	ds_read_b128 v[190:193], v167 offset:18432
	ds_read_b128 v[194:197], v167 offset:19456
	ds_read_b128 v[198:201], v167 offset:20480
	ds_read_b128 v[208:211], v167 offset:21504
	ds_read_b128 v[212:215], v167 offset:22528
	ds_read_b128 v[216:219], v167 offset:23552
	global_load_lds_dwordx4 v[160:161], off
	s_add_i32 m0, s70, 0x2000
	s_add_u32 s70, s30, 0x80000
	v_lshl_add_u64 v[202:203], s[30:31], 0, v[142:143]
	s_addc_u32 s71, s31, 0
	s_add_i32 s73, s73, s0
	global_load_lds_dwordx4 v[202:203], off
	v_lshl_add_u64 v[204:205], s[70:71], 0, v[2:3]
	s_mov_b32 m0, s73
	v_lshl_add_u64 v[206:207], s[42:43], 0, v[140:141]
	global_load_lds_dwordx4 v[204:205], off
	v_lshl_add_u64 v[204:205], s[70:71], 0, v[142:143]
	s_add_i32 m0, s73, 0x2000
	s_nop 0
	global_load_lds_dwordx4 v[204:205], off
	v_lshl_add_u64 v[204:205], s[42:43], 0, v[0:1]
	s_mov_b32 m0, s15
	s_nop 0
	global_load_lds_dwordx4 v[204:205], off
	s_mov_b32 m0, s53
	s_nop 0
	global_load_lds_dwordx4 v[206:207], off
	s_waitcnt vmcnt(8)
	s_waitcnt lgkmcnt(0)
	s_barrier
	s_setprio 1
	s_waitcnt lgkmcnt(0)
	v_mfma_f32_16x16x32_bf16 v[64:67], v[132:135], v[182:185], 0
	v_mfma_f32_16x16x32_bf16 v[64:67], v[136:139], v[186:189], v[64:67]
	v_mfma_f32_16x16x32_bf16 v[52:55], v[156:159], v[182:185], 0
	v_mfma_f32_16x16x32_bf16 v[52:55], v[170:173], v[186:189], v[52:55]
	v_mfma_f32_16x16x32_bf16 v[60:63], v[148:151], v[182:185], 0
	v_mfma_f32_16x16x32_bf16 v[60:63], v[152:155], v[186:189], v[60:63]
	v_mfma_f32_16x16x32_bf16 v[44:47], v[174:177], v[182:185], 0
	v_mfma_f32_16x16x32_bf16 v[44:47], v[178:181], v[186:189], v[44:47]
	v_mfma_f32_16x16x32_bf16 v[56:59], v[132:135], v[190:193], 0
	v_mfma_f32_16x16x32_bf16 v[56:59], v[136:139], v[194:197], v[56:59]
	v_mfma_f32_16x16x32_bf16 v[36:39], v[156:159], v[190:193], 0
	v_mfma_f32_16x16x32_bf16 v[36:39], v[170:173], v[194:197], v[36:39]
	v_mfma_f32_16x16x32_bf16 v[48:51], v[148:151], v[190:193], 0
	v_mfma_f32_16x16x32_bf16 v[48:51], v[152:155], v[194:197], v[48:51]
	v_mfma_f32_16x16x32_bf16 v[28:31], v[174:177], v[190:193], 0
	v_mfma_f32_16x16x32_bf16 v[28:31], v[178:181], v[194:197], v[28:31]
	v_mfma_f32_16x16x32_bf16 v[40:43], v[132:135], v[198:201], 0
	v_mfma_f32_16x16x32_bf16 v[40:43], v[136:139], v[208:211], v[40:43]
	v_mfma_f32_16x16x32_bf16 v[20:23], v[156:159], v[198:201], 0
	v_mfma_f32_16x16x32_bf16 v[20:23], v[170:173], v[208:211], v[20:23]
	v_mfma_f32_16x16x32_bf16 v[32:35], v[148:151], v[198:201], 0
	v_mfma_f32_16x16x32_bf16 v[32:35], v[152:155], v[208:211], v[32:35]
	v_mfma_f32_16x16x32_bf16 v[12:15], v[174:177], v[198:201], 0
	v_mfma_f32_16x16x32_bf16 v[12:15], v[178:181], v[208:211], v[12:15]
	v_mfma_f32_16x16x32_bf16 v[24:27], v[132:135], v[212:215], 0
	v_mfma_f32_16x16x32_bf16 v[24:27], v[136:139], v[216:219], v[24:27]
	v_mfma_f32_16x16x32_bf16 v[8:11], v[156:159], v[212:215], 0
	v_mfma_f32_16x16x32_bf16 v[8:11], v[170:173], v[216:219], v[8:11]
	v_mfma_f32_16x16x32_bf16 v[16:19], v[148:151], v[212:215], 0
	v_mfma_f32_16x16x32_bf16 v[16:19], v[152:155], v[216:219], v[16:19]
	v_mfma_f32_16x16x32_bf16 v[4:7], v[174:177], v[212:215], 0
	v_mfma_f32_16x16x32_bf16 v[4:7], v[178:181], v[216:219], v[4:7]
	s_setprio 0
	s_barrier
	s_sleep 1
	s_add_i32 s70, 0, 0x18000
	s_add_i32 s71, 0, 0x1c000
	s_add_u32 s42, s42, 0x80000
	s_addc_u32 s43, s43, 0
	s_mov_b32 m0, s54
	v_lshl_add_u64 v[220:221], s[42:43], 0, v[0:1]
	global_load_lds_dwordx4 v[220:221], off
	v_lshl_add_u64 v[220:221], s[42:43], 0, v[140:141]
	s_mov_b32 m0, s55
	s_nop 0
	global_load_lds_dwordx4 v[220:221], off
	v_add_u32_e32 v152, s70, v163
	v_add_u32_e32 v178, s71, v163
	ds_read_b128 v[132:135], v152
	ds_read_b128 v[136:139], v152 offset:1024
	ds_read_b128 v[148:151], v152 offset:2048
	ds_read_b128 v[152:155], v152 offset:3072
	ds_read_b128 v[156:159], v178
	ds_read_b128 v[170:173], v178 offset:1024
	ds_read_b128 v[174:177], v178 offset:2048
	ds_read_b128 v[178:181], v178 offset:3072
	ds_read_b128 v[182:185], v167 offset:32768
	ds_read_b128 v[186:189], v167 offset:33792
	ds_read_b128 v[190:193], v167 offset:34816
	ds_read_b128 v[194:197], v167 offset:35840
	ds_read_b128 v[198:201], v167 offset:36864
	ds_read_b128 v[208:211], v167 offset:37888
	ds_read_b128 v[212:215], v167 offset:38912
	ds_read_b128 v[216:219], v167 offset:39936
	s_waitcnt vmcnt(8)
	s_waitcnt lgkmcnt(0)
	s_barrier
	s_setprio 1
	s_waitcnt lgkmcnt(0)
	v_mfma_f32_16x16x32_bf16 v[128:131], v[132:135], v[182:185], v[128:131]
	v_mfma_f32_16x16x32_bf16 v[128:131], v[136:139], v[186:189], v[128:131]
	v_mfma_f32_16x16x32_bf16 v[116:119], v[156:159], v[182:185], v[116:119]
	v_mfma_f32_16x16x32_bf16 v[116:119], v[170:173], v[186:189], v[116:119]
	v_mfma_f32_16x16x32_bf16 v[124:127], v[148:151], v[182:185], v[124:127]
	v_mfma_f32_16x16x32_bf16 v[124:127], v[152:155], v[186:189], v[124:127]
	v_mfma_f32_16x16x32_bf16 v[108:111], v[174:177], v[182:185], v[108:111]
	v_mfma_f32_16x16x32_bf16 v[108:111], v[178:181], v[186:189], v[108:111]
	v_mfma_f32_16x16x32_bf16 v[120:123], v[132:135], v[190:193], v[120:123]
	v_mfma_f32_16x16x32_bf16 v[120:123], v[136:139], v[194:197], v[120:123]
	v_mfma_f32_16x16x32_bf16 v[100:103], v[156:159], v[190:193], v[100:103]
	v_mfma_f32_16x16x32_bf16 v[100:103], v[170:173], v[194:197], v[100:103]
	v_mfma_f32_16x16x32_bf16 v[112:115], v[148:151], v[190:193], v[112:115]
	v_mfma_f32_16x16x32_bf16 v[112:115], v[152:155], v[194:197], v[112:115]
	v_mfma_f32_16x16x32_bf16 v[92:95], v[174:177], v[190:193], v[92:95]
	v_mfma_f32_16x16x32_bf16 v[92:95], v[178:181], v[194:197], v[92:95]
	v_mfma_f32_16x16x32_bf16 v[104:107], v[132:135], v[198:201], v[104:107]
	v_mfma_f32_16x16x32_bf16 v[104:107], v[136:139], v[208:211], v[104:107]
	v_mfma_f32_16x16x32_bf16 v[84:87], v[156:159], v[198:201], v[84:87]
	v_mfma_f32_16x16x32_bf16 v[84:87], v[170:173], v[208:211], v[84:87]
	v_mfma_f32_16x16x32_bf16 v[96:99], v[148:151], v[198:201], v[96:99]
	v_mfma_f32_16x16x32_bf16 v[96:99], v[152:155], v[208:211], v[96:99]
	v_mfma_f32_16x16x32_bf16 v[76:79], v[174:177], v[198:201], v[76:79]
	v_mfma_f32_16x16x32_bf16 v[76:79], v[178:181], v[208:211], v[76:79]
	v_mfma_f32_16x16x32_bf16 v[88:91], v[132:135], v[212:215], v[88:91]
	v_mfma_f32_16x16x32_bf16 v[88:91], v[136:139], v[216:219], v[88:91]
	v_mfma_f32_16x16x32_bf16 v[72:75], v[156:159], v[212:215], v[72:75]
	v_mfma_f32_16x16x32_bf16 v[72:75], v[170:173], v[216:219], v[72:75]
	v_mfma_f32_16x16x32_bf16 v[80:83], v[148:151], v[212:215], v[80:83]
	v_mfma_f32_16x16x32_bf16 v[80:83], v[152:155], v[216:219], v[80:83]
	v_mfma_f32_16x16x32_bf16 v[68:71], v[174:177], v[212:215], v[68:71]
	v_mfma_f32_16x16x32_bf16 v[68:71], v[178:181], v[216:219], v[68:71]
	s_setprio 0
	s_barrier
	s_sleep 2
	s_add_i32 s42, s70, s0
	v_lshl_add_u64 v[160:161], v[160:161], 0, s[66:67]
	s_mov_b32 m0, s42
	ds_read_b128 v[182:185], v167 offset:49152
	ds_read_b128 v[186:189], v167 offset:50176
	ds_read_b128 v[190:193], v167 offset:51200
	ds_read_b128 v[194:197], v167 offset:52224
	ds_read_b128 v[198:201], v167 offset:53248
	ds_read_b128 v[208:211], v167 offset:54272
	ds_read_b128 v[212:215], v167 offset:55296
	ds_read_b128 v[216:219], v167 offset:56320
	global_load_lds_dwordx4 v[160:161], off
	s_add_i32 m0, s42, 0x2000
	s_add_u32 s30, s30, 0x80080
	v_lshl_add_u64 v[160:161], v[202:203], 0, s[66:67]
	s_addc_u32 s31, s31, 0
	s_add_i32 s42, s71, s0
	global_load_lds_dwordx4 v[160:161], off
	v_lshl_add_u64 v[160:161], s[30:31], 0, v[2:3]
	s_mov_b32 m0, s42
	s_nop 0
	global_load_lds_dwordx4 v[160:161], off
	v_lshl_add_u64 v[160:161], s[30:31], 0, v[142:143]
	s_add_i32 m0, s42, 0x2000
	s_nop 0
	global_load_lds_dwordx4 v[160:161], off
	v_lshl_add_u64 v[160:161], v[204:205], 0, s[66:67]
	s_mov_b32 m0, s60
	s_nop 0
	global_load_lds_dwordx4 v[160:161], off
	v_lshl_add_u64 v[160:161], v[206:207], 0, s[66:67]
	s_mov_b32 m0, s64
	s_nop 0
	global_load_lds_dwordx4 v[160:161], off
	s_waitcnt vmcnt(8)
	s_waitcnt lgkmcnt(0)
	s_barrier
	s_setprio 1
	s_waitcnt lgkmcnt(0)
	v_mfma_f32_16x16x32_bf16 v[64:67], v[132:135], v[182:185], v[64:67]
	v_mfma_f32_16x16x32_bf16 v[64:67], v[136:139], v[186:189], v[64:67]
	v_mfma_f32_16x16x32_bf16 v[52:55], v[156:159], v[182:185], v[52:55]
	v_mfma_f32_16x16x32_bf16 v[52:55], v[170:173], v[186:189], v[52:55]
	v_mfma_f32_16x16x32_bf16 v[60:63], v[148:151], v[182:185], v[60:63]
	v_mfma_f32_16x16x32_bf16 v[60:63], v[152:155], v[186:189], v[60:63]
	v_mfma_f32_16x16x32_bf16 v[44:47], v[174:177], v[182:185], v[44:47]
	v_mfma_f32_16x16x32_bf16 v[44:47], v[178:181], v[186:189], v[44:47]
	v_mfma_f32_16x16x32_bf16 v[56:59], v[132:135], v[190:193], v[56:59]
	v_mfma_f32_16x16x32_bf16 v[56:59], v[136:139], v[194:197], v[56:59]
	v_mfma_f32_16x16x32_bf16 v[36:39], v[156:159], v[190:193], v[36:39]
	v_mfma_f32_16x16x32_bf16 v[36:39], v[170:173], v[194:197], v[36:39]
	v_mfma_f32_16x16x32_bf16 v[48:51], v[148:151], v[190:193], v[48:51]
	v_mfma_f32_16x16x32_bf16 v[48:51], v[152:155], v[194:197], v[48:51]
	v_mfma_f32_16x16x32_bf16 v[28:31], v[174:177], v[190:193], v[28:31]
	v_mfma_f32_16x16x32_bf16 v[28:31], v[178:181], v[194:197], v[28:31]
	v_mfma_f32_16x16x32_bf16 v[40:43], v[132:135], v[198:201], v[40:43]
	v_mfma_f32_16x16x32_bf16 v[40:43], v[136:139], v[208:211], v[40:43]
	v_mfma_f32_16x16x32_bf16 v[20:23], v[156:159], v[198:201], v[20:23]
	v_mfma_f32_16x16x32_bf16 v[20:23], v[170:173], v[208:211], v[20:23]
	v_mfma_f32_16x16x32_bf16 v[32:35], v[148:151], v[198:201], v[32:35]
	v_mfma_f32_16x16x32_bf16 v[32:35], v[152:155], v[208:211], v[32:35]
	v_mfma_f32_16x16x32_bf16 v[12:15], v[174:177], v[198:201], v[12:15]
	v_mfma_f32_16x16x32_bf16 v[12:15], v[178:181], v[208:211], v[12:15]
	v_mfma_f32_16x16x32_bf16 v[24:27], v[132:135], v[212:215], v[24:27]
	v_mfma_f32_16x16x32_bf16 v[24:27], v[136:139], v[216:219], v[24:27]
	v_mfma_f32_16x16x32_bf16 v[8:11], v[156:159], v[212:215], v[8:11]
	v_mfma_f32_16x16x32_bf16 v[8:11], v[170:173], v[216:219], v[8:11]
	v_mfma_f32_16x16x32_bf16 v[16:19], v[148:151], v[212:215], v[16:19]
	v_mfma_f32_16x16x32_bf16 v[16:19], v[152:155], v[216:219], v[16:19]
	v_mfma_f32_16x16x32_bf16 v[4:7], v[174:177], v[212:215], v[4:7]
	v_mfma_f32_16x16x32_bf16 v[4:7], v[178:181], v[216:219], v[4:7]
	s_setprio 0
	s_barrier
	s_add_i32 s69, s69, 2
	s_add_u32 s28, s28, 0x100
	s_addc_u32 s29, s29, 0
	s_add_u32 s63, s63, 0x100
	s_addc_u32 s68, s68, 0
	s_cmp_gt_u32 s69, 29
.LBB0_430:
	s_sleep 1
	s_add_u32 s30, s28, 0xfff80080
	s_addc_u32 s31, s29, -1
	s_add_i32 s70, 0, 0x10000
	s_cmp_eq_u32 s69, 28
	s_cselect_b32 s43, s5, s31
	s_cselect_b32 s42, s23, s30
	s_cselect_b32 s31, s21, s68
	s_cselect_b32 s30, s62, s63
	s_add_i32 s73, 0, 0x14000
	s_waitcnt lgkmcnt(0)
	v_lshl_add_u64 v[160:161], s[28:29], 0, v[144:145]
	s_add_i32 m0, s15, 0xc000
	s_nop 0
	global_load_lds_dwordx4 v[160:161], off
	v_lshl_add_u64 v[160:161], s[28:29], 0, v[146:147]
	s_add_i32 m0, s15, 0xe000
	s_nop 0
	global_load_lds_dwordx4 v[160:161], off
	v_add_u32_e32 v152, s70, v163
	v_add_u32_e32 v160, s73, v163
	ds_read_b128 v[132:135], v152
	ds_read_b128 v[136:139], v152 offset:1024
	ds_read_b128 v[148:151], v152 offset:2048
	ds_read_b128 v[152:155], v152 offset:3072
	ds_read_b128 v[156:159], v160
	ds_read_b128 v[170:173], v160 offset:1024
	ds_read_b128 v[174:177], v160 offset:2048
	ds_read_b128 v[178:181], v160 offset:3072
	ds_read_b128 v[182:185], v167
	ds_read_b128 v[186:189], v167 offset:1024
	ds_read_b128 v[190:193], v167 offset:2048
	ds_read_b128 v[194:197], v167 offset:3072
	ds_read_b128 v[198:201], v167 offset:4096
	ds_read_b128 v[208:211], v167 offset:5120
	ds_read_b128 v[212:215], v167 offset:6144
	ds_read_b128 v[216:219], v167 offset:7168
	s_waitcnt vmcnt(8)
	s_waitcnt lgkmcnt(0)
	s_barrier
	s_setprio 1
	s_waitcnt lgkmcnt(0)
	v_mfma_f32_16x16x32_bf16 v[128:131], v[132:135], v[182:185], v[128:131]
	v_mfma_f32_16x16x32_bf16 v[128:131], v[136:139], v[186:189], v[128:131]
	v_mfma_f32_16x16x32_bf16 v[116:119], v[156:159], v[182:185], v[116:119]
	v_mfma_f32_16x16x32_bf16 v[116:119], v[170:173], v[186:189], v[116:119]
	v_mfma_f32_16x16x32_bf16 v[124:127], v[148:151], v[182:185], v[124:127]
	v_mfma_f32_16x16x32_bf16 v[124:127], v[152:155], v[186:189], v[124:127]
	v_mfma_f32_16x16x32_bf16 v[108:111], v[174:177], v[182:185], v[108:111]
	v_mfma_f32_16x16x32_bf16 v[108:111], v[178:181], v[186:189], v[108:111]
	v_mfma_f32_16x16x32_bf16 v[120:123], v[132:135], v[190:193], v[120:123]
	v_mfma_f32_16x16x32_bf16 v[120:123], v[136:139], v[194:197], v[120:123]
	v_mfma_f32_16x16x32_bf16 v[100:103], v[156:159], v[190:193], v[100:103]
	v_mfma_f32_16x16x32_bf16 v[100:103], v[170:173], v[194:197], v[100:103]
	v_mfma_f32_16x16x32_bf16 v[112:115], v[148:151], v[190:193], v[112:115]
	v_mfma_f32_16x16x32_bf16 v[112:115], v[152:155], v[194:197], v[112:115]
	v_mfma_f32_16x16x32_bf16 v[92:95], v[174:177], v[190:193], v[92:95]
	v_mfma_f32_16x16x32_bf16 v[92:95], v[178:181], v[194:197], v[92:95]
	v_mfma_f32_16x16x32_bf16 v[104:107], v[132:135], v[198:201], v[104:107]
	v_mfma_f32_16x16x32_bf16 v[104:107], v[136:139], v[208:211], v[104:107]
	v_mfma_f32_16x16x32_bf16 v[84:87], v[156:159], v[198:201], v[84:87]
	v_mfma_f32_16x16x32_bf16 v[84:87], v[170:173], v[208:211], v[84:87]
	v_mfma_f32_16x16x32_bf16 v[96:99], v[148:151], v[198:201], v[96:99]
	v_mfma_f32_16x16x32_bf16 v[96:99], v[152:155], v[208:211], v[96:99]
	v_mfma_f32_16x16x32_bf16 v[76:79], v[174:177], v[198:201], v[76:79]
	v_mfma_f32_16x16x32_bf16 v[76:79], v[178:181], v[208:211], v[76:79]
	v_mfma_f32_16x16x32_bf16 v[88:91], v[132:135], v[212:215], v[88:91]
	v_mfma_f32_16x16x32_bf16 v[88:91], v[136:139], v[216:219], v[88:91]
	v_mfma_f32_16x16x32_bf16 v[72:75], v[156:159], v[212:215], v[72:75]
	v_mfma_f32_16x16x32_bf16 v[72:75], v[170:173], v[216:219], v[72:75]
	v_mfma_f32_16x16x32_bf16 v[80:83], v[148:151], v[212:215], v[80:83]
	v_mfma_f32_16x16x32_bf16 v[80:83], v[152:155], v[216:219], v[80:83]
	v_mfma_f32_16x16x32_bf16 v[68:71], v[174:177], v[212:215], v[68:71]
	v_mfma_f32_16x16x32_bf16 v[68:71], v[178:181], v[216:219], v[68:71]
	s_setprio 0
	s_barrier
	s_sleep 2
	s_add_i32 s70, s70, s0
	v_lshl_add_u64 v[160:161], s[30:31], 0, v[2:3]
	s_mov_b32 m0, s70
	ds_read_b128 v[182:185], v167 offset:16384
	ds_read_b128 v[186:189], v167 offset:17408
	ds_read_b128 v[190:193], v167 offset:18432
	ds_read_b128 v[194:197], v167 offset:19456
	ds_read_b128 v[198:201], v167 offset:20480
	ds_read_b128 v[208:211], v167 offset:21504
	ds_read_b128 v[212:215], v167 offset:22528
	ds_read_b128 v[216:219], v167 offset:23552
	global_load_lds_dwordx4 v[160:161], off
	s_add_i32 m0, s70, 0x2000
	s_add_u32 s70, s30, 0x80000
	v_lshl_add_u64 v[202:203], s[30:31], 0, v[142:143]
	s_addc_u32 s71, s31, 0
	s_add_i32 s73, s73, s0
	global_load_lds_dwordx4 v[202:203], off
	v_lshl_add_u64 v[204:205], s[70:71], 0, v[2:3]
	s_mov_b32 m0, s73
	v_lshl_add_u64 v[206:207], s[42:43], 0, v[140:141]
	global_load_lds_dwordx4 v[204:205], off
	v_lshl_add_u64 v[204:205], s[70:71], 0, v[142:143]
	s_add_i32 m0, s73, 0x2000
	s_nop 0
	global_load_lds_dwordx4 v[204:205], off
	v_lshl_add_u64 v[204:205], s[42:43], 0, v[0:1]
	s_mov_b32 m0, s15
	s_nop 0
	global_load_lds_dwordx4 v[204:205], off
	s_mov_b32 m0, s53
	s_nop 0
	global_load_lds_dwordx4 v[206:207], off
	s_waitcnt vmcnt(8)
	s_waitcnt lgkmcnt(0)
	s_barrier
	s_setprio 1
	s_waitcnt lgkmcnt(0)
	v_mfma_f32_16x16x32_bf16 v[64:67], v[132:135], v[182:185], v[64:67]
	v_mfma_f32_16x16x32_bf16 v[64:67], v[136:139], v[186:189], v[64:67]
	v_mfma_f32_16x16x32_bf16 v[52:55], v[156:159], v[182:185], v[52:55]
	v_mfma_f32_16x16x32_bf16 v[52:55], v[170:173], v[186:189], v[52:55]
	v_mfma_f32_16x16x32_bf16 v[60:63], v[148:151], v[182:185], v[60:63]
	v_mfma_f32_16x16x32_bf16 v[60:63], v[152:155], v[186:189], v[60:63]
	v_mfma_f32_16x16x32_bf16 v[44:47], v[174:177], v[182:185], v[44:47]
	v_mfma_f32_16x16x32_bf16 v[44:47], v[178:181], v[186:189], v[44:47]
	v_mfma_f32_16x16x32_bf16 v[56:59], v[132:135], v[190:193], v[56:59]
	v_mfma_f32_16x16x32_bf16 v[56:59], v[136:139], v[194:197], v[56:59]
	v_mfma_f32_16x16x32_bf16 v[36:39], v[156:159], v[190:193], v[36:39]
	v_mfma_f32_16x16x32_bf16 v[36:39], v[170:173], v[194:197], v[36:39]
	v_mfma_f32_16x16x32_bf16 v[48:51], v[148:151], v[190:193], v[48:51]
	v_mfma_f32_16x16x32_bf16 v[48:51], v[152:155], v[194:197], v[48:51]
	v_mfma_f32_16x16x32_bf16 v[28:31], v[174:177], v[190:193], v[28:31]
	v_mfma_f32_16x16x32_bf16 v[28:31], v[178:181], v[194:197], v[28:31]
	v_mfma_f32_16x16x32_bf16 v[40:43], v[132:135], v[198:201], v[40:43]
	v_mfma_f32_16x16x32_bf16 v[40:43], v[136:139], v[208:211], v[40:43]
	v_mfma_f32_16x16x32_bf16 v[20:23], v[156:159], v[198:201], v[20:23]
	v_mfma_f32_16x16x32_bf16 v[20:23], v[170:173], v[208:211], v[20:23]
	v_mfma_f32_16x16x32_bf16 v[32:35], v[148:151], v[198:201], v[32:35]
	v_mfma_f32_16x16x32_bf16 v[32:35], v[152:155], v[208:211], v[32:35]
	v_mfma_f32_16x16x32_bf16 v[12:15], v[174:177], v[198:201], v[12:15]
	v_mfma_f32_16x16x32_bf16 v[12:15], v[178:181], v[208:211], v[12:15]
	v_mfma_f32_16x16x32_bf16 v[24:27], v[132:135], v[212:215], v[24:27]
	v_mfma_f32_16x16x32_bf16 v[24:27], v[136:139], v[216:219], v[24:27]
	v_mfma_f32_16x16x32_bf16 v[8:11], v[156:159], v[212:215], v[8:11]
	v_mfma_f32_16x16x32_bf16 v[8:11], v[170:173], v[216:219], v[8:11]
	v_mfma_f32_16x16x32_bf16 v[16:19], v[148:151], v[212:215], v[16:19]
	v_mfma_f32_16x16x32_bf16 v[16:19], v[152:155], v[216:219], v[16:19]
	v_mfma_f32_16x16x32_bf16 v[4:7], v[174:177], v[212:215], v[4:7]
	v_mfma_f32_16x16x32_bf16 v[4:7], v[178:181], v[216:219], v[4:7]
	s_setprio 0
	s_barrier
	s_sleep 1
	s_add_i32 s70, 0, 0x18000
	s_add_i32 s71, 0, 0x1c000
	s_add_u32 s42, s42, 0x80000
	s_addc_u32 s43, s43, 0
	s_mov_b32 m0, s54
	v_lshl_add_u64 v[220:221], s[42:43], 0, v[0:1]
	global_load_lds_dwordx4 v[220:221], off
	v_lshl_add_u64 v[220:221], s[42:43], 0, v[140:141]
	s_mov_b32 m0, s55
	s_nop 0
	global_load_lds_dwordx4 v[220:221], off
	v_add_u32_e32 v152, s70, v163
	v_add_u32_e32 v178, s71, v163
	ds_read_b128 v[132:135], v152
	ds_read_b128 v[136:139], v152 offset:1024
	ds_read_b128 v[148:151], v152 offset:2048
	ds_read_b128 v[152:155], v152 offset:3072
	ds_read_b128 v[156:159], v178
	ds_read_b128 v[170:173], v178 offset:1024
	ds_read_b128 v[174:177], v178 offset:2048
	ds_read_b128 v[178:181], v178 offset:3072
	ds_read_b128 v[182:185], v167 offset:32768
	ds_read_b128 v[186:189], v167 offset:33792
	ds_read_b128 v[190:193], v167 offset:34816
	ds_read_b128 v[194:197], v167 offset:35840
	ds_read_b128 v[198:201], v167 offset:36864
	ds_read_b128 v[208:211], v167 offset:37888
	ds_read_b128 v[212:215], v167 offset:38912
	ds_read_b128 v[216:219], v167 offset:39936
	s_waitcnt vmcnt(8)
	s_waitcnt lgkmcnt(0)
	s_barrier
	s_setprio 1
	s_waitcnt lgkmcnt(0)
	v_mfma_f32_16x16x32_bf16 v[128:131], v[132:135], v[182:185], v[128:131]
	v_mfma_f32_16x16x32_bf16 v[128:131], v[136:139], v[186:189], v[128:131]
	v_mfma_f32_16x16x32_bf16 v[116:119], v[156:159], v[182:185], v[116:119]
	v_mfma_f32_16x16x32_bf16 v[116:119], v[170:173], v[186:189], v[116:119]
	v_mfma_f32_16x16x32_bf16 v[124:127], v[148:151], v[182:185], v[124:127]
	v_mfma_f32_16x16x32_bf16 v[124:127], v[152:155], v[186:189], v[124:127]
	v_mfma_f32_16x16x32_bf16 v[108:111], v[174:177], v[182:185], v[108:111]
	v_mfma_f32_16x16x32_bf16 v[108:111], v[178:181], v[186:189], v[108:111]
	v_mfma_f32_16x16x32_bf16 v[120:123], v[132:135], v[190:193], v[120:123]
	v_mfma_f32_16x16x32_bf16 v[120:123], v[136:139], v[194:197], v[120:123]
	v_mfma_f32_16x16x32_bf16 v[100:103], v[156:159], v[190:193], v[100:103]
	v_mfma_f32_16x16x32_bf16 v[100:103], v[170:173], v[194:197], v[100:103]
	v_mfma_f32_16x16x32_bf16 v[112:115], v[148:151], v[190:193], v[112:115]
	v_mfma_f32_16x16x32_bf16 v[112:115], v[152:155], v[194:197], v[112:115]
	v_mfma_f32_16x16x32_bf16 v[92:95], v[174:177], v[190:193], v[92:95]
	v_mfma_f32_16x16x32_bf16 v[92:95], v[178:181], v[194:197], v[92:95]
	v_mfma_f32_16x16x32_bf16 v[104:107], v[132:135], v[198:201], v[104:107]
	v_mfma_f32_16x16x32_bf16 v[104:107], v[136:139], v[208:211], v[104:107]
	v_mfma_f32_16x16x32_bf16 v[84:87], v[156:159], v[198:201], v[84:87]
	v_mfma_f32_16x16x32_bf16 v[84:87], v[170:173], v[208:211], v[84:87]
	v_mfma_f32_16x16x32_bf16 v[96:99], v[148:151], v[198:201], v[96:99]
	v_mfma_f32_16x16x32_bf16 v[96:99], v[152:155], v[208:211], v[96:99]
	v_mfma_f32_16x16x32_bf16 v[76:79], v[174:177], v[198:201], v[76:79]
	v_mfma_f32_16x16x32_bf16 v[76:79], v[178:181], v[208:211], v[76:79]
	v_mfma_f32_16x16x32_bf16 v[88:91], v[132:135], v[212:215], v[88:91]
	v_mfma_f32_16x16x32_bf16 v[88:91], v[136:139], v[216:219], v[88:91]
	v_mfma_f32_16x16x32_bf16 v[72:75], v[156:159], v[212:215], v[72:75]
	v_mfma_f32_16x16x32_bf16 v[72:75], v[170:173], v[216:219], v[72:75]
	v_mfma_f32_16x16x32_bf16 v[80:83], v[148:151], v[212:215], v[80:83]
	v_mfma_f32_16x16x32_bf16 v[80:83], v[152:155], v[216:219], v[80:83]
	v_mfma_f32_16x16x32_bf16 v[68:71], v[174:177], v[212:215], v[68:71]
	v_mfma_f32_16x16x32_bf16 v[68:71], v[178:181], v[216:219], v[68:71]
	s_setprio 0
	s_barrier
	s_sleep 2
	s_add_i32 s42, s70, s0
	v_lshl_add_u64 v[160:161], v[160:161], 0, s[66:67]
	s_mov_b32 m0, s42
	ds_read_b128 v[182:185], v167 offset:49152
	ds_read_b128 v[186:189], v167 offset:50176
	ds_read_b128 v[190:193], v167 offset:51200
	ds_read_b128 v[194:197], v167 offset:52224
	ds_read_b128 v[198:201], v167 offset:53248
	ds_read_b128 v[208:211], v167 offset:54272
	ds_read_b128 v[212:215], v167 offset:55296
	ds_read_b128 v[216:219], v167 offset:56320
	global_load_lds_dwordx4 v[160:161], off
	s_add_i32 m0, s42, 0x2000
	s_add_u32 s30, s30, 0x80080
	v_lshl_add_u64 v[160:161], v[202:203], 0, s[66:67]
	s_addc_u32 s31, s31, 0
	s_add_i32 s42, s71, s0
	global_load_lds_dwordx4 v[160:161], off
	v_lshl_add_u64 v[160:161], s[30:31], 0, v[2:3]
	s_mov_b32 m0, s42
	s_nop 0
	global_load_lds_dwordx4 v[160:161], off
	v_lshl_add_u64 v[160:161], s[30:31], 0, v[142:143]
	s_add_i32 m0, s42, 0x2000
	s_nop 0
	global_load_lds_dwordx4 v[160:161], off
	v_lshl_add_u64 v[160:161], v[204:205], 0, s[66:67]
	s_mov_b32 m0, s60
	s_nop 0
	global_load_lds_dwordx4 v[160:161], off
	v_lshl_add_u64 v[160:161], v[206:207], 0, s[66:67]
	s_mov_b32 m0, s64
	s_nop 0
	global_load_lds_dwordx4 v[160:161], off
	s_waitcnt vmcnt(8)
	s_waitcnt lgkmcnt(0)
	s_barrier
	s_setprio 1
	s_waitcnt lgkmcnt(0)
	v_mfma_f32_16x16x32_bf16 v[64:67], v[132:135], v[182:185], v[64:67]
	v_mfma_f32_16x16x32_bf16 v[64:67], v[136:139], v[186:189], v[64:67]
	v_mfma_f32_16x16x32_bf16 v[52:55], v[156:159], v[182:185], v[52:55]
	v_mfma_f32_16x16x32_bf16 v[52:55], v[170:173], v[186:189], v[52:55]
	v_mfma_f32_16x16x32_bf16 v[60:63], v[148:151], v[182:185], v[60:63]
	v_mfma_f32_16x16x32_bf16 v[60:63], v[152:155], v[186:189], v[60:63]
	v_mfma_f32_16x16x32_bf16 v[44:47], v[174:177], v[182:185], v[44:47]
	v_mfma_f32_16x16x32_bf16 v[44:47], v[178:181], v[186:189], v[44:47]
	v_mfma_f32_16x16x32_bf16 v[56:59], v[132:135], v[190:193], v[56:59]
	v_mfma_f32_16x16x32_bf16 v[56:59], v[136:139], v[194:197], v[56:59]
	v_mfma_f32_16x16x32_bf16 v[36:39], v[156:159], v[190:193], v[36:39]
	v_mfma_f32_16x16x32_bf16 v[36:39], v[170:173], v[194:197], v[36:39]
	v_mfma_f32_16x16x32_bf16 v[48:51], v[148:151], v[190:193], v[48:51]
	v_mfma_f32_16x16x32_bf16 v[48:51], v[152:155], v[194:197], v[48:51]
	v_mfma_f32_16x16x32_bf16 v[28:31], v[174:177], v[190:193], v[28:31]
	v_mfma_f32_16x16x32_bf16 v[28:31], v[178:181], v[194:197], v[28:31]
	v_mfma_f32_16x16x32_bf16 v[40:43], v[132:135], v[198:201], v[40:43]
	v_mfma_f32_16x16x32_bf16 v[40:43], v[136:139], v[208:211], v[40:43]
	v_mfma_f32_16x16x32_bf16 v[20:23], v[156:159], v[198:201], v[20:23]
	v_mfma_f32_16x16x32_bf16 v[20:23], v[170:173], v[208:211], v[20:23]
	v_mfma_f32_16x16x32_bf16 v[32:35], v[148:151], v[198:201], v[32:35]
	v_mfma_f32_16x16x32_bf16 v[32:35], v[152:155], v[208:211], v[32:35]
	v_mfma_f32_16x16x32_bf16 v[12:15], v[174:177], v[198:201], v[12:15]
	v_mfma_f32_16x16x32_bf16 v[12:15], v[178:181], v[208:211], v[12:15]
	v_mfma_f32_16x16x32_bf16 v[24:27], v[132:135], v[212:215], v[24:27]
	v_mfma_f32_16x16x32_bf16 v[24:27], v[136:139], v[216:219], v[24:27]
	v_mfma_f32_16x16x32_bf16 v[8:11], v[156:159], v[212:215], v[8:11]
	v_mfma_f32_16x16x32_bf16 v[8:11], v[170:173], v[216:219], v[8:11]
	v_mfma_f32_16x16x32_bf16 v[16:19], v[148:151], v[212:215], v[16:19]
	v_mfma_f32_16x16x32_bf16 v[16:19], v[152:155], v[216:219], v[16:19]
	v_mfma_f32_16x16x32_bf16 v[4:7], v[174:177], v[212:215], v[4:7]
	v_mfma_f32_16x16x32_bf16 v[4:7], v[178:181], v[216:219], v[4:7]
	s_setprio 0
	s_barrier
	s_add_i32 s69, s69, 2
	s_add_u32 s28, s28, 0x100
	s_addc_u32 s29, s29, 0
	s_add_u32 s63, s63, 0x100
	s_addc_u32 s68, s68, 0
	s_cmp_gt_u32 s69, 29
	s_cbranch_scc0 .LBB0_430
	s_and_b64 vcc, exec, s[8:9]
	s_cbranch_vccz .LBB0_433
	s_barrier

.LBB0_494:
	s_ashr_i32 s15, s14, 31
	s_lshl_b64 s[16:17], s[14:15], 20
	s_add_u32 s16, s27, s16
	s_addc_u32 s17, s28, s17
	s_and_b64 s[18:19], s[38:39], exec
	s_cselect_b32 s15, s17, s21
	s_cselect_b32 s43, s16, s20
	s_ashr_i32 s11, s10, 31
	s_lshl_b64 s[18:19], s[10:11], 20
	s_add_u32 s18, s29, s18
	s_addc_u32 s19, s30, s19
	s_and_b64 s[24:25], s[38:39], exec
	s_cselect_b32 s11, s19, s23
	s_cselect_b32 s44, s18, s22
	s_add_u32 s20, s20, 0x80080
	s_addc_u32 s21, s21, 0
	s_add_u32 s45, s22, 0x100
	s_addc_u32 s46, s23, 0
	s_mov_b32 s47, -2
	s_sleep 1
	s_add_u32 s22, s20, 0xfff80080
	s_addc_u32 s23, s21, -1
	s_add_i32 s48, 0, 0x10000
	s_cmp_eq_u32 s47, 28
	s_cselect_b32 s25, s15, s23
	s_cselect_b32 s24, s43, s22
	s_cselect_b32 s23, s11, s46
	s_cselect_b32 s22, s44, s45
	s_add_i32 s50, 0, 0x14000
	s_waitcnt lgkmcnt(0)
	v_lshl_add_u64 v[204:205], s[20:21], 0, v[132:133]
	s_add_i32 m0, s31, 0xc000
	s_nop 0
	global_load_lds_dwordx4 v[204:205], off
	v_lshl_add_u64 v[204:205], s[20:21], 0, v[134:135]
	s_add_i32 m0, s31, 0xe000
	s_nop 0
	global_load_lds_dwordx4 v[204:205], off
	v_add_u32_e32 v152, s48, v137
	v_add_u32_e32 v168, s50, v137
	ds_read_b128 v[140:143], v152
	ds_read_b128 v[144:147], v152 offset:1024
	ds_read_b128 v[148:151], v152 offset:2048
	ds_read_b128 v[152:155], v152 offset:3072
	ds_read_b128 v[156:159], v168
	ds_read_b128 v[160:163], v168 offset:1024
	ds_read_b128 v[164:167], v168 offset:2048
	ds_read_b128 v[168:171], v168 offset:3072
	ds_read_b128 v[172:175], v139
	ds_read_b128 v[176:179], v139 offset:1024
	ds_read_b128 v[180:183], v139 offset:2048
	ds_read_b128 v[184:187], v139 offset:3072
	ds_read_b128 v[188:191], v139 offset:4096
	ds_read_b128 v[192:195], v139 offset:5120
	ds_read_b128 v[196:199], v139 offset:6144
	ds_read_b128 v[200:203], v139 offset:7168
	s_waitcnt vmcnt(8)
	s_waitcnt lgkmcnt(0)
	s_barrier
	s_setprio 1
	s_waitcnt lgkmcnt(0)
	v_mfma_f32_16x16x32_bf16 v[128:131], v[140:143], v[172:175], 0
	v_mfma_f32_16x16x32_bf16 v[128:131], v[144:147], v[176:179], v[128:131]
	v_mfma_f32_16x16x32_bf16 v[112:115], v[156:159], v[172:175], 0
	v_mfma_f32_16x16x32_bf16 v[112:115], v[160:163], v[176:179], v[112:115]
	v_mfma_f32_16x16x32_bf16 v[124:127], v[148:151], v[172:175], 0
	v_mfma_f32_16x16x32_bf16 v[124:127], v[152:155], v[176:179], v[124:127]
	v_mfma_f32_16x16x32_bf16 v[104:107], v[164:167], v[172:175], 0
	v_mfma_f32_16x16x32_bf16 v[104:107], v[168:171], v[176:179], v[104:107]
	v_mfma_f32_16x16x32_bf16 v[120:123], v[140:143], v[180:183], 0
	v_mfma_f32_16x16x32_bf16 v[120:123], v[144:147], v[184:187], v[120:123]
	v_mfma_f32_16x16x32_bf16 v[96:99], v[156:159], v[180:183], 0
	v_mfma_f32_16x16x32_bf16 v[96:99], v[160:163], v[184:187], v[96:99]
	v_mfma_f32_16x16x32_bf16 v[116:119], v[148:151], v[180:183], 0
	v_mfma_f32_16x16x32_bf16 v[116:119], v[152:155], v[184:187], v[116:119]
	v_mfma_f32_16x16x32_bf16 v[88:91], v[164:167], v[180:183], 0
	v_mfma_f32_16x16x32_bf16 v[88:91], v[168:171], v[184:187], v[88:91]
	v_mfma_f32_16x16x32_bf16 v[108:111], v[140:143], v[188:191], 0
	v_mfma_f32_16x16x32_bf16 v[108:111], v[144:147], v[192:195], v[108:111]
	v_mfma_f32_16x16x32_bf16 v[80:83], v[156:159], v[188:191], 0
	v_mfma_f32_16x16x32_bf16 v[80:83], v[160:163], v[192:195], v[80:83]
	v_mfma_f32_16x16x32_bf16 v[100:103], v[148:151], v[188:191], 0
	v_mfma_f32_16x16x32_bf16 v[100:103], v[152:155], v[192:195], v[100:103]
	v_mfma_f32_16x16x32_bf16 v[76:79], v[164:167], v[188:191], 0
	v_mfma_f32_16x16x32_bf16 v[76:79], v[168:171], v[192:195], v[76:79]
	v_mfma_f32_16x16x32_bf16 v[92:95], v[140:143], v[196:199], 0
	v_mfma_f32_16x16x32_bf16 v[92:95], v[144:147], v[200:203], v[92:95]
	v_mfma_f32_16x16x32_bf16 v[72:75], v[156:159], v[196:199], 0
	v_mfma_f32_16x16x32_bf16 v[72:75], v[160:163], v[200:203], v[72:75]
	v_mfma_f32_16x16x32_bf16 v[84:87], v[148:151], v[196:199], 0
	v_mfma_f32_16x16x32_bf16 v[84:87], v[152:155], v[200:203], v[84:87]
	v_mfma_f32_16x16x32_bf16 v[68:71], v[164:167], v[196:199], 0
	v_mfma_f32_16x16x32_bf16 v[68:71], v[168:171], v[200:203], v[68:71]
	s_setprio 0
	s_barrier
	s_sleep 2
	s_add_i32 s48, s48, s0
	v_lshl_add_u64 v[204:205], s[22:23], 0, v[2:3]
	s_mov_b32 m0, s48
	ds_read_b128 v[172:175], v139 offset:16384
	ds_read_b128 v[176:179], v139 offset:17408
	ds_read_b128 v[180:183], v139 offset:18432
	ds_read_b128 v[184:187], v139 offset:19456
	ds_read_b128 v[188:191], v139 offset:20480
	ds_read_b128 v[192:195], v139 offset:21504
	ds_read_b128 v[196:199], v139 offset:22528
	ds_read_b128 v[200:203], v139 offset:23552
	global_load_lds_dwordx4 v[204:205], off
	s_add_i32 m0, s48, 0x2000
	s_add_u32 s48, s22, 0x80000
	v_lshl_add_u64 v[206:207], s[22:23], 0, v[0:1]
	s_addc_u32 s49, s23, 0
	s_add_i32 s50, s50, s0
	global_load_lds_dwordx4 v[206:207], off
	v_lshl_add_u64 v[208:209], s[48:49], 0, v[2:3]
	s_mov_b32 m0, s50
	v_lshl_add_u64 v[210:211], s[24:25], 0, v[0:1]
	global_load_lds_dwordx4 v[208:209], off
	v_lshl_add_u64 v[208:209], s[48:49], 0, v[0:1]
	s_add_i32 m0, s50, 0x2000
	s_nop 0
	global_load_lds_dwordx4 v[208:209], off
	v_lshl_add_u64 v[208:209], s[24:25], 0, v[2:3]
	s_mov_b32 m0, s31
	s_nop 0
	global_load_lds_dwordx4 v[208:209], off
	s_mov_b32 m0, s40
	s_nop 0
	global_load_lds_dwordx4 v[210:211], off
	s_waitcnt vmcnt(8)
	s_waitcnt lgkmcnt(0)
	s_barrier
	s_setprio 1
	s_waitcnt lgkmcnt(0)
	v_mfma_f32_16x16x32_bf16 v[64:67], v[140:143], v[172:175], 0
	v_mfma_f32_16x16x32_bf16 v[64:67], v[144:147], v[176:179], v[64:67]
	v_mfma_f32_16x16x32_bf16 v[48:51], v[156:159], v[172:175], 0
	v_mfma_f32_16x16x32_bf16 v[48:51], v[160:163], v[176:179], v[48:51]
	v_mfma_f32_16x16x32_bf16 v[60:63], v[148:151], v[172:175], 0
	v_mfma_f32_16x16x32_bf16 v[60:63], v[152:155], v[176:179], v[60:63]
	v_mfma_f32_16x16x32_bf16 v[44:47], v[164:167], v[172:175], 0
	v_mfma_f32_16x16x32_bf16 v[44:47], v[168:171], v[176:179], v[44:47]
	v_mfma_f32_16x16x32_bf16 v[56:59], v[140:143], v[180:183], 0
	v_mfma_f32_16x16x32_bf16 v[56:59], v[144:147], v[184:187], v[56:59]
	v_mfma_f32_16x16x32_bf16 v[32:35], v[156:159], v[180:183], 0
	v_mfma_f32_16x16x32_bf16 v[32:35], v[160:163], v[184:187], v[32:35]
	v_mfma_f32_16x16x32_bf16 v[52:55], v[148:151], v[180:183], 0
	v_mfma_f32_16x16x32_bf16 v[52:55], v[152:155], v[184:187], v[52:55]
	v_mfma_f32_16x16x32_bf16 v[28:31], v[164:167], v[180:183], 0
	v_mfma_f32_16x16x32_bf16 v[28:31], v[168:171], v[184:187], v[28:31]
	v_mfma_f32_16x16x32_bf16 v[40:43], v[140:143], v[188:191], 0
	v_mfma_f32_16x16x32_bf16 v[40:43], v[144:147], v[192:195], v[40:43]
	v_mfma_f32_16x16x32_bf16 v[16:19], v[156:159], v[188:191], 0
	v_mfma_f32_16x16x32_bf16 v[16:19], v[160:163], v[192:195], v[16:19]
	v_mfma_f32_16x16x32_bf16 v[36:39], v[148:151], v[188:191], 0
	v_mfma_f32_16x16x32_bf16 v[36:39], v[152:155], v[192:195], v[36:39]
	v_mfma_f32_16x16x32_bf16 v[12:15], v[164:167], v[188:191], 0
	v_mfma_f32_16x16x32_bf16 v[12:15], v[168:171], v[192:195], v[12:15]
	v_mfma_f32_16x16x32_bf16 v[24:27], v[140:143], v[196:199], 0
	v_mfma_f32_16x16x32_bf16 v[24:27], v[144:147], v[200:203], v[24:27]
	v_mfma_f32_16x16x32_bf16 v[8:11], v[156:159], v[196:199], 0
	v_mfma_f32_16x16x32_bf16 v[8:11], v[160:163], v[200:203], v[8:11]
	v_mfma_f32_16x16x32_bf16 v[20:23], v[148:151], v[196:199], 0
	v_mfma_f32_16x16x32_bf16 v[20:23], v[152:155], v[200:203], v[20:23]
	v_mfma_f32_16x16x32_bf16 v[4:7], v[164:167], v[196:199], 0
	v_mfma_f32_16x16x32_bf16 v[4:7], v[168:171], v[200:203], v[4:7]
	s_setprio 0
	s_barrier
	s_sleep 1
	s_add_i32 s48, 0, 0x18000
	s_add_i32 s49, 0, 0x1c000
	s_add_u32 s24, s24, 0x80000
	s_addc_u32 s25, s25, 0
	s_mov_b32 m0, s41
	v_lshl_add_u64 v[212:213], s[24:25], 0, v[2:3]
	global_load_lds_dwordx4 v[212:213], off
	v_lshl_add_u64 v[212:213], s[24:25], 0, v[0:1]
	s_mov_b32 m0, s42
	s_nop 0
	global_load_lds_dwordx4 v[212:213], off
	v_add_u32_e32 v152, s48, v137
	v_add_u32_e32 v168, s49, v137
	ds_read_b128 v[140:143], v152
	ds_read_b128 v[144:147], v152 offset:1024
	ds_read_b128 v[148:151], v152 offset:2048
	ds_read_b128 v[152:155], v152 offset:3072
	ds_read_b128 v[156:159], v168
	ds_read_b128 v[160:163], v168 offset:1024
	ds_read_b128 v[164:167], v168 offset:2048
	ds_read_b128 v[168:171], v168 offset:3072
	ds_read_b128 v[172:175], v139 offset:32768
	ds_read_b128 v[176:179], v139 offset:33792
	ds_read_b128 v[180:183], v139 offset:34816
	ds_read_b128 v[184:187], v139 offset:35840
	ds_read_b128 v[188:191], v139 offset:36864
	ds_read_b128 v[192:195], v139 offset:37888
	ds_read_b128 v[196:199], v139 offset:38912
	ds_read_b128 v[200:203], v139 offset:39936
	s_waitcnt vmcnt(8)
	s_waitcnt lgkmcnt(0)
	s_barrier
	s_setprio 1
	s_waitcnt lgkmcnt(0)
	v_mfma_f32_16x16x32_bf16 v[128:131], v[140:143], v[172:175], v[128:131]
	v_mfma_f32_16x16x32_bf16 v[128:131], v[144:147], v[176:179], v[128:131]
	v_mfma_f32_16x16x32_bf16 v[112:115], v[156:159], v[172:175], v[112:115]
	v_mfma_f32_16x16x32_bf16 v[112:115], v[160:163], v[176:179], v[112:115]
	v_mfma_f32_16x16x32_bf16 v[124:127], v[148:151], v[172:175], v[124:127]
	v_mfma_f32_16x16x32_bf16 v[124:127], v[152:155], v[176:179], v[124:127]
	v_mfma_f32_16x16x32_bf16 v[104:107], v[164:167], v[172:175], v[104:107]
	v_mfma_f32_16x16x32_bf16 v[104:107], v[168:171], v[176:179], v[104:107]
	v_mfma_f32_16x16x32_bf16 v[120:123], v[140:143], v[180:183], v[120:123]
	v_mfma_f32_16x16x32_bf16 v[120:123], v[144:147], v[184:187], v[120:123]
	v_mfma_f32_16x16x32_bf16 v[96:99], v[156:159], v[180:183], v[96:99]
	v_mfma_f32_16x16x32_bf16 v[96:99], v[160:163], v[184:187], v[96:99]
	v_mfma_f32_16x16x32_bf16 v[116:119], v[148:151], v[180:183], v[116:119]
	v_mfma_f32_16x16x32_bf16 v[116:119], v[152:155], v[184:187], v[116:119]
	v_mfma_f32_16x16x32_bf16 v[88:91], v[164:167], v[180:183], v[88:91]
	v_mfma_f32_16x16x32_bf16 v[88:91], v[168:171], v[184:187], v[88:91]
	v_mfma_f32_16x16x32_bf16 v[108:111], v[140:143], v[188:191], v[108:111]
	v_mfma_f32_16x16x32_bf16 v[108:111], v[144:147], v[192:195], v[108:111]
	v_mfma_f32_16x16x32_bf16 v[80:83], v[156:159], v[188:191], v[80:83]
	v_mfma_f32_16x16x32_bf16 v[80:83], v[160:163], v[192:195], v[80:83]
	v_mfma_f32_16x16x32_bf16 v[100:103], v[148:151], v[188:191], v[100:103]
	v_mfma_f32_16x16x32_bf16 v[100:103], v[152:155], v[192:195], v[100:103]
	v_mfma_f32_16x16x32_bf16 v[76:79], v[164:167], v[188:191], v[76:79]
	v_mfma_f32_16x16x32_bf16 v[76:79], v[168:171], v[192:195], v[76:79]
	v_mfma_f32_16x16x32_bf16 v[92:95], v[140:143], v[196:199], v[92:95]
	v_mfma_f32_16x16x32_bf16 v[92:95], v[144:147], v[200:203], v[92:95]
	v_mfma_f32_16x16x32_bf16 v[72:75], v[156:159], v[196:199], v[72:75]
	v_mfma_f32_16x16x32_bf16 v[72:75], v[160:163], v[200:203], v[72:75]
	v_mfma_f32_16x16x32_bf16 v[84:87], v[148:151], v[196:199], v[84:87]
	v_mfma_f32_16x16x32_bf16 v[84:87], v[152:155], v[200:203], v[84:87]
	v_mfma_f32_16x16x32_bf16 v[68:71], v[164:167], v[196:199], v[68:71]
	v_mfma_f32_16x16x32_bf16 v[68:71], v[168:171], v[200:203], v[68:71]
	s_setprio 0
	s_barrier
	s_sleep 2
	s_add_i32 s24, s48, s0
	v_lshl_add_u64 v[204:205], v[204:205], 0, s[66:67]
	s_mov_b32 m0, s24
	ds_read_b128 v[172:175], v139 offset:49152
	ds_read_b128 v[176:179], v139 offset:50176
	ds_read_b128 v[180:183], v139 offset:51200
	ds_read_b128 v[184:187], v139 offset:52224
	ds_read_b128 v[188:191], v139 offset:53248
	ds_read_b128 v[192:195], v139 offset:54272
	ds_read_b128 v[196:199], v139 offset:55296
	ds_read_b128 v[200:203], v139 offset:56320
	global_load_lds_dwordx4 v[204:205], off
	s_add_i32 m0, s24, 0x2000
	s_add_u32 s22, s22, 0x80080
	v_lshl_add_u64 v[204:205], v[206:207], 0, s[66:67]
	s_addc_u32 s23, s23, 0
	s_add_i32 s24, s49, s0
	global_load_lds_dwordx4 v[204:205], off
	v_lshl_add_u64 v[204:205], s[22:23], 0, v[2:3]
	s_mov_b32 m0, s24
	s_nop 0
	global_load_lds_dwordx4 v[204:205], off
	v_lshl_add_u64 v[204:205], s[22:23], 0, v[0:1]
	s_add_i32 m0, s24, 0x2000
	s_nop 0
	global_load_lds_dwordx4 v[204:205], off
	v_lshl_add_u64 v[204:205], v[208:209], 0, s[66:67]
	s_mov_b32 m0, s1
	s_nop 0
	global_load_lds_dwordx4 v[204:205], off
	v_lshl_add_u64 v[204:205], v[210:211], 0, s[66:67]
	s_mov_b32 m0, s34
	s_nop 0
	global_load_lds_dwordx4 v[204:205], off
	s_waitcnt vmcnt(8)
	s_waitcnt lgkmcnt(0)
	s_barrier
	s_setprio 1
	s_waitcnt lgkmcnt(0)
	v_mfma_f32_16x16x32_bf16 v[64:67], v[140:143], v[172:175], v[64:67]
	v_mfma_f32_16x16x32_bf16 v[64:67], v[144:147], v[176:179], v[64:67]
	v_mfma_f32_16x16x32_bf16 v[48:51], v[156:159], v[172:175], v[48:51]
	v_mfma_f32_16x16x32_bf16 v[48:51], v[160:163], v[176:179], v[48:51]
	v_mfma_f32_16x16x32_bf16 v[60:63], v[148:151], v[172:175], v[60:63]
	v_mfma_f32_16x16x32_bf16 v[60:63], v[152:155], v[176:179], v[60:63]
	v_mfma_f32_16x16x32_bf16 v[44:47], v[164:167], v[172:175], v[44:47]
	v_mfma_f32_16x16x32_bf16 v[44:47], v[168:171], v[176:179], v[44:47]
	v_mfma_f32_16x16x32_bf16 v[56:59], v[140:143], v[180:183], v[56:59]
	v_mfma_f32_16x16x32_bf16 v[56:59], v[144:147], v[184:187], v[56:59]
	v_mfma_f32_16x16x32_bf16 v[32:35], v[156:159], v[180:183], v[32:35]
	v_mfma_f32_16x16x32_bf16 v[32:35], v[160:163], v[184:187], v[32:35]
	v_mfma_f32_16x16x32_bf16 v[52:55], v[148:151], v[180:183], v[52:55]
	v_mfma_f32_16x16x32_bf16 v[52:55], v[152:155], v[184:187], v[52:55]
	v_mfma_f32_16x16x32_bf16 v[28:31], v[164:167], v[180:183], v[28:31]
	v_mfma_f32_16x16x32_bf16 v[28:31], v[168:171], v[184:187], v[28:31]
	v_mfma_f32_16x16x32_bf16 v[40:43], v[140:143], v[188:191], v[40:43]
	v_mfma_f32_16x16x32_bf16 v[40:43], v[144:147], v[192:195], v[40:43]
	v_mfma_f32_16x16x32_bf16 v[16:19], v[156:159], v[188:191], v[16:19]
	v_mfma_f32_16x16x32_bf16 v[16:19], v[160:163], v[192:195], v[16:19]
	v_mfma_f32_16x16x32_bf16 v[36:39], v[148:151], v[188:191], v[36:39]
	v_mfma_f32_16x16x32_bf16 v[36:39], v[152:155], v[192:195], v[36:39]
	v_mfma_f32_16x16x32_bf16 v[12:15], v[164:167], v[188:191], v[12:15]
	v_mfma_f32_16x16x32_bf16 v[12:15], v[168:171], v[192:195], v[12:15]
	v_mfma_f32_16x16x32_bf16 v[24:27], v[140:143], v[196:199], v[24:27]
	v_mfma_f32_16x16x32_bf16 v[24:27], v[144:147], v[200:203], v[24:27]
	v_mfma_f32_16x16x32_bf16 v[8:11], v[156:159], v[196:199], v[8:11]
	v_mfma_f32_16x16x32_bf16 v[8:11], v[160:163], v[200:203], v[8:11]
	v_mfma_f32_16x16x32_bf16 v[20:23], v[148:151], v[196:199], v[20:23]
	v_mfma_f32_16x16x32_bf16 v[20:23], v[152:155], v[200:203], v[20:23]
	v_mfma_f32_16x16x32_bf16 v[4:7], v[164:167], v[196:199], v[4:7]
	v_mfma_f32_16x16x32_bf16 v[4:7], v[168:171], v[200:203], v[4:7]
	s_setprio 0
	s_barrier
	s_add_i32 s47, s47, 2
	s_add_u32 s20, s20, 0x100
	s_addc_u32 s21, s21, 0
	s_add_u32 s45, s45, 0x100
	s_addc_u32 s46, s46, 0
	s_cmp_gt_u32 s47, 29
.LBB0_495:
	s_sleep 1
	s_add_u32 s22, s20, 0xfff80080
	s_addc_u32 s23, s21, -1
	s_add_i32 s48, 0, 0x10000
	s_cmp_eq_u32 s47, 28
	s_cselect_b32 s25, s15, s23
	s_cselect_b32 s24, s43, s22
	s_cselect_b32 s23, s11, s46
	s_cselect_b32 s22, s44, s45
	s_add_i32 s50, 0, 0x14000
	s_waitcnt lgkmcnt(0)
	v_lshl_add_u64 v[204:205], s[20:21], 0, v[132:133]
	s_add_i32 m0, s31, 0xc000
	s_nop 0
	global_load_lds_dwordx4 v[204:205], off
	v_lshl_add_u64 v[204:205], s[20:21], 0, v[134:135]
	s_add_i32 m0, s31, 0xe000
	s_nop 0
	global_load_lds_dwordx4 v[204:205], off
	v_add_u32_e32 v152, s48, v137
	v_add_u32_e32 v168, s50, v137
	ds_read_b128 v[140:143], v152
	ds_read_b128 v[144:147], v152 offset:1024
	ds_read_b128 v[148:151], v152 offset:2048
	ds_read_b128 v[152:155], v152 offset:3072
	ds_read_b128 v[156:159], v168
	ds_read_b128 v[160:163], v168 offset:1024
	ds_read_b128 v[164:167], v168 offset:2048
	ds_read_b128 v[168:171], v168 offset:3072
	ds_read_b128 v[172:175], v139
	ds_read_b128 v[176:179], v139 offset:1024
	ds_read_b128 v[180:183], v139 offset:2048
	ds_read_b128 v[184:187], v139 offset:3072
	ds_read_b128 v[188:191], v139 offset:4096
	ds_read_b128 v[192:195], v139 offset:5120
	ds_read_b128 v[196:199], v139 offset:6144
	ds_read_b128 v[200:203], v139 offset:7168
	s_waitcnt vmcnt(8)
	s_waitcnt lgkmcnt(0)
	s_barrier
	s_setprio 1
	s_waitcnt lgkmcnt(0)
	v_mfma_f32_16x16x32_bf16 v[128:131], v[140:143], v[172:175], v[128:131]
	v_mfma_f32_16x16x32_bf16 v[128:131], v[144:147], v[176:179], v[128:131]
	v_mfma_f32_16x16x32_bf16 v[112:115], v[156:159], v[172:175], v[112:115]
	v_mfma_f32_16x16x32_bf16 v[112:115], v[160:163], v[176:179], v[112:115]
	v_mfma_f32_16x16x32_bf16 v[124:127], v[148:151], v[172:175], v[124:127]
	v_mfma_f32_16x16x32_bf16 v[124:127], v[152:155], v[176:179], v[124:127]
	v_mfma_f32_16x16x32_bf16 v[104:107], v[164:167], v[172:175], v[104:107]
	v_mfma_f32_16x16x32_bf16 v[104:107], v[168:171], v[176:179], v[104:107]
	v_mfma_f32_16x16x32_bf16 v[120:123], v[140:143], v[180:183], v[120:123]
	v_mfma_f32_16x16x32_bf16 v[120:123], v[144:147], v[184:187], v[120:123]
	v_mfma_f32_16x16x32_bf16 v[96:99], v[156:159], v[180:183], v[96:99]
	v_mfma_f32_16x16x32_bf16 v[96:99], v[160:163], v[184:187], v[96:99]
	v_mfma_f32_16x16x32_bf16 v[116:119], v[148:151], v[180:183], v[116:119]
	v_mfma_f32_16x16x32_bf16 v[116:119], v[152:155], v[184:187], v[116:119]
	v_mfma_f32_16x16x32_bf16 v[88:91], v[164:167], v[180:183], v[88:91]
	v_mfma_f32_16x16x32_bf16 v[88:91], v[168:171], v[184:187], v[88:91]
	v_mfma_f32_16x16x32_bf16 v[108:111], v[140:143], v[188:191], v[108:111]
	v_mfma_f32_16x16x32_bf16 v[108:111], v[144:147], v[192:195], v[108:111]
	v_mfma_f32_16x16x32_bf16 v[80:83], v[156:159], v[188:191], v[80:83]
	v_mfma_f32_16x16x32_bf16 v[80:83], v[160:163], v[192:195], v[80:83]
	v_mfma_f32_16x16x32_bf16 v[100:103], v[148:151], v[188:191], v[100:103]
	v_mfma_f32_16x16x32_bf16 v[100:103], v[152:155], v[192:195], v[100:103]
	v_mfma_f32_16x16x32_bf16 v[76:79], v[164:167], v[188:191], v[76:79]
	v_mfma_f32_16x16x32_bf16 v[76:79], v[168:171], v[192:195], v[76:79]
	v_mfma_f32_16x16x32_bf16 v[92:95], v[140:143], v[196:199], v[92:95]
	v_mfma_f32_16x16x32_bf16 v[92:95], v[144:147], v[200:203], v[92:95]
	v_mfma_f32_16x16x32_bf16 v[72:75], v[156:159], v[196:199], v[72:75]
	v_mfma_f32_16x16x32_bf16 v[72:75], v[160:163], v[200:203], v[72:75]
	v_mfma_f32_16x16x32_bf16 v[84:87], v[148:151], v[196:199], v[84:87]
	v_mfma_f32_16x16x32_bf16 v[84:87], v[152:155], v[200:203], v[84:87]
	v_mfma_f32_16x16x32_bf16 v[68:71], v[164:167], v[196:199], v[68:71]
	v_mfma_f32_16x16x32_bf16 v[68:71], v[168:171], v[200:203], v[68:71]
	s_setprio 0
	s_barrier
	s_sleep 2
	s_add_i32 s48, s48, s0
	v_lshl_add_u64 v[204:205], s[22:23], 0, v[2:3]
	s_mov_b32 m0, s48
	ds_read_b128 v[172:175], v139 offset:16384
	ds_read_b128 v[176:179], v139 offset:17408
	ds_read_b128 v[180:183], v139 offset:18432
	ds_read_b128 v[184:187], v139 offset:19456
	ds_read_b128 v[188:191], v139 offset:20480
	ds_read_b128 v[192:195], v139 offset:21504
	ds_read_b128 v[196:199], v139 offset:22528
	ds_read_b128 v[200:203], v139 offset:23552
	global_load_lds_dwordx4 v[204:205], off
	s_add_i32 m0, s48, 0x2000
	s_add_u32 s48, s22, 0x80000
	v_lshl_add_u64 v[206:207], s[22:23], 0, v[0:1]
	s_addc_u32 s49, s23, 0
	s_add_i32 s50, s50, s0
	global_load_lds_dwordx4 v[206:207], off
	v_lshl_add_u64 v[208:209], s[48:49], 0, v[2:3]
	s_mov_b32 m0, s50
	v_lshl_add_u64 v[210:211], s[24:25], 0, v[0:1]
	global_load_lds_dwordx4 v[208:209], off
	v_lshl_add_u64 v[208:209], s[48:49], 0, v[0:1]
	s_add_i32 m0, s50, 0x2000
	s_nop 0
	global_load_lds_dwordx4 v[208:209], off
	v_lshl_add_u64 v[208:209], s[24:25], 0, v[2:3]
	s_mov_b32 m0, s31
	s_nop 0
	global_load_lds_dwordx4 v[208:209], off
	s_mov_b32 m0, s40
	s_nop 0
	global_load_lds_dwordx4 v[210:211], off
	s_waitcnt vmcnt(8)
	s_waitcnt lgkmcnt(0)
	s_barrier
	s_setprio 1
	s_waitcnt lgkmcnt(0)
	v_mfma_f32_16x16x32_bf16 v[64:67], v[140:143], v[172:175], v[64:67]
	v_mfma_f32_16x16x32_bf16 v[64:67], v[144:147], v[176:179], v[64:67]
	v_mfma_f32_16x16x32_bf16 v[48:51], v[156:159], v[172:175], v[48:51]
	v_mfma_f32_16x16x32_bf16 v[48:51], v[160:163], v[176:179], v[48:51]
	v_mfma_f32_16x16x32_bf16 v[60:63], v[148:151], v[172:175], v[60:63]
	v_mfma_f32_16x16x32_bf16 v[60:63], v[152:155], v[176:179], v[60:63]
	v_mfma_f32_16x16x32_bf16 v[44:47], v[164:167], v[172:175], v[44:47]
	v_mfma_f32_16x16x32_bf16 v[44:47], v[168:171], v[176:179], v[44:47]
	v_mfma_f32_16x16x32_bf16 v[56:59], v[140:143], v[180:183], v[56:59]
	v_mfma_f32_16x16x32_bf16 v[56:59], v[144:147], v[184:187], v[56:59]
	v_mfma_f32_16x16x32_bf16 v[32:35], v[156:159], v[180:183], v[32:35]
	v_mfma_f32_16x16x32_bf16 v[32:35], v[160:163], v[184:187], v[32:35]
	v_mfma_f32_16x16x32_bf16 v[52:55], v[148:151], v[180:183], v[52:55]
	v_mfma_f32_16x16x32_bf16 v[52:55], v[152:155], v[184:187], v[52:55]
	v_mfma_f32_16x16x32_bf16 v[28:31], v[164:167], v[180:183], v[28:31]
	v_mfma_f32_16x16x32_bf16 v[28:31], v[168:171], v[184:187], v[28:31]
	v_mfma_f32_16x16x32_bf16 v[40:43], v[140:143], v[188:191], v[40:43]
	v_mfma_f32_16x16x32_bf16 v[40:43], v[144:147], v[192:195], v[40:43]
	v_mfma_f32_16x16x32_bf16 v[16:19], v[156:159], v[188:191], v[16:19]
	v_mfma_f32_16x16x32_bf16 v[16:19], v[160:163], v[192:195], v[16:19]
	v_mfma_f32_16x16x32_bf16 v[36:39], v[148:151], v[188:191], v[36:39]
	v_mfma_f32_16x16x32_bf16 v[36:39], v[152:155], v[192:195], v[36:39]
	v_mfma_f32_16x16x32_bf16 v[12:15], v[164:167], v[188:191], v[12:15]
	v_mfma_f32_16x16x32_bf16 v[12:15], v[168:171], v[192:195], v[12:15]
	v_mfma_f32_16x16x32_bf16 v[24:27], v[140:143], v[196:199], v[24:27]
	v_mfma_f32_16x16x32_bf16 v[24:27], v[144:147], v[200:203], v[24:27]
	v_mfma_f32_16x16x32_bf16 v[8:11], v[156:159], v[196:199], v[8:11]
	v_mfma_f32_16x16x32_bf16 v[8:11], v[160:163], v[200:203], v[8:11]
	v_mfma_f32_16x16x32_bf16 v[20:23], v[148:151], v[196:199], v[20:23]
	v_mfma_f32_16x16x32_bf16 v[20:23], v[152:155], v[200:203], v[20:23]
	v_mfma_f32_16x16x32_bf16 v[4:7], v[164:167], v[196:199], v[4:7]
	v_mfma_f32_16x16x32_bf16 v[4:7], v[168:171], v[200:203], v[4:7]
	s_setprio 0
	s_barrier
	s_sleep 1
	s_add_i32 s48, 0, 0x18000
	s_add_i32 s49, 0, 0x1c000
	s_add_u32 s24, s24, 0x80000
	s_addc_u32 s25, s25, 0
	s_mov_b32 m0, s41
	v_lshl_add_u64 v[212:213], s[24:25], 0, v[2:3]
	global_load_lds_dwordx4 v[212:213], off
	v_lshl_add_u64 v[212:213], s[24:25], 0, v[0:1]
	s_mov_b32 m0, s42
	s_nop 0
	global_load_lds_dwordx4 v[212:213], off
	v_add_u32_e32 v152, s48, v137
	v_add_u32_e32 v168, s49, v137
	ds_read_b128 v[140:143], v152
	ds_read_b128 v[144:147], v152 offset:1024
	ds_read_b128 v[148:151], v152 offset:2048
	ds_read_b128 v[152:155], v152 offset:3072
	ds_read_b128 v[156:159], v168
	ds_read_b128 v[160:163], v168 offset:1024
	ds_read_b128 v[164:167], v168 offset:2048
	ds_read_b128 v[168:171], v168 offset:3072
	ds_read_b128 v[172:175], v139 offset:32768
	ds_read_b128 v[176:179], v139 offset:33792
	ds_read_b128 v[180:183], v139 offset:34816
	ds_read_b128 v[184:187], v139 offset:35840
	ds_read_b128 v[188:191], v139 offset:36864
	ds_read_b128 v[192:195], v139 offset:37888
	ds_read_b128 v[196:199], v139 offset:38912
	ds_read_b128 v[200:203], v139 offset:39936
	s_waitcnt vmcnt(8)
	s_waitcnt lgkmcnt(0)
	s_barrier
	s_setprio 1
	s_waitcnt lgkmcnt(0)
	v_mfma_f32_16x16x32_bf16 v[128:131], v[140:143], v[172:175], v[128:131]
	v_mfma_f32_16x16x32_bf16 v[128:131], v[144:147], v[176:179], v[128:131]
	v_mfma_f32_16x16x32_bf16 v[112:115], v[156:159], v[172:175], v[112:115]
	v_mfma_f32_16x16x32_bf16 v[112:115], v[160:163], v[176:179], v[112:115]
	v_mfma_f32_16x16x32_bf16 v[124:127], v[148:151], v[172:175], v[124:127]
	v_mfma_f32_16x16x32_bf16 v[124:127], v[152:155], v[176:179], v[124:127]
	v_mfma_f32_16x16x32_bf16 v[104:107], v[164:167], v[172:175], v[104:107]
	v_mfma_f32_16x16x32_bf16 v[104:107], v[168:171], v[176:179], v[104:107]
	v_mfma_f32_16x16x32_bf16 v[120:123], v[140:143], v[180:183], v[120:123]
	v_mfma_f32_16x16x32_bf16 v[120:123], v[144:147], v[184:187], v[120:123]
	v_mfma_f32_16x16x32_bf16 v[96:99], v[156:159], v[180:183], v[96:99]
	v_mfma_f32_16x16x32_bf16 v[96:99], v[160:163], v[184:187], v[96:99]
	v_mfma_f32_16x16x32_bf16 v[116:119], v[148:151], v[180:183], v[116:119]
	v_mfma_f32_16x16x32_bf16 v[116:119], v[152:155], v[184:187], v[116:119]
	v_mfma_f32_16x16x32_bf16 v[88:91], v[164:167], v[180:183], v[88:91]
	v_mfma_f32_16x16x32_bf16 v[88:91], v[168:171], v[184:187], v[88:91]
	v_mfma_f32_16x16x32_bf16 v[108:111], v[140:143], v[188:191], v[108:111]
	v_mfma_f32_16x16x32_bf16 v[108:111], v[144:147], v[192:195], v[108:111]
	v_mfma_f32_16x16x32_bf16 v[80:83], v[156:159], v[188:191], v[80:83]
	v_mfma_f32_16x16x32_bf16 v[80:83], v[160:163], v[192:195], v[80:83]
	v_mfma_f32_16x16x32_bf16 v[100:103], v[148:151], v[188:191], v[100:103]
	v_mfma_f32_16x16x32_bf16 v[100:103], v[152:155], v[192:195], v[100:103]
	v_mfma_f32_16x16x32_bf16 v[76:79], v[164:167], v[188:191], v[76:79]
	v_mfma_f32_16x16x32_bf16 v[76:79], v[168:171], v[192:195], v[76:79]
	v_mfma_f32_16x16x32_bf16 v[92:95], v[140:143], v[196:199], v[92:95]
	v_mfma_f32_16x16x32_bf16 v[92:95], v[144:147], v[200:203], v[92:95]
	v_mfma_f32_16x16x32_bf16 v[72:75], v[156:159], v[196:199], v[72:75]
	v_mfma_f32_16x16x32_bf16 v[72:75], v[160:163], v[200:203], v[72:75]
	v_mfma_f32_16x16x32_bf16 v[84:87], v[148:151], v[196:199], v[84:87]
	v_mfma_f32_16x16x32_bf16 v[84:87], v[152:155], v[200:203], v[84:87]
	v_mfma_f32_16x16x32_bf16 v[68:71], v[164:167], v[196:199], v[68:71]
	v_mfma_f32_16x16x32_bf16 v[68:71], v[168:171], v[200:203], v[68:71]
	s_setprio 0
	s_barrier
	s_sleep 2
	s_add_i32 s24, s48, s0
	v_lshl_add_u64 v[204:205], v[204:205], 0, s[66:67]
	s_mov_b32 m0, s24
	ds_read_b128 v[172:175], v139 offset:49152
	ds_read_b128 v[176:179], v139 offset:50176
	ds_read_b128 v[180:183], v139 offset:51200
	ds_read_b128 v[184:187], v139 offset:52224
	ds_read_b128 v[188:191], v139 offset:53248
	ds_read_b128 v[192:195], v139 offset:54272
	ds_read_b128 v[196:199], v139 offset:55296
	ds_read_b128 v[200:203], v139 offset:56320
	global_load_lds_dwordx4 v[204:205], off
	s_add_i32 m0, s24, 0x2000
	s_add_u32 s22, s22, 0x80080
	v_lshl_add_u64 v[204:205], v[206:207], 0, s[66:67]
	s_addc_u32 s23, s23, 0
	s_add_i32 s24, s49, s0
	global_load_lds_dwordx4 v[204:205], off
	v_lshl_add_u64 v[204:205], s[22:23], 0, v[2:3]
	s_mov_b32 m0, s24
	s_nop 0
	global_load_lds_dwordx4 v[204:205], off
	v_lshl_add_u64 v[204:205], s[22:23], 0, v[0:1]
	s_add_i32 m0, s24, 0x2000
	s_nop 0
	global_load_lds_dwordx4 v[204:205], off
	v_lshl_add_u64 v[204:205], v[208:209], 0, s[66:67]
	s_mov_b32 m0, s1
	s_nop 0
	global_load_lds_dwordx4 v[204:205], off
	v_lshl_add_u64 v[204:205], v[210:211], 0, s[66:67]
	s_mov_b32 m0, s34
	s_nop 0
	global_load_lds_dwordx4 v[204:205], off
	s_waitcnt vmcnt(8)
	s_waitcnt lgkmcnt(0)
	s_barrier
	s_setprio 1
	s_waitcnt lgkmcnt(0)
	v_mfma_f32_16x16x32_bf16 v[64:67], v[140:143], v[172:175], v[64:67]
	v_mfma_f32_16x16x32_bf16 v[64:67], v[144:147], v[176:179], v[64:67]
	v_mfma_f32_16x16x32_bf16 v[48:51], v[156:159], v[172:175], v[48:51]
	v_mfma_f32_16x16x32_bf16 v[48:51], v[160:163], v[176:179], v[48:51]
	v_mfma_f32_16x16x32_bf16 v[60:63], v[148:151], v[172:175], v[60:63]
	v_mfma_f32_16x16x32_bf16 v[60:63], v[152:155], v[176:179], v[60:63]
	v_mfma_f32_16x16x32_bf16 v[44:47], v[164:167], v[172:175], v[44:47]
	v_mfma_f32_16x16x32_bf16 v[44:47], v[168:171], v[176:179], v[44:47]
	v_mfma_f32_16x16x32_bf16 v[56:59], v[140:143], v[180:183], v[56:59]
	v_mfma_f32_16x16x32_bf16 v[56:59], v[144:147], v[184:187], v[56:59]
	v_mfma_f32_16x16x32_bf16 v[32:35], v[156:159], v[180:183], v[32:35]
	v_mfma_f32_16x16x32_bf16 v[32:35], v[160:163], v[184:187], v[32:35]
	v_mfma_f32_16x16x32_bf16 v[52:55], v[148:151], v[180:183], v[52:55]
	v_mfma_f32_16x16x32_bf16 v[52:55], v[152:155], v[184:187], v[52:55]
	v_mfma_f32_16x16x32_bf16 v[28:31], v[164:167], v[180:183], v[28:31]
	v_mfma_f32_16x16x32_bf16 v[28:31], v[168:171], v[184:187], v[28:31]
	v_mfma_f32_16x16x32_bf16 v[40:43], v[140:143], v[188:191], v[40:43]
	v_mfma_f32_16x16x32_bf16 v[40:43], v[144:147], v[192:195], v[40:43]
	v_mfma_f32_16x16x32_bf16 v[16:19], v[156:159], v[188:191], v[16:19]
	v_mfma_f32_16x16x32_bf16 v[16:19], v[160:163], v[192:195], v[16:19]
	v_mfma_f32_16x16x32_bf16 v[36:39], v[148:151], v[188:191], v[36:39]
	v_mfma_f32_16x16x32_bf16 v[36:39], v[152:155], v[192:195], v[36:39]
	v_mfma_f32_16x16x32_bf16 v[12:15], v[164:167], v[188:191], v[12:15]
	v_mfma_f32_16x16x32_bf16 v[12:15], v[168:171], v[192:195], v[12:15]
	v_mfma_f32_16x16x32_bf16 v[24:27], v[140:143], v[196:199], v[24:27]
	v_mfma_f32_16x16x32_bf16 v[24:27], v[144:147], v[200:203], v[24:27]
	v_mfma_f32_16x16x32_bf16 v[8:11], v[156:159], v[196:199], v[8:11]
	v_mfma_f32_16x16x32_bf16 v[8:11], v[160:163], v[200:203], v[8:11]
	v_mfma_f32_16x16x32_bf16 v[20:23], v[148:151], v[196:199], v[20:23]
	v_mfma_f32_16x16x32_bf16 v[20:23], v[152:155], v[200:203], v[20:23]
	v_mfma_f32_16x16x32_bf16 v[4:7], v[164:167], v[196:199], v[4:7]
	v_mfma_f32_16x16x32_bf16 v[4:7], v[168:171], v[200:203], v[4:7]
	s_setprio 0
	s_barrier
	s_add_i32 s47, s47, 2
	s_add_u32 s20, s20, 0x100
	s_addc_u32 s21, s21, 0
	s_add_u32 s45, s45, 0x100
	s_addc_u32 s46, s46, 0
	s_cmp_gt_u32 s47, 29
	s_cbranch_scc0 .LBB0_495
	s_and_b64 vcc, exec, s[8:9]
	s_cbranch_vccz .LBB0_498
	s_barrier

.LBB0_1009:
	s_ashr_i32 s13, s12, 31
	s_lshl_b64 s[14:15], s[12:13], 20
	s_add_u32 s14, s1, s14
	s_addc_u32 s15, s2, s15
	s_and_b64 s[16:17], s[38:39], exec
	s_cselect_b32 s13, s15, s23
	s_cselect_b32 s19, s14, s22
	s_ashr_i32 s11, s10, 31
	s_lshl_b64 s[16:17], s[10:11], 20
	s_add_u32 s16, s28, s16
	s_addc_u32 s17, s29, s17
	s_and_b64 s[26:27], s[38:39], exec
	s_cselect_b32 s11, s17, s25
	s_cselect_b32 s45, s16, s24
	s_add_u32 s22, s22, 0x80080
	s_addc_u32 s23, s23, 0
	s_add_u32 s46, s24, 0x100
	s_addc_u32 s47, s25, 0
	s_mov_b32 s48, -2
	s_sleep 1
	s_add_u32 s24, s22, 0xfff80080
	s_addc_u32 s25, s23, -1
	s_add_i32 s49, 0, 0x10000
	s_cmp_eq_u32 s48, 28
	s_cselect_b32 s27, s13, s25
	s_cselect_b32 s26, s19, s24
	s_cselect_b32 s25, s11, s47
	s_cselect_b32 s24, s45, s46
	s_add_i32 s52, 0, 0x14000
	v_lshl_add_u64 v[204:205], s[22:23], 0, v[192:193]
	s_add_i32 m0, s21, 0xc000
	s_nop 0
	global_load_lds_dwordx4 v[204:205], off
	v_lshl_add_u64 v[204:205], s[22:23], 0, v[194:195]
	s_add_i32 m0, s21, 0xe000
	s_nop 0
	global_load_lds_dwordx4 v[204:205], off
	v_add_u32_e32 v144, s49, v219
	v_add_u32_e32 v160, s52, v219
	ds_read_b128 v[116:119], v144
	ds_read_b128 v[124:127], v144 offset:1024
	ds_read_b128 v[132:135], v144 offset:2048
	ds_read_b128 v[144:147], v144 offset:3072
	ds_read_b128 v[148:151], v160
	ds_read_b128 v[152:155], v160 offset:1024
	ds_read_b128 v[156:159], v160 offset:2048
	ds_read_b128 v[160:163], v160 offset:3072
	ds_read_b128 v[164:167], v221
	ds_read_b128 v[168:171], v221 offset:1024
	ds_read_b128 v[172:175], v221 offset:2048
	ds_read_b128 v[176:179], v221 offset:3072
	ds_read_b128 v[180:183], v221 offset:4096
	ds_read_b128 v[184:187], v221 offset:5120
	ds_read_b128 v[196:199], v221 offset:6144
	ds_read_b128 v[200:203], v221 offset:7168
	s_waitcnt vmcnt(8)
	s_waitcnt lgkmcnt(0)
	s_barrier
	s_setprio 1
	s_waitcnt lgkmcnt(0)
	v_mfma_f32_16x16x32_bf16 v[140:143], v[116:119], v[164:167], 0
	v_mfma_f32_16x16x32_bf16 v[140:143], v[124:127], v[168:171], v[140:143]
	v_mfma_f32_16x16x32_bf16 v[128:131], v[148:151], v[164:167], 0
	v_mfma_f32_16x16x32_bf16 v[128:131], v[152:155], v[168:171], v[128:131]
	v_mfma_f32_16x16x32_bf16 v[136:139], v[132:135], v[164:167], 0
	v_mfma_f32_16x16x32_bf16 v[136:139], v[144:147], v[168:171], v[136:139]
	v_mfma_f32_16x16x32_bf16 v[120:123], v[156:159], v[164:167], 0
	v_mfma_f32_16x16x32_bf16 v[120:123], v[160:163], v[168:171], v[120:123]
	v_mfma_f32_16x16x32_bf16 v[112:115], v[116:119], v[172:175], 0
	v_mfma_f32_16x16x32_bf16 v[112:115], v[124:127], v[176:179], v[112:115]
	v_mfma_f32_16x16x32_bf16 v[104:107], v[148:151], v[172:175], 0
	v_mfma_f32_16x16x32_bf16 v[104:107], v[152:155], v[176:179], v[104:107]
	v_mfma_f32_16x16x32_bf16 v[108:111], v[132:135], v[172:175], 0
	v_mfma_f32_16x16x32_bf16 v[108:111], v[144:147], v[176:179], v[108:111]
	v_mfma_f32_16x16x32_bf16 v[100:103], v[156:159], v[172:175], 0
	v_mfma_f32_16x16x32_bf16 v[100:103], v[160:163], v[176:179], v[100:103]
	v_mfma_f32_16x16x32_bf16 v[96:99], v[116:119], v[180:183], 0
	v_mfma_f32_16x16x32_bf16 v[96:99], v[124:127], v[184:187], v[96:99]
	v_mfma_f32_16x16x32_bf16 v[88:91], v[148:151], v[180:183], 0
	v_mfma_f32_16x16x32_bf16 v[88:91], v[152:155], v[184:187], v[88:91]
	v_mfma_f32_16x16x32_bf16 v[92:95], v[132:135], v[180:183], 0
	v_mfma_f32_16x16x32_bf16 v[92:95], v[144:147], v[184:187], v[92:95]
	v_mfma_f32_16x16x32_bf16 v[84:87], v[156:159], v[180:183], 0
	v_mfma_f32_16x16x32_bf16 v[84:87], v[160:163], v[184:187], v[84:87]
	v_mfma_f32_16x16x32_bf16 v[80:83], v[116:119], v[196:199], 0
	v_mfma_f32_16x16x32_bf16 v[80:83], v[124:127], v[200:203], v[80:83]
	v_mfma_f32_16x16x32_bf16 v[72:75], v[148:151], v[196:199], 0
	v_mfma_f32_16x16x32_bf16 v[72:75], v[152:155], v[200:203], v[72:75]
	v_mfma_f32_16x16x32_bf16 v[76:79], v[132:135], v[196:199], 0
	v_mfma_f32_16x16x32_bf16 v[76:79], v[144:147], v[200:203], v[76:79]
	v_mfma_f32_16x16x32_bf16 v[68:71], v[156:159], v[196:199], 0
	v_mfma_f32_16x16x32_bf16 v[68:71], v[160:163], v[200:203], v[68:71]
	s_setprio 0
	s_barrier
	s_sleep 2
	s_add_i32 s49, s49, s30
	v_lshl_add_u64 v[204:205], s[24:25], 0, v[2:3]
	s_mov_b32 m0, s49
	ds_read_b128 v[164:167], v221 offset:16384
	ds_read_b128 v[168:171], v221 offset:17408
	ds_read_b128 v[172:175], v221 offset:18432
	ds_read_b128 v[176:179], v221 offset:19456
	ds_read_b128 v[180:183], v221 offset:20480
	ds_read_b128 v[184:187], v221 offset:21504
	ds_read_b128 v[196:199], v221 offset:22528
	ds_read_b128 v[200:203], v221 offset:23552
	global_load_lds_dwordx4 v[204:205], off
	s_add_i32 m0, s49, 0x2000
	s_add_u32 s50, s24, 0x80000
	v_lshl_add_u64 v[206:207], s[24:25], 0, v[190:191]
	s_addc_u32 s51, s25, 0
	s_add_i32 s49, s52, s30
	global_load_lds_dwordx4 v[206:207], off
	v_lshl_add_u64 v[208:209], s[50:51], 0, v[2:3]
	s_mov_b32 m0, s49
	v_lshl_add_u64 v[210:211], s[26:27], 0, v[188:189]
	global_load_lds_dwordx4 v[208:209], off
	v_lshl_add_u64 v[208:209], s[50:51], 0, v[190:191]
	s_add_i32 m0, s49, 0x2000
	s_nop 0
	global_load_lds_dwordx4 v[208:209], off
	v_lshl_add_u64 v[208:209], s[26:27], 0, v[0:1]
	s_mov_b32 m0, s21
	s_nop 0
	global_load_lds_dwordx4 v[208:209], off
	s_mov_b32 m0, s31
	s_nop 0
	global_load_lds_dwordx4 v[210:211], off
	s_waitcnt vmcnt(8)
	s_waitcnt lgkmcnt(0)
	s_barrier
	s_setprio 1
	s_waitcnt lgkmcnt(0)
	v_mfma_f32_16x16x32_bf16 v[64:67], v[116:119], v[164:167], 0
	v_mfma_f32_16x16x32_bf16 v[64:67], v[124:127], v[168:171], v[64:67]
	v_mfma_f32_16x16x32_bf16 v[56:59], v[148:151], v[164:167], 0
	v_mfma_f32_16x16x32_bf16 v[56:59], v[152:155], v[168:171], v[56:59]
	v_mfma_f32_16x16x32_bf16 v[60:63], v[132:135], v[164:167], 0
	v_mfma_f32_16x16x32_bf16 v[60:63], v[144:147], v[168:171], v[60:63]
	v_mfma_f32_16x16x32_bf16 v[52:55], v[156:159], v[164:167], 0
	v_mfma_f32_16x16x32_bf16 v[52:55], v[160:163], v[168:171], v[52:55]
	v_mfma_f32_16x16x32_bf16 v[48:51], v[116:119], v[172:175], 0
	v_mfma_f32_16x16x32_bf16 v[48:51], v[124:127], v[176:179], v[48:51]
	v_mfma_f32_16x16x32_bf16 v[40:43], v[148:151], v[172:175], 0
	v_mfma_f32_16x16x32_bf16 v[40:43], v[152:155], v[176:179], v[40:43]
	v_mfma_f32_16x16x32_bf16 v[44:47], v[132:135], v[172:175], 0
	v_mfma_f32_16x16x32_bf16 v[44:47], v[144:147], v[176:179], v[44:47]
	v_mfma_f32_16x16x32_bf16 v[36:39], v[156:159], v[172:175], 0
	v_mfma_f32_16x16x32_bf16 v[36:39], v[160:163], v[176:179], v[36:39]
	v_mfma_f32_16x16x32_bf16 v[32:35], v[116:119], v[180:183], 0
	v_mfma_f32_16x16x32_bf16 v[32:35], v[124:127], v[184:187], v[32:35]
	v_mfma_f32_16x16x32_bf16 v[24:27], v[148:151], v[180:183], 0
	v_mfma_f32_16x16x32_bf16 v[24:27], v[152:155], v[184:187], v[24:27]
	v_mfma_f32_16x16x32_bf16 v[28:31], v[132:135], v[180:183], 0
	v_mfma_f32_16x16x32_bf16 v[28:31], v[144:147], v[184:187], v[28:31]
	v_mfma_f32_16x16x32_bf16 v[20:23], v[156:159], v[180:183], 0
	v_mfma_f32_16x16x32_bf16 v[20:23], v[160:163], v[184:187], v[20:23]
	v_mfma_f32_16x16x32_bf16 v[16:19], v[116:119], v[196:199], 0
	v_mfma_f32_16x16x32_bf16 v[16:19], v[124:127], v[200:203], v[16:19]
	v_mfma_f32_16x16x32_bf16 v[8:11], v[148:151], v[196:199], 0
	v_mfma_f32_16x16x32_bf16 v[8:11], v[152:155], v[200:203], v[8:11]
	v_mfma_f32_16x16x32_bf16 v[12:15], v[132:135], v[196:199], 0
	v_mfma_f32_16x16x32_bf16 v[12:15], v[144:147], v[200:203], v[12:15]
	v_mfma_f32_16x16x32_bf16 v[4:7], v[156:159], v[196:199], 0
	v_mfma_f32_16x16x32_bf16 v[4:7], v[160:163], v[200:203], v[4:7]
	s_setprio 0
	s_barrier
	s_sleep 1
	s_add_i32 s49, 0, 0x18000
	s_add_i32 s50, 0, 0x1c000
	s_add_u32 s26, s26, 0x80000
	s_addc_u32 s27, s27, 0
	s_mov_b32 m0, s35
	v_lshl_add_u64 v[212:213], s[26:27], 0, v[0:1]
	global_load_lds_dwordx4 v[212:213], off
	v_lshl_add_u64 v[212:213], s[26:27], 0, v[188:189]
	s_mov_b32 m0, s40
	s_nop 0
	global_load_lds_dwordx4 v[212:213], off
	v_add_u32_e32 v144, s49, v219
	v_add_u32_e32 v160, s50, v219
	ds_read_b128 v[116:119], v144
	ds_read_b128 v[124:127], v144 offset:1024
	ds_read_b128 v[132:135], v144 offset:2048
	ds_read_b128 v[144:147], v144 offset:3072
	ds_read_b128 v[148:151], v160
	ds_read_b128 v[152:155], v160 offset:1024
	ds_read_b128 v[156:159], v160 offset:2048
	ds_read_b128 v[160:163], v160 offset:3072
	ds_read_b128 v[164:167], v221 offset:32768
	ds_read_b128 v[168:171], v221 offset:33792
	ds_read_b128 v[172:175], v221 offset:34816
	ds_read_b128 v[176:179], v221 offset:35840
	ds_read_b128 v[180:183], v221 offset:36864
	ds_read_b128 v[184:187], v221 offset:37888
	ds_read_b128 v[196:199], v221 offset:38912
	ds_read_b128 v[200:203], v221 offset:39936
	s_waitcnt vmcnt(8)
	s_waitcnt lgkmcnt(0)
	s_barrier
	s_setprio 1
	s_waitcnt lgkmcnt(0)
	v_mfma_f32_16x16x32_bf16 v[140:143], v[116:119], v[164:167], v[140:143]
	v_mfma_f32_16x16x32_bf16 v[140:143], v[124:127], v[168:171], v[140:143]
	v_mfma_f32_16x16x32_bf16 v[128:131], v[148:151], v[164:167], v[128:131]
	v_mfma_f32_16x16x32_bf16 v[128:131], v[152:155], v[168:171], v[128:131]
	v_mfma_f32_16x16x32_bf16 v[136:139], v[132:135], v[164:167], v[136:139]
	v_mfma_f32_16x16x32_bf16 v[136:139], v[144:147], v[168:171], v[136:139]
	v_mfma_f32_16x16x32_bf16 v[120:123], v[156:159], v[164:167], v[120:123]
	v_mfma_f32_16x16x32_bf16 v[120:123], v[160:163], v[168:171], v[120:123]
	v_mfma_f32_16x16x32_bf16 v[112:115], v[116:119], v[172:175], v[112:115]
	v_mfma_f32_16x16x32_bf16 v[112:115], v[124:127], v[176:179], v[112:115]
	v_mfma_f32_16x16x32_bf16 v[104:107], v[148:151], v[172:175], v[104:107]
	v_mfma_f32_16x16x32_bf16 v[104:107], v[152:155], v[176:179], v[104:107]
	v_mfma_f32_16x16x32_bf16 v[108:111], v[132:135], v[172:175], v[108:111]
	v_mfma_f32_16x16x32_bf16 v[108:111], v[144:147], v[176:179], v[108:111]
	v_mfma_f32_16x16x32_bf16 v[100:103], v[156:159], v[172:175], v[100:103]
	v_mfma_f32_16x16x32_bf16 v[100:103], v[160:163], v[176:179], v[100:103]
	v_mfma_f32_16x16x32_bf16 v[96:99], v[116:119], v[180:183], v[96:99]
	v_mfma_f32_16x16x32_bf16 v[96:99], v[124:127], v[184:187], v[96:99]
	v_mfma_f32_16x16x32_bf16 v[88:91], v[148:151], v[180:183], v[88:91]
	v_mfma_f32_16x16x32_bf16 v[88:91], v[152:155], v[184:187], v[88:91]
	v_mfma_f32_16x16x32_bf16 v[92:95], v[132:135], v[180:183], v[92:95]
	v_mfma_f32_16x16x32_bf16 v[92:95], v[144:147], v[184:187], v[92:95]
	v_mfma_f32_16x16x32_bf16 v[84:87], v[156:159], v[180:183], v[84:87]
	v_mfma_f32_16x16x32_bf16 v[84:87], v[160:163], v[184:187], v[84:87]
	v_mfma_f32_16x16x32_bf16 v[80:83], v[116:119], v[196:199], v[80:83]
	v_mfma_f32_16x16x32_bf16 v[80:83], v[124:127], v[200:203], v[80:83]
	v_mfma_f32_16x16x32_bf16 v[72:75], v[148:151], v[196:199], v[72:75]
	v_mfma_f32_16x16x32_bf16 v[72:75], v[152:155], v[200:203], v[72:75]
	v_mfma_f32_16x16x32_bf16 v[76:79], v[132:135], v[196:199], v[76:79]
	v_mfma_f32_16x16x32_bf16 v[76:79], v[144:147], v[200:203], v[76:79]
	v_mfma_f32_16x16x32_bf16 v[68:71], v[156:159], v[196:199], v[68:71]
	v_mfma_f32_16x16x32_bf16 v[68:71], v[160:163], v[200:203], v[68:71]
	s_setprio 0
	s_barrier
	s_sleep 2
	s_add_i32 s26, s49, s30
	v_lshl_add_u64 v[204:205], v[204:205], 0, s[66:67]
	s_mov_b32 m0, s26
	ds_read_b128 v[164:167], v221 offset:49152
	ds_read_b128 v[168:171], v221 offset:50176
	ds_read_b128 v[172:175], v221 offset:51200
	ds_read_b128 v[176:179], v221 offset:52224
	ds_read_b128 v[180:183], v221 offset:53248
	ds_read_b128 v[184:187], v221 offset:54272
	ds_read_b128 v[196:199], v221 offset:55296
	ds_read_b128 v[200:203], v221 offset:56320
	global_load_lds_dwordx4 v[204:205], off
	s_add_i32 m0, s26, 0x2000
	s_add_u32 s24, s24, 0x80080
	v_lshl_add_u64 v[204:205], v[206:207], 0, s[66:67]
	s_addc_u32 s25, s25, 0
	s_add_i32 s26, s50, s30
	global_load_lds_dwordx4 v[204:205], off
	v_lshl_add_u64 v[204:205], s[24:25], 0, v[2:3]
	s_mov_b32 m0, s26
	s_nop 0
	global_load_lds_dwordx4 v[204:205], off
	v_lshl_add_u64 v[204:205], s[24:25], 0, v[190:191]
	s_add_i32 m0, s26, 0x2000
	s_nop 0
	global_load_lds_dwordx4 v[204:205], off
	v_lshl_add_u64 v[204:205], v[208:209], 0, s[66:67]
	s_mov_b32 m0, s41
	s_nop 0
	global_load_lds_dwordx4 v[204:205], off
	v_lshl_add_u64 v[204:205], v[210:211], 0, s[66:67]
	s_mov_b32 m0, s42
	s_nop 0
	global_load_lds_dwordx4 v[204:205], off
	s_waitcnt vmcnt(8)
	s_waitcnt lgkmcnt(0)
	s_barrier
	s_setprio 1
	s_waitcnt lgkmcnt(0)
	v_mfma_f32_16x16x32_bf16 v[64:67], v[116:119], v[164:167], v[64:67]
	v_mfma_f32_16x16x32_bf16 v[64:67], v[124:127], v[168:171], v[64:67]
	v_mfma_f32_16x16x32_bf16 v[56:59], v[148:151], v[164:167], v[56:59]
	v_mfma_f32_16x16x32_bf16 v[56:59], v[152:155], v[168:171], v[56:59]
	v_mfma_f32_16x16x32_bf16 v[60:63], v[132:135], v[164:167], v[60:63]
	v_mfma_f32_16x16x32_bf16 v[60:63], v[144:147], v[168:171], v[60:63]
	v_mfma_f32_16x16x32_bf16 v[52:55], v[156:159], v[164:167], v[52:55]
	v_mfma_f32_16x16x32_bf16 v[52:55], v[160:163], v[168:171], v[52:55]
	v_mfma_f32_16x16x32_bf16 v[48:51], v[116:119], v[172:175], v[48:51]
	v_mfma_f32_16x16x32_bf16 v[48:51], v[124:127], v[176:179], v[48:51]
	v_mfma_f32_16x16x32_bf16 v[40:43], v[148:151], v[172:175], v[40:43]
	v_mfma_f32_16x16x32_bf16 v[40:43], v[152:155], v[176:179], v[40:43]
	v_mfma_f32_16x16x32_bf16 v[44:47], v[132:135], v[172:175], v[44:47]
	v_mfma_f32_16x16x32_bf16 v[44:47], v[144:147], v[176:179], v[44:47]
	v_mfma_f32_16x16x32_bf16 v[36:39], v[156:159], v[172:175], v[36:39]
	v_mfma_f32_16x16x32_bf16 v[36:39], v[160:163], v[176:179], v[36:39]
	v_mfma_f32_16x16x32_bf16 v[32:35], v[116:119], v[180:183], v[32:35]
	v_mfma_f32_16x16x32_bf16 v[32:35], v[124:127], v[184:187], v[32:35]
	v_mfma_f32_16x16x32_bf16 v[24:27], v[148:151], v[180:183], v[24:27]
	v_mfma_f32_16x16x32_bf16 v[24:27], v[152:155], v[184:187], v[24:27]
	v_mfma_f32_16x16x32_bf16 v[28:31], v[132:135], v[180:183], v[28:31]
	v_mfma_f32_16x16x32_bf16 v[28:31], v[144:147], v[184:187], v[28:31]
	v_mfma_f32_16x16x32_bf16 v[20:23], v[156:159], v[180:183], v[20:23]
	v_mfma_f32_16x16x32_bf16 v[20:23], v[160:163], v[184:187], v[20:23]
	v_mfma_f32_16x16x32_bf16 v[16:19], v[116:119], v[196:199], v[16:19]
	v_mfma_f32_16x16x32_bf16 v[16:19], v[124:127], v[200:203], v[16:19]
	v_mfma_f32_16x16x32_bf16 v[8:11], v[148:151], v[196:199], v[8:11]
	v_mfma_f32_16x16x32_bf16 v[8:11], v[152:155], v[200:203], v[8:11]
	v_mfma_f32_16x16x32_bf16 v[12:15], v[132:135], v[196:199], v[12:15]
	v_mfma_f32_16x16x32_bf16 v[12:15], v[144:147], v[200:203], v[12:15]
	v_mfma_f32_16x16x32_bf16 v[4:7], v[156:159], v[196:199], v[4:7]
	v_mfma_f32_16x16x32_bf16 v[4:7], v[160:163], v[200:203], v[4:7]
	s_setprio 0
	s_barrier
	s_add_i32 s48, s48, 2
	s_add_u32 s22, s22, 0x100
	s_addc_u32 s23, s23, 0
	s_add_u32 s46, s46, 0x100
	s_addc_u32 s47, s47, 0
	s_cmp_gt_u32 s48, 29
.LBB0_1010:
	s_sleep 1
	s_add_u32 s24, s22, 0xfff80080
	s_addc_u32 s25, s23, -1
	s_add_i32 s49, 0, 0x10000
	s_cmp_eq_u32 s48, 28
	s_cselect_b32 s27, s13, s25
	s_cselect_b32 s26, s19, s24
	s_cselect_b32 s25, s11, s47
	s_cselect_b32 s24, s45, s46
	s_add_i32 s52, 0, 0x14000
	v_lshl_add_u64 v[204:205], s[22:23], 0, v[192:193]
	s_add_i32 m0, s21, 0xc000
	s_nop 0
	global_load_lds_dwordx4 v[204:205], off
	v_lshl_add_u64 v[204:205], s[22:23], 0, v[194:195]
	s_add_i32 m0, s21, 0xe000
	s_nop 0
	global_load_lds_dwordx4 v[204:205], off
	v_add_u32_e32 v144, s49, v219
	v_add_u32_e32 v160, s52, v219
	ds_read_b128 v[116:119], v144
	ds_read_b128 v[124:127], v144 offset:1024
	ds_read_b128 v[132:135], v144 offset:2048
	ds_read_b128 v[144:147], v144 offset:3072
	ds_read_b128 v[148:151], v160
	ds_read_b128 v[152:155], v160 offset:1024
	ds_read_b128 v[156:159], v160 offset:2048
	ds_read_b128 v[160:163], v160 offset:3072
	ds_read_b128 v[164:167], v221
	ds_read_b128 v[168:171], v221 offset:1024
	ds_read_b128 v[172:175], v221 offset:2048
	ds_read_b128 v[176:179], v221 offset:3072
	ds_read_b128 v[180:183], v221 offset:4096
	ds_read_b128 v[184:187], v221 offset:5120
	ds_read_b128 v[196:199], v221 offset:6144
	ds_read_b128 v[200:203], v221 offset:7168
	s_waitcnt vmcnt(8)
	s_waitcnt lgkmcnt(0)
	s_barrier
	s_setprio 1
	s_waitcnt lgkmcnt(0)
	v_mfma_f32_16x16x32_bf16 v[140:143], v[116:119], v[164:167], v[140:143]
	v_mfma_f32_16x16x32_bf16 v[140:143], v[124:127], v[168:171], v[140:143]
	v_mfma_f32_16x16x32_bf16 v[128:131], v[148:151], v[164:167], v[128:131]
	v_mfma_f32_16x16x32_bf16 v[128:131], v[152:155], v[168:171], v[128:131]
	v_mfma_f32_16x16x32_bf16 v[136:139], v[132:135], v[164:167], v[136:139]
	v_mfma_f32_16x16x32_bf16 v[136:139], v[144:147], v[168:171], v[136:139]
	v_mfma_f32_16x16x32_bf16 v[120:123], v[156:159], v[164:167], v[120:123]
	v_mfma_f32_16x16x32_bf16 v[120:123], v[160:163], v[168:171], v[120:123]
	v_mfma_f32_16x16x32_bf16 v[112:115], v[116:119], v[172:175], v[112:115]
	v_mfma_f32_16x16x32_bf16 v[112:115], v[124:127], v[176:179], v[112:115]
	v_mfma_f32_16x16x32_bf16 v[104:107], v[148:151], v[172:175], v[104:107]
	v_mfma_f32_16x16x32_bf16 v[104:107], v[152:155], v[176:179], v[104:107]
	v_mfma_f32_16x16x32_bf16 v[108:111], v[132:135], v[172:175], v[108:111]
	v_mfma_f32_16x16x32_bf16 v[108:111], v[144:147], v[176:179], v[108:111]
	v_mfma_f32_16x16x32_bf16 v[100:103], v[156:159], v[172:175], v[100:103]
	v_mfma_f32_16x16x32_bf16 v[100:103], v[160:163], v[176:179], v[100:103]
	v_mfma_f32_16x16x32_bf16 v[96:99], v[116:119], v[180:183], v[96:99]
	v_mfma_f32_16x16x32_bf16 v[96:99], v[124:127], v[184:187], v[96:99]
	v_mfma_f32_16x16x32_bf16 v[88:91], v[148:151], v[180:183], v[88:91]
	v_mfma_f32_16x16x32_bf16 v[88:91], v[152:155], v[184:187], v[88:91]
	v_mfma_f32_16x16x32_bf16 v[92:95], v[132:135], v[180:183], v[92:95]
	v_mfma_f32_16x16x32_bf16 v[92:95], v[144:147], v[184:187], v[92:95]
	v_mfma_f32_16x16x32_bf16 v[84:87], v[156:159], v[180:183], v[84:87]
	v_mfma_f32_16x16x32_bf16 v[84:87], v[160:163], v[184:187], v[84:87]
	v_mfma_f32_16x16x32_bf16 v[80:83], v[116:119], v[196:199], v[80:83]
	v_mfma_f32_16x16x32_bf16 v[80:83], v[124:127], v[200:203], v[80:83]
	v_mfma_f32_16x16x32_bf16 v[72:75], v[148:151], v[196:199], v[72:75]
	v_mfma_f32_16x16x32_bf16 v[72:75], v[152:155], v[200:203], v[72:75]
	v_mfma_f32_16x16x32_bf16 v[76:79], v[132:135], v[196:199], v[76:79]
	v_mfma_f32_16x16x32_bf16 v[76:79], v[144:147], v[200:203], v[76:79]
	v_mfma_f32_16x16x32_bf16 v[68:71], v[156:159], v[196:199], v[68:71]
	v_mfma_f32_16x16x32_bf16 v[68:71], v[160:163], v[200:203], v[68:71]
	s_setprio 0
	s_barrier
	s_sleep 2
	s_add_i32 s49, s49, s30
	v_lshl_add_u64 v[204:205], s[24:25], 0, v[2:3]
	s_mov_b32 m0, s49
	ds_read_b128 v[164:167], v221 offset:16384
	ds_read_b128 v[168:171], v221 offset:17408
	ds_read_b128 v[172:175], v221 offset:18432
	ds_read_b128 v[176:179], v221 offset:19456
	ds_read_b128 v[180:183], v221 offset:20480
	ds_read_b128 v[184:187], v221 offset:21504
	ds_read_b128 v[196:199], v221 offset:22528
	ds_read_b128 v[200:203], v221 offset:23552
	global_load_lds_dwordx4 v[204:205], off
	s_add_i32 m0, s49, 0x2000
	s_add_u32 s50, s24, 0x80000
	v_lshl_add_u64 v[206:207], s[24:25], 0, v[190:191]
	s_addc_u32 s51, s25, 0
	s_add_i32 s49, s52, s30
	global_load_lds_dwordx4 v[206:207], off
	v_lshl_add_u64 v[208:209], s[50:51], 0, v[2:3]
	s_mov_b32 m0, s49
	v_lshl_add_u64 v[210:211], s[26:27], 0, v[188:189]
	global_load_lds_dwordx4 v[208:209], off
	v_lshl_add_u64 v[208:209], s[50:51], 0, v[190:191]
	s_add_i32 m0, s49, 0x2000
	s_nop 0
	global_load_lds_dwordx4 v[208:209], off
	v_lshl_add_u64 v[208:209], s[26:27], 0, v[0:1]
	s_mov_b32 m0, s21
	s_nop 0
	global_load_lds_dwordx4 v[208:209], off
	s_mov_b32 m0, s31
	s_nop 0
	global_load_lds_dwordx4 v[210:211], off
	s_waitcnt vmcnt(8)
	s_waitcnt lgkmcnt(0)
	s_barrier
	s_setprio 1
	s_waitcnt lgkmcnt(0)
	v_mfma_f32_16x16x32_bf16 v[64:67], v[116:119], v[164:167], v[64:67]
	v_mfma_f32_16x16x32_bf16 v[64:67], v[124:127], v[168:171], v[64:67]
	v_mfma_f32_16x16x32_bf16 v[56:59], v[148:151], v[164:167], v[56:59]
	v_mfma_f32_16x16x32_bf16 v[56:59], v[152:155], v[168:171], v[56:59]
	v_mfma_f32_16x16x32_bf16 v[60:63], v[132:135], v[164:167], v[60:63]
	v_mfma_f32_16x16x32_bf16 v[60:63], v[144:147], v[168:171], v[60:63]
	v_mfma_f32_16x16x32_bf16 v[52:55], v[156:159], v[164:167], v[52:55]
	v_mfma_f32_16x16x32_bf16 v[52:55], v[160:163], v[168:171], v[52:55]
	v_mfma_f32_16x16x32_bf16 v[48:51], v[116:119], v[172:175], v[48:51]
	v_mfma_f32_16x16x32_bf16 v[48:51], v[124:127], v[176:179], v[48:51]
	v_mfma_f32_16x16x32_bf16 v[40:43], v[148:151], v[172:175], v[40:43]
	v_mfma_f32_16x16x32_bf16 v[40:43], v[152:155], v[176:179], v[40:43]
	v_mfma_f32_16x16x32_bf16 v[44:47], v[132:135], v[172:175], v[44:47]
	v_mfma_f32_16x16x32_bf16 v[44:47], v[144:147], v[176:179], v[44:47]
	v_mfma_f32_16x16x32_bf16 v[36:39], v[156:159], v[172:175], v[36:39]
	v_mfma_f32_16x16x32_bf16 v[36:39], v[160:163], v[176:179], v[36:39]
	v_mfma_f32_16x16x32_bf16 v[32:35], v[116:119], v[180:183], v[32:35]
	v_mfma_f32_16x16x32_bf16 v[32:35], v[124:127], v[184:187], v[32:35]
	v_mfma_f32_16x16x32_bf16 v[24:27], v[148:151], v[180:183], v[24:27]
	v_mfma_f32_16x16x32_bf16 v[24:27], v[152:155], v[184:187], v[24:27]
	v_mfma_f32_16x16x32_bf16 v[28:31], v[132:135], v[180:183], v[28:31]
	v_mfma_f32_16x16x32_bf16 v[28:31], v[144:147], v[184:187], v[28:31]
	v_mfma_f32_16x16x32_bf16 v[20:23], v[156:159], v[180:183], v[20:23]
	v_mfma_f32_16x16x32_bf16 v[20:23], v[160:163], v[184:187], v[20:23]
	v_mfma_f32_16x16x32_bf16 v[16:19], v[116:119], v[196:199], v[16:19]
	v_mfma_f32_16x16x32_bf16 v[16:19], v[124:127], v[200:203], v[16:19]
	v_mfma_f32_16x16x32_bf16 v[8:11], v[148:151], v[196:199], v[8:11]
	v_mfma_f32_16x16x32_bf16 v[8:11], v[152:155], v[200:203], v[8:11]
	v_mfma_f32_16x16x32_bf16 v[12:15], v[132:135], v[196:199], v[12:15]
	v_mfma_f32_16x16x32_bf16 v[12:15], v[144:147], v[200:203], v[12:15]
	v_mfma_f32_16x16x32_bf16 v[4:7], v[156:159], v[196:199], v[4:7]
	v_mfma_f32_16x16x32_bf16 v[4:7], v[160:163], v[200:203], v[4:7]
	s_setprio 0
	s_barrier
	s_sleep 1
	s_add_i32 s49, 0, 0x18000
	s_add_i32 s50, 0, 0x1c000
	s_add_u32 s26, s26, 0x80000
	s_addc_u32 s27, s27, 0
	s_mov_b32 m0, s35
	v_lshl_add_u64 v[212:213], s[26:27], 0, v[0:1]
	global_load_lds_dwordx4 v[212:213], off
	v_lshl_add_u64 v[212:213], s[26:27], 0, v[188:189]
	s_mov_b32 m0, s40
	s_nop 0
	global_load_lds_dwordx4 v[212:213], off
	v_add_u32_e32 v144, s49, v219
	v_add_u32_e32 v160, s50, v219
	ds_read_b128 v[116:119], v144
	ds_read_b128 v[124:127], v144 offset:1024
	ds_read_b128 v[132:135], v144 offset:2048
	ds_read_b128 v[144:147], v144 offset:3072
	ds_read_b128 v[148:151], v160
	ds_read_b128 v[152:155], v160 offset:1024
	ds_read_b128 v[156:159], v160 offset:2048
	ds_read_b128 v[160:163], v160 offset:3072
	ds_read_b128 v[164:167], v221 offset:32768
	ds_read_b128 v[168:171], v221 offset:33792
	ds_read_b128 v[172:175], v221 offset:34816
	ds_read_b128 v[176:179], v221 offset:35840
	ds_read_b128 v[180:183], v221 offset:36864
	ds_read_b128 v[184:187], v221 offset:37888
	ds_read_b128 v[196:199], v221 offset:38912
	ds_read_b128 v[200:203], v221 offset:39936
	s_waitcnt vmcnt(8)
	s_waitcnt lgkmcnt(0)
	s_barrier
	s_setprio 1
	s_waitcnt lgkmcnt(0)
	v_mfma_f32_16x16x32_bf16 v[140:143], v[116:119], v[164:167], v[140:143]
	v_mfma_f32_16x16x32_bf16 v[140:143], v[124:127], v[168:171], v[140:143]
	v_mfma_f32_16x16x32_bf16 v[128:131], v[148:151], v[164:167], v[128:131]
	v_mfma_f32_16x16x32_bf16 v[128:131], v[152:155], v[168:171], v[128:131]
	v_mfma_f32_16x16x32_bf16 v[136:139], v[132:135], v[164:167], v[136:139]
	v_mfma_f32_16x16x32_bf16 v[136:139], v[144:147], v[168:171], v[136:139]
	v_mfma_f32_16x16x32_bf16 v[120:123], v[156:159], v[164:167], v[120:123]
	v_mfma_f32_16x16x32_bf16 v[120:123], v[160:163], v[168:171], v[120:123]
	v_mfma_f32_16x16x32_bf16 v[112:115], v[116:119], v[172:175], v[112:115]
	v_mfma_f32_16x16x32_bf16 v[112:115], v[124:127], v[176:179], v[112:115]
	v_mfma_f32_16x16x32_bf16 v[104:107], v[148:151], v[172:175], v[104:107]
	v_mfma_f32_16x16x32_bf16 v[104:107], v[152:155], v[176:179], v[104:107]
	v_mfma_f32_16x16x32_bf16 v[108:111], v[132:135], v[172:175], v[108:111]
	v_mfma_f32_16x16x32_bf16 v[108:111], v[144:147], v[176:179], v[108:111]
	v_mfma_f32_16x16x32_bf16 v[100:103], v[156:159], v[172:175], v[100:103]
	v_mfma_f32_16x16x32_bf16 v[100:103], v[160:163], v[176:179], v[100:103]
	v_mfma_f32_16x16x32_bf16 v[96:99], v[116:119], v[180:183], v[96:99]
	v_mfma_f32_16x16x32_bf16 v[96:99], v[124:127], v[184:187], v[96:99]
	v_mfma_f32_16x16x32_bf16 v[88:91], v[148:151], v[180:183], v[88:91]
	v_mfma_f32_16x16x32_bf16 v[88:91], v[152:155], v[184:187], v[88:91]
	v_mfma_f32_16x16x32_bf16 v[92:95], v[132:135], v[180:183], v[92:95]
	v_mfma_f32_16x16x32_bf16 v[92:95], v[144:147], v[184:187], v[92:95]
	v_mfma_f32_16x16x32_bf16 v[84:87], v[156:159], v[180:183], v[84:87]
	v_mfma_f32_16x16x32_bf16 v[84:87], v[160:163], v[184:187], v[84:87]
	v_mfma_f32_16x16x32_bf16 v[80:83], v[116:119], v[196:199], v[80:83]
	v_mfma_f32_16x16x32_bf16 v[80:83], v[124:127], v[200:203], v[80:83]
	v_mfma_f32_16x16x32_bf16 v[72:75], v[148:151], v[196:199], v[72:75]
	v_mfma_f32_16x16x32_bf16 v[72:75], v[152:155], v[200:203], v[72:75]
	v_mfma_f32_16x16x32_bf16 v[76:79], v[132:135], v[196:199], v[76:79]
	v_mfma_f32_16x16x32_bf16 v[76:79], v[144:147], v[200:203], v[76:79]
	v_mfma_f32_16x16x32_bf16 v[68:71], v[156:159], v[196:199], v[68:71]
	v_mfma_f32_16x16x32_bf16 v[68:71], v[160:163], v[200:203], v[68:71]
	s_setprio 0
	s_barrier
	s_sleep 2
	s_add_i32 s26, s49, s30
	v_lshl_add_u64 v[204:205], v[204:205], 0, s[66:67]
	s_mov_b32 m0, s26
	ds_read_b128 v[164:167], v221 offset:49152
	ds_read_b128 v[168:171], v221 offset:50176
	ds_read_b128 v[172:175], v221 offset:51200
	ds_read_b128 v[176:179], v221 offset:52224
	ds_read_b128 v[180:183], v221 offset:53248
	ds_read_b128 v[184:187], v221 offset:54272
	ds_read_b128 v[196:199], v221 offset:55296
	ds_read_b128 v[200:203], v221 offset:56320
	global_load_lds_dwordx4 v[204:205], off
	s_add_i32 m0, s26, 0x2000
	s_add_u32 s24, s24, 0x80080
	v_lshl_add_u64 v[204:205], v[206:207], 0, s[66:67]
	s_addc_u32 s25, s25, 0
	s_add_i32 s26, s50, s30
	global_load_lds_dwordx4 v[204:205], off
	v_lshl_add_u64 v[204:205], s[24:25], 0, v[2:3]
	s_mov_b32 m0, s26
	s_nop 0
	global_load_lds_dwordx4 v[204:205], off
	v_lshl_add_u64 v[204:205], s[24:25], 0, v[190:191]
	s_add_i32 m0, s26, 0x2000
	s_nop 0
	global_load_lds_dwordx4 v[204:205], off
	v_lshl_add_u64 v[204:205], v[208:209], 0, s[66:67]
	s_mov_b32 m0, s41
	s_nop 0
	global_load_lds_dwordx4 v[204:205], off
	v_lshl_add_u64 v[204:205], v[210:211], 0, s[66:67]
	s_mov_b32 m0, s42
	s_nop 0
	global_load_lds_dwordx4 v[204:205], off
	s_waitcnt vmcnt(8)
	s_waitcnt lgkmcnt(0)
	s_barrier
	s_setprio 1
	s_waitcnt lgkmcnt(0)
	v_mfma_f32_16x16x32_bf16 v[64:67], v[116:119], v[164:167], v[64:67]
	v_mfma_f32_16x16x32_bf16 v[64:67], v[124:127], v[168:171], v[64:67]
	v_mfma_f32_16x16x32_bf16 v[56:59], v[148:151], v[164:167], v[56:59]
	v_mfma_f32_16x16x32_bf16 v[56:59], v[152:155], v[168:171], v[56:59]
	v_mfma_f32_16x16x32_bf16 v[60:63], v[132:135], v[164:167], v[60:63]
	v_mfma_f32_16x16x32_bf16 v[60:63], v[144:147], v[168:171], v[60:63]
	v_mfma_f32_16x16x32_bf16 v[52:55], v[156:159], v[164:167], v[52:55]
	v_mfma_f32_16x16x32_bf16 v[52:55], v[160:163], v[168:171], v[52:55]
	v_mfma_f32_16x16x32_bf16 v[48:51], v[116:119], v[172:175], v[48:51]
	v_mfma_f32_16x16x32_bf16 v[48:51], v[124:127], v[176:179], v[48:51]
	v_mfma_f32_16x16x32_bf16 v[40:43], v[148:151], v[172:175], v[40:43]
	v_mfma_f32_16x16x32_bf16 v[40:43], v[152:155], v[176:179], v[40:43]
	v_mfma_f32_16x16x32_bf16 v[44:47], v[132:135], v[172:175], v[44:47]
	v_mfma_f32_16x16x32_bf16 v[44:47], v[144:147], v[176:179], v[44:47]
	v_mfma_f32_16x16x32_bf16 v[36:39], v[156:159], v[172:175], v[36:39]
	v_mfma_f32_16x16x32_bf16 v[36:39], v[160:163], v[176:179], v[36:39]
	v_mfma_f32_16x16x32_bf16 v[32:35], v[116:119], v[180:183], v[32:35]
	v_mfma_f32_16x16x32_bf16 v[32:35], v[124:127], v[184:187], v[32:35]
	v_mfma_f32_16x16x32_bf16 v[24:27], v[148:151], v[180:183], v[24:27]
	v_mfma_f32_16x16x32_bf16 v[24:27], v[152:155], v[184:187], v[24:27]
	v_mfma_f32_16x16x32_bf16 v[28:31], v[132:135], v[180:183], v[28:31]
	v_mfma_f32_16x16x32_bf16 v[28:31], v[144:147], v[184:187], v[28:31]
	v_mfma_f32_16x16x32_bf16 v[20:23], v[156:159], v[180:183], v[20:23]
	v_mfma_f32_16x16x32_bf16 v[20:23], v[160:163], v[184:187], v[20:23]
	v_mfma_f32_16x16x32_bf16 v[16:19], v[116:119], v[196:199], v[16:19]
	v_mfma_f32_16x16x32_bf16 v[16:19], v[124:127], v[200:203], v[16:19]
	v_mfma_f32_16x16x32_bf16 v[8:11], v[148:151], v[196:199], v[8:11]
	v_mfma_f32_16x16x32_bf16 v[8:11], v[152:155], v[200:203], v[8:11]
	v_mfma_f32_16x16x32_bf16 v[12:15], v[132:135], v[196:199], v[12:15]
	v_mfma_f32_16x16x32_bf16 v[12:15], v[144:147], v[200:203], v[12:15]
	v_mfma_f32_16x16x32_bf16 v[4:7], v[156:159], v[196:199], v[4:7]
	v_mfma_f32_16x16x32_bf16 v[4:7], v[160:163], v[200:203], v[4:7]
	s_setprio 0
	s_barrier
	s_add_i32 s48, s48, 2
	s_add_u32 s22, s22, 0x100
	s_addc_u32 s23, s23, 0
	s_add_u32 s46, s46, 0x100
	s_addc_u32 s47, s47, 0
	s_cmp_gt_u32 s48, 29
	s_cbranch_scc0 .LBB0_1010
	s_and_b64 vcc, exec, s[8:9]
	s_cbranch_vccz .LBB0_1013
	s_barrier
